# nt hint on the pool mixer input row loads
# baseline (speedup 1.0000x reference)
.LBB0_110:
	s_or_b64 exec, exec, s[2:3]
	v_ashrrev_i32_e32 v143, 31, v142
	v_lshl_add_u64 v[12:13], s[28:29], 0, v[142:143]
	v_lshlrev_b64 v[102:103], 11, v[12:13]
	v_lshl_add_u64 v[12:13], v[136:137], 0, v[102:103]
	global_load_dwordx4 v[60:63], v[12:13], off nt
	global_load_dwordx4 v[64:67], v[12:13], off offset:2048 nt
	s_waitcnt vmcnt(2)
	v_lshlrev_b32_e32 v128, 16, v72
	v_and_b32_e32 v129, 0xffff0000, v72
	v_min_i32_e32 v72, 3, v142
	v_add_u32_e32 v72, 1, v72
	v_cvt_f32_i32_e32 v72, v72
	v_add_co_u32_e32 v14, vcc, s53, v12
	v_lshlrev_b32_e32 v124, 16, v73
	v_and_b32_e32 v125, 0xffff0000, v73
	v_div_scale_f32 v73, s[2:3], v72, v72, 1.0
	v_addc_co_u32_e32 v15, vcc, 0, v13, vcc
	v_lshlrev_b32_e32 v114, 16, v74
	v_and_b32_e32 v115, 0xffff0000, v74
	v_rcp_f32_e32 v74, v73
	v_add_co_u32_e32 v24, vcc, s58, v12
	v_lshlrev_b32_e32 v88, 16, v75
	s_nop 0
	v_addc_co_u32_e32 v25, vcc, 0, v13, vcc
	v_add_co_u32_e32 v12, vcc, s64, v12
	v_and_b32_e32 v89, 0xffff0000, v75
	s_nop 0
	v_addc_co_u32_e32 v13, vcc, 0, v13, vcc
	v_fma_f32 v75, -v73, v74, 1.0
	v_fmac_f32_e32 v74, v75, v74
	v_div_scale_f32 v75, vcc, 1.0, v72, 1.0
	v_lshlrev_b32_e32 v112, 16, v78
	v_and_b32_e32 v113, 0xffff0000, v78
	v_mul_f32_e32 v78, v75, v74
	v_lshlrev_b32_e32 v86, 16, v79
	v_and_b32_e32 v87, 0xffff0000, v79
	v_fma_f32 v79, -v73, v78, v75
	v_fmac_f32_e32 v78, v79, v74
	v_fma_f32 v73, -v73, v78, v75
	v_div_fmas_f32 v73, v73, v74, v78
	v_min_i32_e32 v74, 3, v104
	v_add_u32_e32 v74, 1, v74
	v_cvt_f32_i32_e32 v74, v74
	v_lshlrev_b32_e32 v106, 16, v70
	v_and_b32_e32 v107, 0xffff0000, v70
	v_min_i32_e32 v70, 3, v100
	v_div_scale_f32 v75, s[2:3], v74, v74, 1.0
	v_rcp_f32_e32 v78, v75
	v_add_u32_e32 v70, 1, v70
	v_cvt_f32_i32_e32 v70, v70
	v_lshlrev_b32_e32 v116, 16, v80
	v_fma_f32 v79, -v75, v78, 1.0
	v_fmac_f32_e32 v78, v79, v78
	v_div_scale_f32 v79, vcc, 1.0, v74, 1.0
	v_and_b32_e32 v117, 0xffff0000, v80
	v_mul_f32_e32 v80, v79, v78
	v_lshlrev_b32_e32 v120, 16, v81
	v_and_b32_e32 v121, 0xffff0000, v81
	v_fma_f32 v81, -v75, v80, v79
	v_fmac_f32_e32 v80, v81, v78
	v_fma_f32 v75, -v75, v80, v79
	v_lshlrev_b32_e32 v110, 16, v68
	v_and_b32_e32 v111, 0xffff0000, v68
	v_lshlrev_b32_e32 v118, 16, v69
	v_and_b32_e32 v119, 0xffff0000, v69
	v_lshlrev_b32_e32 v68, 16, v71
	v_and_b32_e32 v69, 0xffff0000, v71
	v_div_scale_f32 v71, s[2:3], v70, v70, 1.0
	global_load_dwordx4 v[56:59], v[24:25], off offset:-4096 nt
	global_load_dwordx4 v[52:55], v[14:15], off offset:2048 nt
	global_load_dwordx4 v[44:47], v[24:25], off nt
	global_load_dwordx4 v[36:39], v[24:25], off offset:2048 nt
	v_div_fmas_f32 v75, v75, v78, v80
	v_rcp_f32_e32 v78, v71
	v_lshlrev_b32_e32 v108, 16, v82
	v_and_b32_e32 v109, 0xffff0000, v82
	v_lshlrev_b32_e32 v126, 16, v76
	v_fma_f32 v79, -v71, v78, 1.0
	v_fmac_f32_e32 v78, v79, v78
	v_div_scale_f32 v79, vcc, 1.0, v70, 1.0
	v_mul_f32_e32 v80, v79, v78
	v_fma_f32 v81, -v71, v80, v79
	v_fmac_f32_e32 v80, v81, v78
	v_fma_f32 v71, -v71, v80, v79
	v_div_fmas_f32 v71, v71, v78, v80
	v_min_i32_e32 v78, 3, v98
	v_add_u32_e32 v78, 1, v78
	v_cvt_f32_i32_e32 v78, v78
	v_and_b32_e32 v127, 0xffff0000, v76
	v_lshlrev_b32_e32 v122, 16, v77
	v_and_b32_e32 v123, 0xffff0000, v77
	v_div_scale_f32 v79, s[2:3], v78, v78, 1.0
	v_rcp_f32_e32 v80, v79
	v_lshlrev_b32_e32 v76, 16, v83
	v_and_b32_e32 v77, 0xffff0000, v83
	s_waitcnt vmcnt(4)
	v_lshlrev_b32_e32 v144, 16, v64
	v_fma_f32 v81, -v79, v80, 1.0
	v_fmac_f32_e32 v80, v81, v80
	v_div_scale_f32 v81, vcc, 1.0, v78, 1.0
	v_mul_f32_e32 v82, v81, v80
	v_fma_f32 v83, -v79, v82, v81
	v_fmac_f32_e32 v82, v83, v80
	v_fma_f32 v79, -v79, v82, v81
	v_div_fmas_f32 v79, v79, v80, v82
	v_min_i32_e32 v80, 3, v94
	v_add_u32_e32 v80, 1, v80
	v_cvt_f32_i32_e32 v80, v80
	v_lshlrev_b32_e32 v132, 16, v40
	v_and_b32_e32 v133, 0xffff0000, v40
	v_mul_f32_e32 v40, 0xbfb8aa3b, v144
	v_div_scale_f32 v81, s[2:3], v80, v80, 1.0
	v_rcp_f32_e32 v82, v81
	v_exp_f32_e32 v40, v40
	v_and_b32_e32 v145, 0xffff0000, v64
	v_ashrrev_i32_e32 v105, 31, v104
	v_fma_f32 v83, -v81, v82, 1.0
	v_fmac_f32_e32 v82, v83, v82
	v_div_scale_f32 v83, vcc, 1.0, v80, 1.0
	v_mul_f32_e32 v85, v83, v82
	v_fma_f32 v91, -v81, v85, v83
	v_fmac_f32_e32 v85, v91, v82
	v_fma_f32 v81, -v81, v85, v83
	v_div_fmas_f32 v81, v81, v82, v85
	v_min_i32_e32 v82, 3, v92
	v_add_u32_e32 v82, 1, v82
	v_cvt_f32_i32_e32 v82, v82
	v_add_f32_e32 v40, 1.0, v40
	v_rcp_f32_e32 v146, v40
	v_mul_f32_e32 v40, 0xbfb8aa3b, v145
	v_div_scale_f32 v83, s[2:3], v82, v82, 1.0
	v_rcp_f32_e32 v85, v83
	v_exp_f32_e32 v40, v40
	v_ashrrev_i32_e32 v101, 31, v100
	v_ashrrev_i32_e32 v99, 31, v98
	v_fma_f32 v91, -v83, v85, 1.0
	v_add_f32_e32 v40, 1.0, v40
	v_fmac_f32_e32 v85, v91, v85
	v_div_scale_f32 v91, vcc, 1.0, v82, 1.0
	v_rcp_f32_e32 v147, v40
	v_ashrrev_i32_e32 v95, 31, v94
	v_mul_f32_e32 v93, v91, v85
	v_div_fixup_f32 v90, v73, v72, 1.0
	v_lshl_add_u64 v[72:73], v[138:139], 0, v[102:103]
	v_div_fixup_f32 v102, v75, v74, 1.0
	v_lshl_add_u64 v[74:75], s[28:29], 0, v[104:105]
	v_div_fixup_f32 v104, v71, v70, 1.0
	v_lshl_add_u64 v[70:71], s[28:29], 0, v[100:101]
	v_div_fixup_f32 v100, v79, v78, 1.0
	v_lshl_add_u64 v[78:79], s[28:29], 0, v[98:99]
	v_div_fixup_f32 v98, v81, v80, 1.0
	v_lshl_add_u64 v[80:81], s[28:29], 0, v[94:95]
	v_fma_f32 v94, -v83, v93, v91
	v_fmac_f32_e32 v93, v94, v85
	v_fma_f32 v83, -v83, v93, v91
	v_pk_mul_f32 v[144:145], v[146:147], v[144:145]
	v_lshlrev_b32_e32 v146, 16, v60
	v_div_fmas_f32 v83, v83, v85, v93
	v_ashrrev_i32_e32 v93, 31, v92
	v_mul_f32_e32 v40, 0xbfb8aa3b, v146
	v_div_fixup_f32 v94, v83, v82, 1.0
	v_lshl_add_u64 v[82:83], s[28:29], 0, v[92:93]
	v_exp_f32_e32 v40, v40
	v_lshlrev_b64 v[82:83], 11, v[82:83]
	v_lshl_add_u64 v[92:93], v[138:139], 0, v[82:83]
	v_min_i32_e32 v82, 3, v84
	v_add_u32_e32 v82, 1, v82
	v_cvt_f32_i32_e32 v82, v82
	v_and_b32_e32 v147, 0xffff0000, v60
	v_add_f32_e32 v40, 1.0, v40
	v_rcp_f32_e32 v148, v40
	v_mul_f32_e32 v40, 0xbfb8aa3b, v147
	v_exp_f32_e32 v40, v40
	v_div_scale_f32 v83, s[2:3], v82, v82, 1.0
	v_rcp_f32_e32 v85, v83
	v_pk_add_f32 v[142:143], v[126:127], 0 op_sel_hi:[1,0]
	v_add_f32_e32 v40, 1.0, v40
	v_pk_add_f32 v[142:143], v[142:143], v[128:129]
	v_rcp_f32_e32 v149, v40
	v_pk_add_f32 v[142:143], v[142:143], v[116:117]
	global_load_dwordx4 v[24:27], v[12:13], off nt
	s_nop 0
	global_load_dwordx4 v[12:15], v[12:13], off offset:2048 nt
	v_pk_add_f32 v[142:143], v[142:143], v[132:133]
	v_fma_f32 v91, -v83, v85, 1.0
	v_lshlrev_b32_e32 v130, 16, v48
	v_and_b32_e32 v131, 0xffff0000, v48
	v_pk_add_f32 v[126:127], v[142:143], v[126:127] neg_lo:[0,1] neg_hi:[0,1]
	v_fmac_f32_e32 v85, v91, v85
	v_div_scale_f32 v91, vcc, 1.0, v82, 1.0
	v_pk_add_f32 v[126:127], v[126:127], v[130:131]
	v_pk_mul_f32 v[146:147], v[148:149], v[146:147]
	v_pk_fma_f32 v[148:149], v[90:91], v[142:143], v[132:133] op_sel_hi:[0,1,1] neg_lo:[0,0,1] neg_hi:[0,0,1]
	v_pk_fma_f32 v[142:143], v[102:103], v[126:127], v[130:131] op_sel_hi:[0,1,1] neg_lo:[0,0,1] neg_hi:[0,0,1]
	v_pk_add_f32 v[126:127], v[126:127], v[128:129] neg_lo:[0,1] neg_hi:[0,1]
	s_waitcnt vmcnt(5)
	v_lshlrev_b32_e32 v128, 16, v56
	v_and_b32_e32 v129, 0xffff0000, v56
	v_mul_f32_e32 v56, 0xbfb8aa3b, v128
	v_exp_f32_e32 v56, v56
	v_pk_mul_f32 v[142:143], v[4:5], v[142:143]
	v_pk_add_f32 v[126:127], v[126:127], v[110:111]
	v_pk_mul_f32 v[142:143], v[142:143], v[144:145]
	v_add_f32_e32 v56, 1.0, v56
	v_cvt_pk_bf16_f32 v48, v142, v143
	v_rcp_f32_e32 v142, v56
	v_mul_f32_e32 v56, 0xbfb8aa3b, v129
	v_exp_f32_e32 v56, v56
	v_pk_add_f32 v[116:117], v[126:127], v[116:117] neg_lo:[0,1] neg_hi:[0,1]
	v_mul_f32_e32 v95, v91, v85
	v_fma_f32 v99, -v83, v95, v91
	v_add_f32_e32 v56, 1.0, v56
	v_rcp_f32_e32 v143, v56
	v_fmac_f32_e32 v95, v99, v85
	v_lshlrev_b32_e32 v64, 16, v65
	v_and_b32_e32 v65, 0xffff0000, v65
	v_pk_mul_f32 v[128:129], v[142:143], v[128:129]
	v_pk_fma_f32 v[142:143], v[104:105], v[126:127], v[110:111] op_sel_hi:[0,1,1] neg_lo:[0,0,1] neg_hi:[0,0,1]
	v_pk_mul_f32 v[142:143], v[4:5], v[142:143]
	v_lshlrev_b32_e32 v126, 16, v32
	v_pk_mul_f32 v[128:129], v[142:143], v[128:129]
	v_and_b32_e32 v127, 0xffff0000, v32
	v_cvt_pk_bf16_f32 v56, v128, v129
	s_waitcnt vmcnt(4)
	v_lshlrev_b32_e32 v128, 16, v52
	v_mul_f32_e32 v32, 0xbfb8aa3b, v128
	v_exp_f32_e32 v32, v32
	v_and_b32_e32 v129, 0xffff0000, v52
	v_pk_add_f32 v[116:117], v[116:117], v[126:127]
	v_lshlrev_b32_e32 v60, 16, v61
	v_add_f32_e32 v32, 1.0, v32
	v_rcp_f32_e32 v142, v32
	v_mul_f32_e32 v32, 0xbfb8aa3b, v129
	v_exp_f32_e32 v32, v32
	v_and_b32_e32 v61, 0xffff0000, v61
	v_fma_f32 v83, -v83, v95, v91
	v_div_fmas_f32 v83, v83, v85, v95
	v_add_f32_e32 v32, 1.0, v32
	v_rcp_f32_e32 v143, v32
	v_div_fixup_f32 v82, v83, v82, 1.0
	v_lshlrev_b32_e32 v52, 16, v53
	v_and_b32_e32 v53, 0xffff0000, v53
	v_pk_mul_f32 v[128:129], v[142:143], v[128:129]
	v_pk_fma_f32 v[142:143], v[100:101], v[116:117], v[126:127] op_sel_hi:[0,1,1] neg_lo:[0,0,1] neg_hi:[0,0,1]
	v_pk_mul_f32 v[142:143], v[4:5], v[142:143]
	v_pk_add_f32 v[116:117], v[116:117], v[132:133] neg_lo:[0,1] neg_hi:[0,1]
	v_pk_mul_f32 v[128:129], v[142:143], v[128:129]
	s_waitcnt vmcnt(3)
	v_lshlrev_b32_e32 v132, 16, v44
	v_cvt_pk_bf16_f32 v32, v128, v129
	v_lshlrev_b32_e32 v128, 16, v28
	v_and_b32_e32 v129, 0xffff0000, v28
	v_mul_f32_e32 v28, 0xbfb8aa3b, v132
	v_exp_f32_e32 v28, v28
	v_and_b32_e32 v133, 0xffff0000, v44
	v_pk_add_f32 v[116:117], v[116:117], v[128:129]
	v_lshlrev_b32_e32 v44, 16, v45
	v_add_f32_e32 v28, 1.0, v28
	v_rcp_f32_e32 v142, v28
	v_mul_f32_e32 v28, 0xbfb8aa3b, v133
	v_exp_f32_e32 v28, v28
	v_pk_fma_f32 v[128:129], v[98:99], v[116:117], v[128:129] op_sel_hi:[0,1,1] neg_lo:[0,0,1] neg_hi:[0,0,1]
	v_pk_mul_f32 v[128:129], v[4:5], v[128:129]
	v_pk_add_f32 v[116:117], v[116:117], v[130:131] neg_lo:[0,1] neg_hi:[0,1]
	v_add_f32_e32 v28, 1.0, v28
	v_rcp_f32_e32 v143, v28
	s_waitcnt vmcnt(2)
	v_lshlrev_b32_e32 v130, 16, v36
	v_and_b32_e32 v131, 0xffff0000, v36
	v_and_b32_e32 v45, 0xffff0000, v45
	v_pk_mul_f32 v[132:133], v[142:143], v[132:133]
	v_lshlrev_b32_e32 v36, 16, v37
	v_pk_mul_f32 v[128:129], v[128:129], v[132:133]
	v_and_b32_e32 v37, 0xffff0000, v37
	v_cvt_pk_bf16_f32 v28, v128, v129
	v_lshlrev_b32_e32 v128, 16, v20
	v_and_b32_e32 v129, 0xffff0000, v20
	v_mul_f32_e32 v20, 0xbfb8aa3b, v130
	v_exp_f32_e32 v20, v20
	v_pk_add_f32 v[116:117], v[116:117], v[128:129]
	v_pk_mul_f32 v[148:149], v[4:5], v[148:149]
	v_pk_fma_f32 v[128:129], v[94:95], v[116:117], v[128:129] op_sel_hi:[0,1,1] neg_lo:[0,0,1] neg_hi:[0,0,1]
	v_add_f32_e32 v20, 1.0, v20
	v_rcp_f32_e32 v132, v20
	v_mul_f32_e32 v20, 0xbfb8aa3b, v131
	v_exp_f32_e32 v20, v20
	v_pk_mul_f32 v[128:129], v[4:5], v[128:129]
	v_pk_add_f32 v[110:111], v[116:117], v[110:111] neg_lo:[0,1] neg_hi:[0,1]
	v_lshlrev_b32_e32 v116, 16, v16
	v_add_f32_e32 v20, 1.0, v20
	v_rcp_f32_e32 v133, v20
	v_and_b32_e32 v117, 0xffff0000, v16
	v_pk_add_f32 v[110:111], v[110:111], v[116:117]
	v_pk_mul_f32 v[146:147], v[148:149], v[146:147]
	v_pk_mul_f32 v[130:131], v[132:133], v[130:131]
	v_pk_fma_f32 v[116:117], v[82:83], v[110:111], v[116:117] op_sel_hi:[0,1,1] neg_lo:[0,0,1] neg_hi:[0,0,1]
	v_pk_mul_f32 v[128:129], v[128:129], v[130:131]
	v_pk_mul_f32 v[116:117], v[4:5], v[116:117]
	v_cvt_pk_bf16_f32 v20, v128, v129
	s_waitcnt vmcnt(1)
	v_lshlrev_b32_e32 v128, 16, v24
	v_mul_f32_e32 v16, 0xbfb8aa3b, v128
	v_exp_f32_e32 v16, v16
	v_and_b32_e32 v129, 0xffff0000, v24
	v_pk_add_f32 v[110:111], v[110:111], v[126:127] neg_lo:[0,1] neg_hi:[0,1]
	v_lshlrev_b32_e32 v126, 16, v49
	v_add_f32_e32 v16, 1.0, v16
	v_rcp_f32_e32 v130, v16
	v_mul_f32_e32 v16, 0xbfb8aa3b, v129
	v_exp_f32_e32 v16, v16
	v_and_b32_e32 v127, 0xffff0000, v49
	v_lshlrev_b32_e32 v24, 16, v25
	v_and_b32_e32 v25, 0xffff0000, v25
	v_add_f32_e32 v16, 1.0, v16
	v_rcp_f32_e32 v131, v16
	v_mul_f32_e32 v16, 0xbfb8aa3b, v64
	v_exp_f32_e32 v16, v16
	v_lshlrev_b64 v[74:75], 11, v[74:75]
	v_pk_mul_f32 v[128:129], v[130:131], v[128:129]
	v_pk_add_f32 v[130:131], v[122:123], 0 op_sel_hi:[1,0]
	v_add_f32_e32 v16, 1.0, v16
	v_rcp_f32_e32 v132, v16
	v_mul_f32_e32 v16, 0xbfb8aa3b, v65
	v_exp_f32_e32 v16, v16
	v_pk_add_f32 v[130:131], v[130:131], v[124:125]
	v_pk_mul_f32 v[116:117], v[116:117], v[128:129]
	v_lshlrev_b32_e32 v128, 16, v41
	v_add_f32_e32 v16, 1.0, v16
	v_rcp_f32_e32 v133, v16
	v_mul_f32_e32 v16, 0xbfb8aa3b, v60
	v_exp_f32_e32 v16, v16
	v_and_b32_e32 v129, 0xffff0000, v41
	v_pk_mul_f32 v[64:65], v[132:133], v[64:65]
	v_pk_add_f32 v[130:131], v[130:131], v[120:121]
	v_add_f32_e32 v16, 1.0, v16
	v_rcp_f32_e32 v132, v16
	v_mul_f32_e32 v16, 0xbfb8aa3b, v61
	v_exp_f32_e32 v16, v16
	v_pk_add_f32 v[130:131], v[130:131], v[128:129]
	v_lshlrev_b64 v[70:71], 11, v[70:71]
	v_pk_add_f32 v[122:123], v[130:131], v[122:123] neg_lo:[0,1] neg_hi:[0,1]
	v_add_f32_e32 v16, 1.0, v16
	v_rcp_f32_e32 v133, v16
	v_lshlrev_b64 v[78:79], 11, v[78:79]
	v_lshlrev_b64 v[80:81], 11, v[80:81]
	v_cvt_pk_bf16_f32 v40, v146, v147
	v_pk_mul_f32 v[60:61], v[132:133], v[60:61]
	v_pk_fma_f32 v[132:133], v[90:91], v[130:131], v[128:129] op_sel_hi:[0,1,1] neg_lo:[0,0,1] neg_hi:[0,0,1]
	v_pk_mul_f32 v[132:133], v[6:7], v[132:133]
	v_lshl_add_u64 v[74:75], v[138:139], 0, v[74:75]
	v_pk_mul_f32 v[60:61], v[132:133], v[60:61]
	v_lshl_add_u64 v[70:71], v[138:139], 0, v[70:71]
	v_cvt_pk_bf16_f32 v41, v60, v61
	v_pk_add_f32 v[60:61], v[122:123], v[126:127]
	v_lshl_add_u64 v[78:79], v[138:139], 0, v[78:79]
	v_pk_fma_f32 v[122:123], v[102:103], v[60:61], v[126:127] op_sel_hi:[0,1,1] neg_lo:[0,0,1] neg_hi:[0,0,1]
	v_pk_mul_f32 v[122:123], v[6:7], v[122:123]
	v_pk_add_f32 v[60:61], v[60:61], v[124:125] neg_lo:[0,1] neg_hi:[0,1]
	v_pk_mul_f32 v[64:65], v[122:123], v[64:65]
	v_pk_add_f32 v[60:61], v[60:61], v[118:119]
	v_cvt_pk_bf16_f32 v49, v64, v65
	v_lshlrev_b32_e32 v64, 16, v57
	v_mul_f32_e32 v16, 0xbfb8aa3b, v64
	v_exp_f32_e32 v16, v16
	v_and_b32_e32 v65, 0xffff0000, v57
	v_pk_add_f32 v[120:121], v[60:61], v[120:121] neg_lo:[0,1] neg_hi:[0,1]
	v_lshl_add_u64 v[80:81], v[138:139], 0, v[80:81]
	v_add_f32_e32 v16, 1.0, v16
	v_rcp_f32_e32 v122, v16
	v_mul_f32_e32 v16, 0xbfb8aa3b, v65
	v_exp_f32_e32 v16, v16
	v_ashrrev_i32_e32 v85, 31, v84
	v_add_f32_e32 v16, 1.0, v16
	v_rcp_f32_e32 v123, v16
	v_mul_f32_e32 v16, 0xbfb8aa3b, v52
	v_exp_f32_e32 v16, v16
	v_pk_mul_f32 v[64:65], v[122:123], v[64:65]
	v_pk_fma_f32 v[122:123], v[104:105], v[60:61], v[118:119] op_sel_hi:[0,1,1] neg_lo:[0,0,1] neg_hi:[0,0,1]
	v_pk_mul_f32 v[122:123], v[6:7], v[122:123]
	v_lshlrev_b32_e32 v60, 16, v33
	v_pk_mul_f32 v[64:65], v[122:123], v[64:65]
	v_and_b32_e32 v61, 0xffff0000, v33
	v_add_f32_e32 v16, 1.0, v16
	v_cvt_pk_bf16_f32 v57, v64, v65
	v_pk_add_f32 v[64:65], v[120:121], v[60:61]
	v_rcp_f32_e32 v120, v16
	v_mul_f32_e32 v16, 0xbfb8aa3b, v53
	v_exp_f32_e32 v16, v16
	s_nop 0
	v_add_f32_e32 v16, 1.0, v16
	v_rcp_f32_e32 v121, v16
	v_mul_f32_e32 v16, 0xbfb8aa3b, v44
	v_exp_f32_e32 v16, v16
	v_pk_mul_f32 v[52:53], v[120:121], v[52:53]
	v_pk_fma_f32 v[120:121], v[100:101], v[64:65], v[60:61] op_sel_hi:[0,1,1] neg_lo:[0,0,1] neg_hi:[0,0,1]
	v_pk_mul_f32 v[120:121], v[6:7], v[120:121]
	v_add_f32_e32 v16, 1.0, v16
	v_pk_mul_f32 v[52:53], v[120:121], v[52:53]
	v_rcp_f32_e32 v120, v16
	v_mul_f32_e32 v16, 0xbfb8aa3b, v45
	v_exp_f32_e32 v16, v16
	v_pk_add_f32 v[64:65], v[64:65], v[128:129] neg_lo:[0,1] neg_hi:[0,1]
	v_cvt_pk_bf16_f32 v33, v52, v53
	v_lshlrev_b32_e32 v52, 16, v29
	v_add_f32_e32 v16, 1.0, v16
	v_rcp_f32_e32 v121, v16
	v_mul_f32_e32 v16, 0xbfb8aa3b, v36
	v_exp_f32_e32 v16, v16
	v_and_b32_e32 v53, 0xffff0000, v29
	v_pk_add_f32 v[64:65], v[64:65], v[52:53]
	v_pk_mul_f32 v[44:45], v[120:121], v[44:45]
	v_pk_fma_f32 v[52:53], v[98:99], v[64:65], v[52:53] op_sel_hi:[0,1,1] neg_lo:[0,0,1] neg_hi:[0,0,1]
	v_pk_mul_f32 v[52:53], v[6:7], v[52:53]
	v_add_f32_e32 v16, 1.0, v16
	v_pk_mul_f32 v[44:45], v[52:53], v[44:45]
	v_pk_add_f32 v[52:53], v[64:65], v[126:127] neg_lo:[0,1] neg_hi:[0,1]
	v_rcp_f32_e32 v64, v16
	v_mul_f32_e32 v16, 0xbfb8aa3b, v37
	v_exp_f32_e32 v16, v16
	v_cvt_pk_bf16_f32 v29, v44, v45
	v_lshlrev_b32_e32 v44, 16, v21
	v_and_b32_e32 v45, 0xffff0000, v21
	v_add_f32_e32 v16, 1.0, v16
	v_rcp_f32_e32 v65, v16
	v_pk_add_f32 v[52:53], v[52:53], v[44:45]
	v_lshlrev_b32_e32 v16, 16, v17
	v_pk_fma_f32 v[44:45], v[94:95], v[52:53], v[44:45] op_sel_hi:[0,1,1] neg_lo:[0,0,1] neg_hi:[0,0,1]
	v_pk_mul_f32 v[36:37], v[64:65], v[36:37]
	v_pk_mul_f32 v[44:45], v[6:7], v[44:45]
	v_and_b32_e32 v17, 0xffff0000, v17
	v_pk_mul_f32 v[36:37], v[44:45], v[36:37]
	v_pk_add_f32 v[44:45], v[52:53], v[118:119] neg_lo:[0,1] neg_hi:[0,1]
	v_cvt_pk_bf16_f32 v21, v36, v37
	v_pk_add_f32 v[36:37], v[44:45], v[16:17]
	v_lshlrev_b32_e32 v52, 16, v42
	v_pk_fma_f32 v[16:17], v[82:83], v[36:37], v[16:17] op_sel_hi:[0,1,1] neg_lo:[0,0,1] neg_hi:[0,0,1]
	v_pk_add_f32 v[36:37], v[36:37], v[60:61] neg_lo:[0,1] neg_hi:[0,1]
	v_lshlrev_b32_e32 v60, 16, v66
	v_and_b32_e32 v53, 0xffff0000, v42
	v_mul_f32_e32 v42, 0xbfb8aa3b, v60
	v_exp_f32_e32 v42, v42
	v_and_b32_e32 v61, 0xffff0000, v66
	v_mul_f32_e32 v44, 0xbfb8aa3b, v24
	v_mul_f32_e32 v45, 0xbfb8aa3b, v25
	v_add_f32_e32 v42, 1.0, v42
	v_rcp_f32_e32 v64, v42
	v_mul_f32_e32 v42, 0xbfb8aa3b, v61
	v_exp_f32_e32 v42, v42
	v_exp_f32_e32 v44, v44
	v_exp_f32_e32 v45, v45
	v_pk_mul_f32 v[16:17], v[6:7], v[16:17]
	v_add_f32_e32 v42, 1.0, v42
	v_rcp_f32_e32 v65, v42
	v_add_f32_e32 v44, 1.0, v44
	v_add_f32_e32 v45, 1.0, v45
	v_rcp_f32_e32 v44, v44
	v_pk_mul_f32 v[60:61], v[64:65], v[60:61]
	v_lshlrev_b32_e32 v64, 16, v62
	v_mul_f32_e32 v42, 0xbfb8aa3b, v64
	v_exp_f32_e32 v42, v42
	v_and_b32_e32 v65, 0xffff0000, v62
	v_rcp_f32_e32 v45, v45
	v_lshlrev_b32_e32 v66, 16, v67
	v_add_f32_e32 v42, 1.0, v42
	v_rcp_f32_e32 v118, v42
	v_mul_f32_e32 v42, 0xbfb8aa3b, v65
	v_exp_f32_e32 v42, v42
	v_pk_mul_f32 v[24:25], v[44:45], v[24:25]
	v_pk_add_f32 v[44:45], v[112:113], 0 op_sel_hi:[1,0]
	v_pk_mul_f32 v[16:17], v[16:17], v[24:25]
	v_add_f32_e32 v42, 1.0, v42
	v_rcp_f32_e32 v119, v42
	v_pk_add_f32 v[44:45], v[44:45], v[114:115]
	v_lshlrev_b32_e32 v24, 16, v50
	v_pk_add_f32 v[44:45], v[44:45], v[108:109]
	v_pk_mul_f32 v[64:65], v[118:119], v[64:65]
	v_pk_add_f32 v[44:45], v[44:45], v[52:53]
	v_and_b32_e32 v25, 0xffff0000, v50
	v_pk_fma_f32 v[118:119], v[90:91], v[44:45], v[52:53] op_sel_hi:[0,1,1] neg_lo:[0,0,1] neg_hi:[0,0,1]
	v_pk_mul_f32 v[118:119], v[0:1], v[118:119]
	v_pk_add_f32 v[44:45], v[44:45], v[112:113] neg_lo:[0,1] neg_hi:[0,1]
	v_pk_mul_f32 v[64:65], v[118:119], v[64:65]
	v_pk_add_f32 v[44:45], v[44:45], v[24:25]
	v_cvt_pk_bf16_f32 v42, v64, v65
	v_pk_fma_f32 v[64:65], v[102:103], v[44:45], v[24:25] op_sel_hi:[0,1,1] neg_lo:[0,0,1] neg_hi:[0,0,1]
	v_pk_mul_f32 v[64:65], v[0:1], v[64:65]
	v_pk_add_f32 v[44:45], v[44:45], v[114:115] neg_lo:[0,1] neg_hi:[0,1]
	v_pk_mul_f32 v[60:61], v[64:65], v[60:61]
	v_pk_add_f32 v[44:45], v[44:45], v[106:107]
	v_cvt_pk_bf16_f32 v50, v60, v61
	v_lshlrev_b32_e32 v60, 16, v58
	v_and_b32_e32 v61, 0xffff0000, v58
	v_mul_f32_e32 v58, 0xbfb8aa3b, v60
	v_exp_f32_e32 v58, v58
	v_and_b32_e32 v67, 0xffff0000, v67
	v_lshlrev_b32_e32 v62, 16, v63
	v_and_b32_e32 v63, 0xffff0000, v63
	v_add_f32_e32 v58, 1.0, v58
	v_rcp_f32_e32 v64, v58
	v_mul_f32_e32 v58, 0xbfb8aa3b, v61
	v_exp_f32_e32 v58, v58
	s_nop 0
	v_add_f32_e32 v58, 1.0, v58
	v_rcp_f32_e32 v65, v58
	s_nop 0
	v_pk_mul_f32 v[60:61], v[64:65], v[60:61]
	v_pk_fma_f32 v[64:65], v[104:105], v[44:45], v[106:107] op_sel_hi:[0,1,1] neg_lo:[0,0,1] neg_hi:[0,0,1]
	v_pk_mul_f32 v[64:65], v[0:1], v[64:65]
	s_nop 0
	v_pk_mul_f32 v[60:61], v[64:65], v[60:61]
	v_pk_add_f32 v[64:65], v[44:45], v[108:109] neg_lo:[0,1] neg_hi:[0,1]
	v_lshlrev_b32_e32 v44, 16, v34
	v_and_b32_e32 v45, 0xffff0000, v34
	v_cvt_pk_bf16_f32 v58, v60, v61
	v_pk_add_f32 v[60:61], v[64:65], v[44:45]
	v_lshlrev_b32_e32 v64, 16, v54
	v_mul_f32_e32 v34, 0xbfb8aa3b, v64
	v_exp_f32_e32 v34, v34
	v_and_b32_e32 v65, 0xffff0000, v54
	v_pk_add_f32 v[52:53], v[60:61], v[52:53] neg_lo:[0,1] neg_hi:[0,1]
	v_lshlrev_b32_e32 v54, 16, v55
	v_add_f32_e32 v34, 1.0, v34
	v_rcp_f32_e32 v108, v34
	v_mul_f32_e32 v34, 0xbfb8aa3b, v65
	v_exp_f32_e32 v34, v34
	v_and_b32_e32 v55, 0xffff0000, v55
	v_add_f32_e32 v34, 1.0, v34
	v_rcp_f32_e32 v109, v34
	s_nop 0
	v_pk_mul_f32 v[64:65], v[108:109], v[64:65]
	v_pk_fma_f32 v[108:109], v[100:101], v[60:61], v[44:45] op_sel_hi:[0,1,1] neg_lo:[0,0,1] neg_hi:[0,0,1]
	v_pk_mul_f32 v[108:109], v[0:1], v[108:109]
	v_lshlrev_b32_e32 v60, 16, v30
	v_pk_mul_f32 v[64:65], v[108:109], v[64:65]
	v_and_b32_e32 v61, 0xffff0000, v30
	v_cvt_pk_bf16_f32 v34, v64, v65
	v_lshlrev_b32_e32 v64, 16, v46
	v_mul_f32_e32 v30, 0xbfb8aa3b, v64
	v_exp_f32_e32 v30, v30
	v_and_b32_e32 v65, 0xffff0000, v46
	v_pk_add_f32 v[52:53], v[52:53], v[60:61]
	v_lshlrev_b32_e32 v46, 16, v47
	v_add_f32_e32 v30, 1.0, v30
	v_rcp_f32_e32 v108, v30
	v_mul_f32_e32 v30, 0xbfb8aa3b, v65
	v_exp_f32_e32 v30, v30
	v_pk_fma_f32 v[60:61], v[98:99], v[52:53], v[60:61] op_sel_hi:[0,1,1] neg_lo:[0,0,1] neg_hi:[0,0,1]
	v_pk_mul_f32 v[60:61], v[0:1], v[60:61]
	v_pk_add_f32 v[24:25], v[52:53], v[24:25] neg_lo:[0,1] neg_hi:[0,1]
	v_add_f32_e32 v30, 1.0, v30
	v_rcp_f32_e32 v109, v30
	v_lshlrev_b32_e32 v52, 16, v22
	v_and_b32_e32 v53, 0xffff0000, v22
	v_pk_add_f32 v[24:25], v[24:25], v[52:53]
	v_pk_mul_f32 v[64:65], v[108:109], v[64:65]
	v_pk_fma_f32 v[52:53], v[94:95], v[24:25], v[52:53] op_sel_hi:[0,1,1] neg_lo:[0,0,1] neg_hi:[0,0,1]
	v_pk_mul_f32 v[60:61], v[60:61], v[64:65]
	v_pk_mul_f32 v[52:53], v[0:1], v[52:53]
	v_cvt_pk_bf16_f32 v30, v60, v61
	v_lshlrev_b32_e32 v60, 16, v38
	v_mul_f32_e32 v22, 0xbfb8aa3b, v60
	v_exp_f32_e32 v22, v22
	v_and_b32_e32 v61, 0xffff0000, v38
	v_pk_add_f32 v[24:25], v[24:25], v[106:107] neg_lo:[0,1] neg_hi:[0,1]
	v_and_b32_e32 v47, 0xffff0000, v47
	v_add_f32_e32 v22, 1.0, v22
	v_rcp_f32_e32 v64, v22
	v_mul_f32_e32 v22, 0xbfb8aa3b, v61
	v_exp_f32_e32 v22, v22
	v_lshlrev_b32_e32 v38, 16, v39
	v_and_b32_e32 v39, 0xffff0000, v39
	v_add_f32_e32 v22, 1.0, v22
	v_rcp_f32_e32 v65, v22
	s_nop 0
	v_pk_mul_f32 v[60:61], v[64:65], v[60:61]
	s_nop 0
	v_pk_mul_f32 v[52:53], v[52:53], v[60:61]
	s_nop 0
	v_cvt_pk_bf16_f32 v22, v52, v53
	v_lshlrev_b32_e32 v52, 16, v18
	v_and_b32_e32 v53, 0xffff0000, v18
	v_pk_add_f32 v[60:61], v[24:25], v[52:53]
	v_lshlrev_b32_e32 v24, 16, v26
	v_mul_f32_e32 v18, 0xbfb8aa3b, v24
	v_exp_f32_e32 v18, v18
	v_and_b32_e32 v25, 0xffff0000, v26
	v_pk_fma_f32 v[52:53], v[82:83], v[60:61], v[52:53] op_sel_hi:[0,1,1] neg_lo:[0,0,1] neg_hi:[0,0,1]
	v_pk_add_f32 v[44:45], v[60:61], v[44:45] neg_lo:[0,1] neg_hi:[0,1]
	v_add_f32_e32 v18, 1.0, v18
	v_rcp_f32_e32 v64, v18
	v_mul_f32_e32 v18, 0xbfb8aa3b, v25
	v_exp_f32_e32 v18, v18
	v_pk_add_f32 v[60:61], v[86:87], 0 op_sel_hi:[1,0]
	v_pk_mul_f32 v[52:53], v[0:1], v[52:53]
	v_pk_add_f32 v[60:61], v[60:61], v[88:89]
	v_add_f32_e32 v18, 1.0, v18
	v_rcp_f32_e32 v65, v18
	v_mul_f32_e32 v18, 0xbfb8aa3b, v66
	v_exp_f32_e32 v18, v18
	v_pk_add_f32 v[60:61], v[60:61], v[76:77]
	v_pk_mul_f32 v[24:25], v[64:65], v[24:25]
	v_lshlrev_b32_e32 v64, 16, v43
	v_add_f32_e32 v18, 1.0, v18
	v_rcp_f32_e32 v106, v18
	v_mul_f32_e32 v18, 0xbfb8aa3b, v67
	v_exp_f32_e32 v18, v18
	v_and_b32_e32 v65, 0xffff0000, v43
	v_pk_add_f32 v[60:61], v[60:61], v[64:65]
	v_pk_mul_f32 v[24:25], v[52:53], v[24:25]
	v_add_f32_e32 v18, 1.0, v18
	v_rcp_f32_e32 v107, v18
	v_mul_f32_e32 v18, 0xbfb8aa3b, v62
	v_exp_f32_e32 v18, v18
	v_pk_fma_f32 v[90:91], v[90:91], v[60:61], v[64:65] op_sel_hi:[0,1,1] neg_lo:[0,0,1] neg_hi:[0,0,1]
	v_pk_mul_f32 v[66:67], v[106:107], v[66:67]
	v_lshlrev_b32_e32 v52, 16, v51
	v_add_f32_e32 v18, 1.0, v18
	v_rcp_f32_e32 v106, v18
	v_mul_f32_e32 v18, 0xbfb8aa3b, v63
	v_exp_f32_e32 v18, v18
	v_and_b32_e32 v53, 0xffff0000, v51
	v_pk_mul_f32 v[90:91], v[2:3], v[90:91]
	v_pk_add_f32 v[60:61], v[60:61], v[86:87] neg_lo:[0,1] neg_hi:[0,1]
	v_add_f32_e32 v18, 1.0, v18
	v_rcp_f32_e32 v107, v18
	v_pk_add_f32 v[60:61], v[60:61], v[52:53]
	v_pk_mul_f32 v[62:63], v[106:107], v[62:63]
	s_nop 0
	v_pk_mul_f32 v[62:63], v[90:91], v[62:63]
	s_nop 0
	v_cvt_pk_bf16_f32 v43, v62, v63
	v_pk_fma_f32 v[62:63], v[102:103], v[60:61], v[52:53] op_sel_hi:[0,1,1] neg_lo:[0,0,1] neg_hi:[0,0,1]
	v_pk_mul_f32 v[62:63], v[2:3], v[62:63]
	v_pk_add_f32 v[60:61], v[60:61], v[88:89] neg_lo:[0,1] neg_hi:[0,1]
	v_pk_mul_f32 v[62:63], v[62:63], v[66:67]
	v_pk_add_f32 v[60:61], v[60:61], v[68:69]
	v_cvt_pk_bf16_f32 v51, v62, v63
	v_lshlrev_b32_e32 v62, 16, v59
	v_mul_f32_e32 v18, 0xbfb8aa3b, v62
	v_exp_f32_e32 v18, v18
	v_and_b32_e32 v63, 0xffff0000, v59
	v_add_f32_e32 v18, 1.0, v18
	v_rcp_f32_e32 v66, v18
	v_mul_f32_e32 v18, 0xbfb8aa3b, v63
	v_exp_f32_e32 v18, v18
	s_nop 0
	v_add_f32_e32 v18, 1.0, v18
	v_rcp_f32_e32 v67, v18
	v_mul_f32_e32 v18, 0xbfb8aa3b, v54
	v_exp_f32_e32 v18, v18
	v_pk_mul_f32 v[62:63], v[66:67], v[62:63]
	v_pk_fma_f32 v[66:67], v[104:105], v[60:61], v[68:69] op_sel_hi:[0,1,1] neg_lo:[0,0,1] neg_hi:[0,0,1]
	v_pk_mul_f32 v[66:67], v[2:3], v[66:67]
	v_add_f32_e32 v18, 1.0, v18
	v_pk_mul_f32 v[62:63], v[66:67], v[62:63]
	v_pk_add_f32 v[66:67], v[60:61], v[76:77] neg_lo:[0,1] neg_hi:[0,1]
	v_lshlrev_b32_e32 v60, 16, v35
	v_and_b32_e32 v61, 0xffff0000, v35
	v_cvt_pk_bf16_f32 v59, v62, v63
	v_pk_add_f32 v[62:63], v[66:67], v[60:61]
	v_rcp_f32_e32 v66, v18
	v_mul_f32_e32 v18, 0xbfb8aa3b, v55
	v_exp_f32_e32 v18, v18
	s_nop 0
	v_add_f32_e32 v18, 1.0, v18
	v_rcp_f32_e32 v67, v18
	v_mul_f32_e32 v18, 0xbfb8aa3b, v46
	v_exp_f32_e32 v18, v18
	v_pk_mul_f32 v[54:55], v[66:67], v[54:55]
	v_pk_fma_f32 v[66:67], v[100:101], v[62:63], v[60:61] op_sel_hi:[0,1,1] neg_lo:[0,0,1] neg_hi:[0,0,1]
	v_add_f32_e32 v18, 1.0, v18
	v_pk_add_f32 v[62:63], v[62:63], v[64:65] neg_lo:[0,1] neg_hi:[0,1]
	v_rcp_f32_e32 v64, v18
	v_mul_f32_e32 v18, 0xbfb8aa3b, v47
	v_exp_f32_e32 v18, v18
	v_pk_mul_f32 v[66:67], v[2:3], v[66:67]
	v_add_f32_e32 v18, 1.0, v18
	v_rcp_f32_e32 v65, v18
	v_mul_f32_e32 v18, 0xbfb8aa3b, v38
	v_pk_mul_f32 v[54:55], v[66:67], v[54:55]
	v_exp_f32_e32 v18, v18
	v_cvt_pk_bf16_f32 v35, v54, v55
	v_lshlrev_b32_e32 v54, 16, v31
	v_and_b32_e32 v55, 0xffff0000, v31
	v_pk_add_f32 v[62:63], v[62:63], v[54:55]
	v_pk_mul_f32 v[46:47], v[64:65], v[46:47]
	v_pk_fma_f32 v[54:55], v[98:99], v[62:63], v[54:55] op_sel_hi:[0,1,1] neg_lo:[0,0,1] neg_hi:[0,0,1]
	v_pk_mul_f32 v[54:55], v[2:3], v[54:55]
	v_add_f32_e32 v18, 1.0, v18
	v_pk_mul_f32 v[46:47], v[54:55], v[46:47]
	v_rcp_f32_e32 v54, v18
	v_mul_f32_e32 v18, 0xbfb8aa3b, v39
	v_exp_f32_e32 v18, v18
	v_pk_add_f32 v[52:53], v[62:63], v[52:53] neg_lo:[0,1] neg_hi:[0,1]
	v_cvt_pk_bf16_f32 v31, v46, v47
	v_lshlrev_b32_e32 v46, 16, v23
	v_add_f32_e32 v18, 1.0, v18
	v_rcp_f32_e32 v55, v18
	v_and_b32_e32 v47, 0xffff0000, v23
	v_pk_add_f32 v[52:53], v[52:53], v[46:47]
	v_lshlrev_b32_e32 v18, 16, v19
	v_pk_fma_f32 v[46:47], v[94:95], v[52:53], v[46:47] op_sel_hi:[0,1,1] neg_lo:[0,0,1] neg_hi:[0,0,1]
	v_pk_mul_f32 v[38:39], v[54:55], v[38:39]
	v_pk_mul_f32 v[46:47], v[2:3], v[46:47]
	v_and_b32_e32 v19, 0xffff0000, v19
	v_pk_mul_f32 v[38:39], v[46:47], v[38:39]
	v_pk_add_f32 v[46:47], v[52:53], v[68:69] neg_lo:[0,1] neg_hi:[0,1]
	v_cvt_pk_bf16_f32 v23, v38, v39
	global_store_dwordx4 v[72:73], v[40:43], off
	global_store_dwordx4 v[74:75], v[48:51], off
	global_store_dwordx4 v[70:71], v[56:59], off
	global_store_dwordx4 v[78:79], v[32:35], off
	global_store_dwordx4 v[80:81], v[28:31], off
	global_store_dwordx4 v[92:93], v[20:23], off
	s_nop 1
	v_lshlrev_b32_e32 v22, 16, v27
	v_and_b32_e32 v23, 0xffff0000, v27
	v_mul_f32_e32 v26, 0xbfb8aa3b, v22
	v_mul_f32_e32 v27, 0xbfb8aa3b, v23
	v_exp_f32_e32 v26, v26
	v_exp_f32_e32 v27, v27
	v_pk_add_f32 v[20:21], v[46:47], v[18:19]
	v_add_f32_e32 v26, 1.0, v26
	v_add_f32_e32 v27, 1.0, v27
	v_rcp_f32_e32 v26, v26
	v_rcp_f32_e32 v27, v27
	v_pk_fma_f32 v[18:19], v[82:83], v[20:21], v[18:19] op_sel_hi:[0,1,1] neg_lo:[0,0,1] neg_hi:[0,0,1]
	v_pk_mul_f32 v[18:19], v[2:3], v[18:19]
	v_pk_mul_f32 v[22:23], v[26:27], v[22:23]
	s_nop 0
	v_pk_mul_f32 v[26:27], v[18:19], v[22:23]
	v_pk_add_f32 v[18:19], v[20:21], v[60:61] neg_lo:[0,1] neg_hi:[0,1]
	v_cvt_pk_bf16_f32 v21, v16, v17
	v_lshl_add_u64 v[16:17], s[28:29], 0, v[84:85]
	v_lshlrev_b64 v[16:17], 11, v[16:17]
	v_cvt_pk_bf16_f32 v20, v116, v117
	v_cvt_pk_bf16_f32 v22, v24, v25
	v_cvt_pk_bf16_f32 v23, v26, v27
	v_lshl_add_u64 v[16:17], v[138:139], 0, v[16:17]
	global_store_dwordx4 v[16:17], v[20:23], off
	s_waitcnt vmcnt(7)
	v_lshlrev_b32_e32 v16, 16, v12
	v_and_b32_e32 v17, 0xffff0000, v12
	v_mul_f32_e32 v12, 0xbfb8aa3b, v16
	v_exp_f32_e32 v12, v12
	s_nop 0
	v_add_f32_e32 v12, 1.0, v12
	v_rcp_f32_e32 v20, v12
	v_mul_f32_e32 v12, 0xbfb8aa3b, v17
	v_exp_f32_e32 v12, v12
	s_nop 0
	v_add_f32_e32 v12, 1.0, v12
	v_rcp_f32_e32 v21, v12
	v_lshlrev_b32_e32 v12, 16, v13
	v_and_b32_e32 v13, 0xffff0000, v13
	v_pk_mul_f32 v[16:17], v[20:21], v[16:17]
	v_mul_f32_e32 v20, 0xbfb8aa3b, v12
	v_mul_f32_e32 v21, 0xbfb8aa3b, v13
	v_exp_f32_e32 v20, v20
	v_exp_f32_e32 v21, v21
	v_add_f32_e32 v20, 1.0, v20
	v_add_f32_e32 v21, 1.0, v21
	v_rcp_f32_e32 v20, v20
	v_rcp_f32_e32 v21, v21
	s_nop 0
	v_pk_mul_f32 v[12:13], v[20:21], v[12:13]
	v_lshlrev_b32_e32 v20, 16, v14
	v_and_b32_e32 v21, 0xffff0000, v14
	v_mul_f32_e32 v14, 0xbfb8aa3b, v20
	v_exp_f32_e32 v14, v14
	s_nop 0
	v_add_f32_e32 v14, 1.0, v14
	v_rcp_f32_e32 v22, v14
	v_mul_f32_e32 v14, 0xbfb8aa3b, v21
	v_exp_f32_e32 v14, v14
	s_nop 0
	v_add_f32_e32 v14, 1.0, v14
	v_rcp_f32_e32 v23, v14
	v_lshlrev_b32_e32 v14, 16, v15
	v_and_b32_e32 v15, 0xffff0000, v15
	v_pk_mul_f32 v[20:21], v[22:23], v[20:21]
	v_mul_f32_e32 v22, 0xbfb8aa3b, v14
	v_mul_f32_e32 v23, 0xbfb8aa3b, v15
	v_exp_f32_e32 v22, v22
	v_exp_f32_e32 v23, v23
	v_add_f32_e32 v22, 1.0, v22
	v_add_f32_e32 v23, 1.0, v23
	v_rcp_f32_e32 v22, v22
	v_rcp_f32_e32 v23, v23
	s_nop 0
	v_pk_mul_f32 v[14:15], v[22:23], v[14:15]
	v_min_i32_e32 v22, 3, v140

.LBB0_112:
	s_and_b64 s[2:3], s[82:83], exec
	s_cselect_b32 s19, s5, s18
	s_ashr_i32 s2, s19, 6
	s_ashr_i32 s3, s2, 31
	s_lshl_b64 s[28:29], s[2:3], 11
	s_lshl_b32 s2, s19, 5
	s_and_b32 s2, s2, 0x7e0
	v_add_u32_e32 v142, s2, v161
	s_cmp_lt_i32 s26, 2
	s_mov_b64 s[2:3], -1
	s_cbranch_scc1 .LBB0_194
	s_cmp_gt_i32 s26, 2
	s_cbranch_scc0 .LBB0_161
	v_cmp_lt_i32_e32 vcc, 14, v142
	v_mov_b32_e32 v110, 0
	v_mov_b32_e32 v12, 0
	v_mov_b32_e32 v13, 0
	v_mov_b32_e32 v14, 0
	v_mov_b32_e32 v15, 0
	s_and_saveexec_b64 s[2:3], vcc
	s_cbranch_execz .LBB0_116
	v_add_u32_e32 v8, -15, v142
	v_mov_b32_e32 v9, v97
	v_lshl_add_u64 v[8:9], s[28:29], 0, v[8:9]
	v_lshlrev_b64 v[8:9], 11, v[8:9]
	v_lshl_add_u64 v[8:9], v[134:135], 0, v[8:9]
	global_load_dwordx4 v[12:15], v[8:9], off nt
.LBB0_116:
	s_or_b64 exec, exec, s[2:3]
	v_cmp_lt_i32_e32 vcc, 13, v142
	v_mov_b32_e32 v111, 0
	v_mov_b32_e32 v112, 0
	v_mov_b32_e32 v113, 0
	s_and_saveexec_b64 s[2:3], vcc
	s_cbranch_execz .LBB0_118
	v_add_u32_e32 v8, -14, v142
	v_mov_b32_e32 v9, v97
	v_lshl_add_u64 v[8:9], s[28:29], 0, v[8:9]
	v_lshlrev_b64 v[8:9], 11, v[8:9]
	v_lshl_add_u64 v[8:9], v[134:135], 0, v[8:9]
	global_load_dwordx4 v[110:113], v[8:9], off nt
.LBB0_118:
	s_or_b64 exec, exec, s[2:3]
	v_cmp_lt_i32_e32 vcc, 12, v142
	v_mov_b32_e32 v16, 0
	v_mov_b32_e32 v114, 0
	v_mov_b32_e32 v115, 0
	v_mov_b32_e32 v116, 0
	v_mov_b32_e32 v117, 0
	s_and_saveexec_b64 s[2:3], vcc
	s_cbranch_execz .LBB0_120
	v_add_u32_e32 v8, -13, v142
	v_mov_b32_e32 v9, v97
	v_lshl_add_u64 v[8:9], s[28:29], 0, v[8:9]
	v_lshlrev_b64 v[8:9], 11, v[8:9]
	v_lshl_add_u64 v[8:9], v[134:135], 0, v[8:9]
	global_load_dwordx4 v[114:117], v[8:9], off nt
.LBB0_120:
	s_or_b64 exec, exec, s[2:3]
	v_cmp_lt_i32_e32 vcc, 11, v142
	v_mov_b32_e32 v17, 0
	v_mov_b32_e32 v18, 0
	v_mov_b32_e32 v19, 0
	s_and_saveexec_b64 s[2:3], vcc
	s_cbranch_execz .LBB0_122
	v_add_u32_e32 v8, -12, v142
	v_mov_b32_e32 v9, v97
	v_lshl_add_u64 v[8:9], s[28:29], 0, v[8:9]
	v_lshlrev_b64 v[8:9], 11, v[8:9]
	v_lshl_add_u64 v[8:9], v[134:135], 0, v[8:9]
	global_load_dwordx4 v[16:19], v[8:9], off nt
.LBB0_122:
	s_or_b64 exec, exec, s[2:3]
	v_cmp_lt_i32_e32 vcc, 10, v142
	v_mov_b32_e32 v20, 0
	v_mov_b32_e32 v24, 0
	v_mov_b32_e32 v25, 0
	v_mov_b32_e32 v26, 0
	v_mov_b32_e32 v27, 0
	s_and_saveexec_b64 s[2:3], vcc
	s_cbranch_execz .LBB0_124
	v_add_u32_e32 v8, -11, v142
	v_mov_b32_e32 v9, v97
	v_lshl_add_u64 v[8:9], s[28:29], 0, v[8:9]
	v_lshlrev_b64 v[8:9], 11, v[8:9]
	v_lshl_add_u64 v[8:9], v[134:135], 0, v[8:9]
	global_load_dwordx4 v[24:27], v[8:9], off nt
.LBB0_124:
	s_or_b64 exec, exec, s[2:3]
	v_cmp_lt_i32_e32 vcc, 9, v142
	v_mov_b32_e32 v21, 0
	v_mov_b32_e32 v22, 0
	v_mov_b32_e32 v23, 0
	s_and_saveexec_b64 s[2:3], vcc
	s_cbranch_execz .LBB0_126
	v_add_u32_e32 v8, -10, v142
	v_mov_b32_e32 v9, v97
	v_lshl_add_u64 v[8:9], s[28:29], 0, v[8:9]
	v_lshlrev_b64 v[8:9], 11, v[8:9]
	v_lshl_add_u64 v[8:9], v[134:135], 0, v[8:9]
	global_load_dwordx4 v[20:23], v[8:9], off nt
.LBB0_126:
	s_or_b64 exec, exec, s[2:3]
	v_cmp_lt_i32_e32 vcc, 8, v142
	v_mov_b32_e32 v28, 0
	v_mov_b32_e32 v32, 0
	v_mov_b32_e32 v33, 0
	v_mov_b32_e32 v34, 0
	v_mov_b32_e32 v35, 0
	s_and_saveexec_b64 s[2:3], vcc
	s_cbranch_execz .LBB0_128
	v_add_u32_e32 v8, -9, v142
	v_mov_b32_e32 v9, v97
	v_lshl_add_u64 v[8:9], s[28:29], 0, v[8:9]
	v_lshlrev_b64 v[8:9], 11, v[8:9]
	v_lshl_add_u64 v[8:9], v[134:135], 0, v[8:9]
	global_load_dwordx4 v[32:35], v[8:9], off nt
.LBB0_128:
	s_or_b64 exec, exec, s[2:3]
	v_cmp_lt_i32_e32 vcc, 7, v142
	v_mov_b32_e32 v29, 0
	v_mov_b32_e32 v30, 0
	v_mov_b32_e32 v31, 0
	s_and_saveexec_b64 s[2:3], vcc
	s_cbranch_execz .LBB0_130
	v_add_u32_e32 v8, -8, v142
	v_mov_b32_e32 v9, v97
	v_lshl_add_u64 v[8:9], s[28:29], 0, v[8:9]
	v_lshlrev_b64 v[8:9], 11, v[8:9]
	v_lshl_add_u64 v[8:9], v[134:135], 0, v[8:9]
	global_load_dwordx4 v[28:31], v[8:9], off nt
.LBB0_130:
	s_or_b64 exec, exec, s[2:3]
	v_cmp_lt_i32_e32 vcc, 6, v142
	v_mov_b32_e32 v36, 0
	v_mov_b32_e32 v40, 0
	v_mov_b32_e32 v41, 0
	v_mov_b32_e32 v42, 0
	v_mov_b32_e32 v43, 0
	s_and_saveexec_b64 s[2:3], vcc
	s_cbranch_execz .LBB0_132
	v_add_u32_e32 v8, -7, v142
	v_mov_b32_e32 v9, v97
	v_lshl_add_u64 v[8:9], s[28:29], 0, v[8:9]
	v_lshlrev_b64 v[8:9], 11, v[8:9]
	v_lshl_add_u64 v[8:9], v[134:135], 0, v[8:9]
	global_load_dwordx4 v[40:43], v[8:9], off nt
.LBB0_132:
	s_or_b64 exec, exec, s[2:3]
	v_cmp_lt_i32_e32 vcc, 5, v142
	v_mov_b32_e32 v37, 0
	v_mov_b32_e32 v38, 0
	v_mov_b32_e32 v39, 0
	s_and_saveexec_b64 s[2:3], vcc
	s_cbranch_execz .LBB0_134
	v_add_u32_e32 v8, -6, v142
	v_mov_b32_e32 v9, v97
	v_lshl_add_u64 v[8:9], s[28:29], 0, v[8:9]
	v_lshlrev_b64 v[8:9], 11, v[8:9]
	v_lshl_add_u64 v[8:9], v[134:135], 0, v[8:9]
	global_load_dwordx4 v[36:39], v[8:9], off nt
.LBB0_134:
	s_or_b64 exec, exec, s[2:3]
	v_cmp_lt_i32_e32 vcc, 4, v142
	v_mov_b32_e32 v118, 0
	v_mov_b32_e32 v44, 0
	v_mov_b32_e32 v45, 0
	v_mov_b32_e32 v46, 0
	v_mov_b32_e32 v47, 0
	s_and_saveexec_b64 s[2:3], vcc
	s_cbranch_execz .LBB0_136
	v_add_u32_e32 v8, -5, v142
	v_mov_b32_e32 v9, v97
	v_lshl_add_u64 v[8:9], s[28:29], 0, v[8:9]
	v_lshlrev_b64 v[8:9], 11, v[8:9]
	v_lshl_add_u64 v[8:9], v[134:135], 0, v[8:9]
	global_load_dwordx4 v[44:47], v[8:9], off nt
.LBB0_136:
	s_or_b64 exec, exec, s[2:3]
	v_cmp_lt_i32_e32 vcc, 3, v142
	v_mov_b32_e32 v119, 0
	v_mov_b32_e32 v120, 0
	v_mov_b32_e32 v121, 0
	s_and_saveexec_b64 s[2:3], vcc
	s_cbranch_execz .LBB0_138
	v_add_u32_e32 v8, -4, v142
	v_mov_b32_e32 v9, v97
	v_lshl_add_u64 v[8:9], s[28:29], 0, v[8:9]
	v_lshlrev_b64 v[8:9], 11, v[8:9]
	v_lshl_add_u64 v[8:9], v[134:135], 0, v[8:9]
	global_load_dwordx4 v[118:121], v[8:9], off nt
.LBB0_138:
	s_or_b64 exec, exec, s[2:3]
	v_cmp_lt_i32_e32 vcc, 2, v142
	v_mov_b32_e32 v122, 0
	v_mov_b32_e32 v126, 0
	v_mov_b32_e32 v127, 0
	v_mov_b32_e32 v128, 0
	v_mov_b32_e32 v129, 0
	s_and_saveexec_b64 s[2:3], vcc
	s_cbranch_execz .LBB0_140
	v_add_u32_e32 v8, -3, v142
	v_mov_b32_e32 v9, v97
	v_lshl_add_u64 v[8:9], s[28:29], 0, v[8:9]
	v_lshlrev_b64 v[8:9], 11, v[8:9]
	v_lshl_add_u64 v[8:9], v[134:135], 0, v[8:9]
	global_load_dwordx4 v[126:129], v[8:9], off nt
.LBB0_140:
	s_or_b64 exec, exec, s[2:3]
	v_cmp_lt_i32_e32 vcc, 1, v142
	v_mov_b32_e32 v123, 0
	v_mov_b32_e32 v124, 0
	v_mov_b32_e32 v125, 0
	s_and_saveexec_b64 s[2:3], vcc
	s_cbranch_execz .LBB0_142
	v_add_u32_e32 v8, -2, v142
	v_mov_b32_e32 v9, v97
	v_lshl_add_u64 v[8:9], s[28:29], 0, v[8:9]
	v_lshlrev_b64 v[8:9], 11, v[8:9]
	v_lshl_add_u64 v[8:9], v[134:135], 0, v[8:9]
	global_load_dwordx4 v[122:125], v[8:9], off nt
.LBB0_142:
	s_or_b64 exec, exec, s[2:3]
	v_mov_b32_e32 v60, 0
	v_cmp_lt_i32_e32 vcc, 0, v142
	v_mov_b32_e32 v72, 0
	v_mov_b32_e32 v73, 0
	v_mov_b32_e32 v74, 0
	v_mov_b32_e32 v75, 0
	s_and_saveexec_b64 s[2:3], vcc
	s_cbranch_execz .LBB0_144
	v_add_u32_e32 v8, -1, v142
	v_mov_b32_e32 v9, v97
	v_lshl_add_u64 v[8:9], s[28:29], 0, v[8:9]
	v_lshlrev_b64 v[8:9], 11, v[8:9]
	v_lshl_add_u64 v[8:9], v[134:135], 0, v[8:9]
	global_load_dwordx4 v[72:75], v[8:9], off nt
.LBB0_144:
	s_or_b64 exec, exec, s[2:3]
	v_cmp_lt_i32_e32 vcc, -1, v142
	v_mov_b32_e32 v61, 0
	v_mov_b32_e32 v62, 0
	v_mov_b32_e32 v63, 0
	s_and_saveexec_b64 s[2:3], vcc
	s_cbranch_execz .LBB0_146
	v_mov_b32_e32 v143, v97
	v_lshl_add_u64 v[8:9], s[28:29], 0, v[142:143]
	v_lshlrev_b64 v[8:9], 11, v[8:9]
	v_lshl_add_u64 v[8:9], v[134:135], 0, v[8:9]
	global_load_dwordx4 v[60:63], v[8:9], off nt
.LBB0_146:
	s_or_b64 exec, exec, s[2:3]
	v_or_b32_e32 v158, 1, v142
	v_cmp_lt_i32_e32 vcc, -2, v142
	v_mov_b32_e32 v130, 0
	v_mov_b32_e32 v76, 0
	v_mov_b32_e32 v77, 0
	v_mov_b32_e32 v78, 0
	v_mov_b32_e32 v79, 0
	s_and_saveexec_b64 s[2:3], vcc
	s_cbranch_execz .LBB0_148
	v_mov_b32_e32 v159, v97
	v_lshl_add_u64 v[8:9], s[28:29], 0, v[158:159]
	v_lshlrev_b64 v[8:9], 11, v[8:9]
	v_lshl_add_u64 v[8:9], v[134:135], 0, v[8:9]
	global_load_dwordx4 v[76:79], v[8:9], off nt
.LBB0_148:
	s_or_b64 exec, exec, s[2:3]
	v_or_b32_e32 v156, 2, v142
	v_cmp_lt_i32_e32 vcc, -3, v142
	v_mov_b32_e32 v131, 0
	v_mov_b32_e32 v132, 0
	v_mov_b32_e32 v133, 0
	s_and_saveexec_b64 s[2:3], vcc
	s_cbranch_execz .LBB0_150
	v_mov_b32_e32 v157, v97
	v_lshl_add_u64 v[8:9], s[28:29], 0, v[156:157]
	v_lshlrev_b64 v[8:9], 11, v[8:9]
	v_lshl_add_u64 v[8:9], v[134:135], 0, v[8:9]
	global_load_dwordx4 v[130:133], v[8:9], off nt
.LBB0_150:
	s_or_b64 exec, exec, s[2:3]
	v_or_b32_e32 v196, 3, v142
	v_cmp_lt_i32_e32 vcc, -4, v142
	v_mov_b32_e32 v48, 0
	v_mov_b32_e32 v64, 0
	v_mov_b32_e32 v65, 0
	v_mov_b32_e32 v66, 0
	v_mov_b32_e32 v67, 0
	s_and_saveexec_b64 s[2:3], vcc
	s_cbranch_execz .LBB0_152
	v_mov_b32_e32 v197, v97
	v_lshl_add_u64 v[8:9], s[28:29], 0, v[196:197]
	v_lshlrev_b64 v[8:9], 11, v[8:9]
	v_lshl_add_u64 v[8:9], v[134:135], 0, v[8:9]
	global_load_dwordx4 v[64:67], v[8:9], off nt
.LBB0_152:
	s_or_b64 exec, exec, s[2:3]
	v_or_b32_e32 v198, 4, v142
	v_cmp_lt_i32_e32 vcc, -5, v142
	v_mov_b32_e32 v49, 0
	v_mov_b32_e32 v50, 0
	v_mov_b32_e32 v51, 0
	s_and_saveexec_b64 s[2:3], vcc
	s_cbranch_execz .LBB0_154
	v_mov_b32_e32 v199, v97
	v_lshl_add_u64 v[8:9], s[28:29], 0, v[198:199]
	v_lshlrev_b64 v[8:9], 11, v[8:9]
	v_lshl_add_u64 v[8:9], v[134:135], 0, v[8:9]
	global_load_dwordx4 v[48:51], v[8:9], off nt
.LBB0_154:
	s_or_b64 exec, exec, s[2:3]
	v_or_b32_e32 v200, 5, v142
	v_cmp_lt_i32_e32 vcc, -6, v142
	v_mov_b32_e32 v56, 0
	v_mov_b32_e32 v68, 0
	v_mov_b32_e32 v69, 0
	v_mov_b32_e32 v70, 0
	v_mov_b32_e32 v71, 0
	s_and_saveexec_b64 s[2:3], vcc
	s_cbranch_execz .LBB0_156
	v_mov_b32_e32 v201, v97
	v_lshl_add_u64 v[8:9], s[28:29], 0, v[200:201]
	v_lshlrev_b64 v[8:9], 11, v[8:9]
	v_lshl_add_u64 v[8:9], v[134:135], 0, v[8:9]
	global_load_dwordx4 v[68:71], v[8:9], off nt
.LBB0_156:
	s_or_b64 exec, exec, s[2:3]
	v_or_b32_e32 v144, 6, v142
	v_cmp_lt_i32_e32 vcc, -7, v142
	v_mov_b32_e32 v57, 0
	v_mov_b32_e32 v58, 0
	v_mov_b32_e32 v59, 0
	s_and_saveexec_b64 s[2:3], vcc
	s_cbranch_execz .LBB0_158
	v_mov_b32_e32 v145, v97
	v_lshl_add_u64 v[8:9], s[28:29], 0, v[144:145]
	v_lshlrev_b64 v[8:9], 11, v[8:9]
	v_lshl_add_u64 v[8:9], v[134:135], 0, v[8:9]
	global_load_dwordx4 v[56:59], v[8:9], off nt
.LBB0_158:
	s_or_b64 exec, exec, s[2:3]
	v_or_b32_e32 v140, 7, v142
	v_cmp_lt_i32_e32 vcc, -8, v142
	v_mov_b32_e32 v8, 0
	v_mov_b32_e32 v9, 0
	v_mov_b32_e32 v10, 0
	v_mov_b32_e32 v11, 0
	s_and_saveexec_b64 s[2:3], vcc
	s_cbranch_execz .LBB0_160
	v_mov_b32_e32 v141, v97
	v_lshl_add_u64 v[8:9], s[28:29], 0, v[140:141]
	v_lshlrev_b64 v[8:9], 11, v[8:9]
	v_lshl_add_u64 v[8:9], v[134:135], 0, v[8:9]
	global_load_dwordx4 v[8:11], v[8:9], off nt
.LBB0_160:
	s_or_b64 exec, exec, s[2:3]
	s_waitcnt vmcnt(0)
	v_lshlrev_b32_e32 v164, 16, v112
	v_and_b32_e32 v165, 0xffff0000, v112
	v_min_i32_e32 v112, 15, v142
	v_add_u32_e32 v112, 1, v112
	v_ashrrev_i32_e32 v143, 31, v142
	v_cvt_f32_i32_e32 v112, v112
	v_lshl_add_u64 v[52:53], s[28:29], 0, v[142:143]
	v_lshlrev_b64 v[182:183], 11, v[52:53]
	v_lshl_add_u64 v[52:53], v[136:137], 0, v[182:183]
	v_add_co_u32_e32 v54, vcc, s53, v52
	v_lshlrev_b32_e32 v146, 16, v113
	v_and_b32_e32 v147, 0xffff0000, v113
	v_div_scale_f32 v113, s[2:3], v112, v112, 1.0
	global_load_dwordx4 v[102:105], v[52:53], off nt
	global_load_dwordx4 v[106:109], v[52:53], off offset:2048 nt
	v_addc_co_u32_e32 v55, vcc, 0, v53, vcc
	v_lshlrev_b32_e32 v168, 16, v110
	v_and_b32_e32 v169, 0xffff0000, v110
	v_lshlrev_b32_e32 v186, 16, v111
	v_and_b32_e32 v187, 0xffff0000, v111
	v_lshlrev_b32_e32 v110, 16, v114
	v_and_b32_e32 v111, 0xffff0000, v114
	v_rcp_f32_e32 v114, v113
	v_add_co_u32_e32 v98, vcc, s58, v52
	v_lshlrev_b32_e32 v170, 16, v120
	s_nop 0
	v_addc_co_u32_e32 v99, vcc, 0, v53, vcc
	v_add_co_u32_e32 v52, vcc, s64, v52
	v_and_b32_e32 v171, 0xffff0000, v120
	v_min_i32_e32 v120, 15, v158
	v_addc_co_u32_e32 v53, vcc, 0, v53, vcc
	v_lshlrev_b32_e32 v184, 16, v115
	v_and_b32_e32 v185, 0xffff0000, v115
	v_fma_f32 v115, -v113, v114, 1.0
	v_add_u32_e32 v120, 1, v120
	v_fmac_f32_e32 v114, v115, v114
	v_div_scale_f32 v115, vcc, 1.0, v112, 1.0
	v_cvt_f32_i32_e32 v120, v120
	v_lshlrev_b32_e32 v206, 16, v118
	v_and_b32_e32 v207, 0xffff0000, v118
	v_mul_f32_e32 v118, v115, v114
	v_lshlrev_b32_e32 v192, 16, v119
	v_and_b32_e32 v193, 0xffff0000, v119
	v_fma_f32 v119, -v113, v118, v115
	v_fmac_f32_e32 v118, v119, v114
	v_fma_f32 v113, -v113, v118, v115
	v_div_scale_f32 v115, s[2:3], v120, v120, 1.0
	v_rcp_f32_e32 v119, v115
	v_div_fmas_f32 v113, v113, v114, v118
	v_lshlrev_b32_e32 v148, 16, v121
	v_and_b32_e32 v149, 0xffff0000, v121
	v_fma_f32 v114, -v115, v119, 1.0
	v_fmac_f32_e32 v119, v114, v119
	v_div_scale_f32 v114, vcc, 1.0, v120, 1.0
	v_mul_f32_e32 v118, v114, v119
	v_fma_f32 v121, -v115, v118, v114
	v_fmac_f32_e32 v118, v121, v119
	v_fma_f32 v114, -v115, v118, v114
	v_div_fmas_f32 v114, v114, v119, v118
	v_min_i32_e32 v118, 15, v156
	v_add_u32_e32 v118, 1, v118
	v_cvt_f32_i32_e32 v118, v118
	v_div_fixup_f32 v154, v114, v120, 1.0
	global_load_dwordx4 v[88:91], v[98:99], off nt
	global_load_dwordx4 v[84:87], v[98:99], off offset:2048 nt
	global_load_dwordx4 v[92:95], v[54:55], off offset:2048 nt
	global_load_dwordx4 v[80:83], v[52:53], off nt
	s_nop 0
	global_load_dwordx4 v[98:101], v[98:99], off offset:-4096 nt
	s_nop 0
	global_load_dwordx4 v[52:55], v[52:53], off offset:2048 nt
	v_div_scale_f32 v119, s[2:3], v118, v118, 1.0
	v_rcp_f32_e32 v120, v119
	v_lshlrev_b32_e32 v204, 16, v122
	v_and_b32_e32 v205, 0xffff0000, v122
	v_lshlrev_b32_e32 v190, 16, v123
	v_fma_f32 v121, -v119, v120, 1.0
	v_fmac_f32_e32 v120, v121, v120
	v_div_scale_f32 v121, vcc, 1.0, v118, 1.0
	v_mul_f32_e32 v122, v121, v120
	v_and_b32_e32 v191, 0xffff0000, v123
	v_fma_f32 v123, -v119, v122, v121
	v_fmac_f32_e32 v122, v123, v120
	v_fma_f32 v119, -v119, v122, v121
	v_div_fmas_f32 v119, v119, v120, v122
	v_min_i32_e32 v120, 15, v196
	v_add_u32_e32 v120, 1, v120
	v_cvt_f32_i32_e32 v122, v120
	v_lshlrev_b32_e32 v180, 16, v124
	v_and_b32_e32 v181, 0xffff0000, v124
	v_ashrrev_i32_e32 v157, 31, v156
	v_div_scale_f32 v123, s[2:3], v122, v122, 1.0
	v_rcp_f32_e32 v124, v123
	v_div_fixup_f32 v160, v119, v118, 1.0
	v_lshl_add_u64 v[118:119], s[28:29], 0, v[156:157]
	v_lshlrev_b64 v[118:119], 11, v[118:119]
	v_lshl_add_u64 v[120:121], v[138:139], 0, v[118:119]
	v_fma_f32 v118, -v123, v124, 1.0
	v_fmac_f32_e32 v124, v118, v124
	v_div_scale_f32 v118, vcc, 1.0, v122, 1.0
	v_mul_f32_e32 v119, v118, v124
	v_lshlrev_b32_e32 v150, 16, v125
	v_and_b32_e32 v151, 0xffff0000, v125
	v_fma_f32 v125, -v123, v119, v118
	v_fmac_f32_e32 v119, v125, v124
	v_fma_f32 v118, -v123, v119, v118
	v_div_fmas_f32 v118, v118, v124, v119
	v_min_i32_e32 v119, 15, v198
	v_add_u32_e32 v119, 1, v119
	v_cvt_f32_i32_e32 v123, v119
	v_ashrrev_i32_e32 v159, 31, v158
	v_lshl_add_u64 v[114:115], s[28:29], 0, v[158:159]
	v_div_fixup_f32 v158, v118, v122, 1.0
	v_div_scale_f32 v122, s[2:3], v123, v123, 1.0
	v_rcp_f32_e32 v124, v122
	v_lshlrev_b32_e32 v166, 16, v128
	v_and_b32_e32 v167, 0xffff0000, v128
	v_lshlrev_b32_e32 v202, 16, v126
	v_fma_f32 v125, -v122, v124, 1.0
	v_fmac_f32_e32 v124, v125, v124
	v_div_scale_f32 v125, vcc, 1.0, v123, 1.0
	v_mul_f32_e32 v128, v125, v124
	v_and_b32_e32 v203, 0xffff0000, v126
	v_lshlrev_b32_e32 v188, 16, v127
	v_and_b32_e32 v189, 0xffff0000, v127
	v_lshlrev_b32_e32 v126, 16, v129
	v_and_b32_e32 v127, 0xffff0000, v129
	v_fma_f32 v129, -v122, v128, v125
	v_fmac_f32_e32 v128, v129, v124
	v_fma_f32 v122, -v122, v128, v125
	v_div_fmas_f32 v122, v122, v124, v128
	v_min_i32_e32 v124, 15, v200
	v_add_u32_e32 v124, 1, v124
	v_cvt_f32_i32_e32 v124, v124
	s_waitcnt vmcnt(6)
	v_lshlrev_b32_e32 v228, 16, v106
	v_ashrrev_i32_e32 v199, 31, v198
	v_lshlrev_b32_e32 v224, 16, v12
	v_div_scale_f32 v125, s[2:3], v124, v124, 1.0
	v_rcp_f32_e32 v128, v125
	v_and_b32_e32 v225, 0xffff0000, v12
	v_and_b32_e32 v229, 0xffff0000, v106
	v_mul_f32_e32 v12, 0xbfb8aa3b, v228
	v_div_fixup_f32 v156, v122, v123, 1.0
	v_lshl_add_u64 v[122:123], s[28:29], 0, v[198:199]
	v_fma_f32 v129, -v125, v128, 1.0
	v_lshlrev_b32_e32 v198, 16, v16
	v_and_b32_e32 v199, 0xffff0000, v16
	v_exp_f32_e32 v12, v12
	v_mul_f32_e32 v16, 0xbfb8aa3b, v229
	v_fmac_f32_e32 v128, v129, v128
	v_div_scale_f32 v129, vcc, 1.0, v124, 1.0
	v_exp_f32_e32 v16, v16
	v_div_fixup_f32 v152, v113, v112, 1.0
	v_lshl_add_u64 v[112:113], v[138:139], 0, v[182:183]
	v_lshlrev_b32_e32 v182, 16, v132
	v_and_b32_e32 v183, 0xffff0000, v132
	v_mul_f32_e32 v132, v129, v128
	v_lshlrev_b32_e32 v208, 16, v130
	v_and_b32_e32 v209, 0xffff0000, v130
	v_lshlrev_b32_e32 v194, 16, v131
	v_and_b32_e32 v195, 0xffff0000, v131
	v_lshlrev_b32_e32 v130, 16, v133
	v_and_b32_e32 v131, 0xffff0000, v133
	v_fma_f32 v133, -v125, v132, v129
	v_fmac_f32_e32 v132, v133, v128
	v_add_f32_e32 v12, 1.0, v12
	v_pk_add_f32 v[242:243], v[224:225], 0 op_sel_hi:[1,0]
	v_fma_f32 v125, -v125, v132, v129
	v_rcp_f32_e32 v232, v12
	v_add_f32_e32 v12, 1.0, v16
	v_pk_add_f32 v[242:243], v[242:243], v[168:169]
	v_div_fmas_f32 v125, v125, v128, v132
	v_ashrrev_i32_e32 v201, 31, v200
	v_rcp_f32_e32 v233, v12
	v_pk_add_f32 v[242:243], v[242:243], v[110:111]
	v_div_fixup_f32 v132, v125, v124, 1.0
	v_lshl_add_u64 v[124:125], s[28:29], 0, v[200:201]
	v_lshlrev_b32_e32 v200, 16, v24
	v_and_b32_e32 v201, 0xffff0000, v24
	v_pk_add_f32 v[242:243], v[242:243], v[198:199]
	v_ashrrev_i32_e32 v197, 31, v196
	v_lshlrev_b32_e32 v222, 16, v20
	v_and_b32_e32 v223, 0xffff0000, v20
	v_pk_add_f32 v[242:243], v[242:243], v[200:201]
	v_lshl_add_u64 v[118:119], s[28:29], 0, v[196:197]
	v_lshlrev_b32_e32 v196, 16, v32
	v_and_b32_e32 v197, 0xffff0000, v32
	v_pk_add_f32 v[242:243], v[242:243], v[222:223]
	v_pk_mul_f32 v[228:229], v[232:233], v[228:229]
	v_lshlrev_b32_e32 v232, 16, v28
	v_and_b32_e32 v233, 0xffff0000, v28
	v_pk_add_f32 v[242:243], v[242:243], v[196:197]
	v_lshlrev_b32_e32 v236, 16, v40
	v_and_b32_e32 v237, 0xffff0000, v40
	v_pk_add_f32 v[232:233], v[242:243], v[232:233]
	v_lshlrev_b32_e32 v238, 16, v36
	v_and_b32_e32 v239, 0xffff0000, v36
	v_pk_add_f32 v[232:233], v[232:233], v[236:237]
	v_lshlrev_b32_e32 v240, 16, v44
	v_and_b32_e32 v241, 0xffff0000, v44
	v_pk_add_f32 v[232:233], v[232:233], v[238:239]
	v_lshlrev_b32_e32 v226, 16, v72
	v_pk_add_f32 v[232:233], v[232:233], v[240:241]
	v_and_b32_e32 v227, 0xffff0000, v72
	v_pk_add_f32 v[206:207], v[232:233], v[206:207]
	v_lshlrev_b32_e32 v232, 16, v102
	v_and_b32_e32 v233, 0xffff0000, v102
	v_mul_f32_e32 v12, 0xbfb8aa3b, v232
	v_exp_f32_e32 v12, v12
	v_mul_f32_e32 v16, 0xbfb8aa3b, v233
	v_exp_f32_e32 v16, v16
	v_pk_add_f32 v[202:203], v[206:207], v[202:203]
	v_add_f32_e32 v12, 1.0, v12
	v_rcp_f32_e32 v206, v12
	v_add_f32_e32 v12, 1.0, v16
	v_rcp_f32_e32 v207, v12
	v_pk_add_f32 v[202:203], v[202:203], v[204:205]
	v_lshlrev_b32_e32 v230, 16, v60
	v_and_b32_e32 v231, 0xffff0000, v60
	v_pk_add_f32 v[202:203], v[202:203], v[226:227]
	v_pk_mul_f32 v[204:205], v[206:207], v[232:233]
	v_pk_add_f32 v[202:203], v[202:203], v[230:231]
	v_lshlrev_b32_e32 v234, 16, v76
	v_pk_fma_f32 v[206:207], v[152:153], v[202:203], v[230:231] op_sel_hi:[0,1,1] neg_lo:[0,0,1] neg_hi:[0,0,1]
	v_pk_mul_f32 v[206:207], v[4:5], v[206:207]
	v_and_b32_e32 v235, 0xffff0000, v76
	v_pk_mul_f32 v[204:205], v[206:207], v[204:205]
	s_waitcnt vmcnt(1)
	v_lshlrev_b32_e32 v206, 16, v98
	v_and_b32_e32 v207, 0xffff0000, v98
	v_mul_f32_e32 v16, 0xbfb8aa3b, v206
	v_exp_f32_e32 v16, v16
	v_mul_f32_e32 v20, 0xbfb8aa3b, v207
	v_pk_add_f32 v[202:203], v[202:203], v[224:225] neg_lo:[0,1] neg_hi:[0,1]
	v_exp_f32_e32 v20, v20
	v_pk_add_f32 v[202:203], v[202:203], v[234:235]
	v_cvt_pk_bf16_f32 v12, v204, v205
	v_pk_fma_f32 v[204:205], v[154:155], v[202:203], v[234:235] op_sel_hi:[0,1,1] neg_lo:[0,0,1] neg_hi:[0,0,1]
	v_pk_mul_f32 v[204:205], v[4:5], v[204:205]
	v_add_f32_e32 v16, 1.0, v16
	v_pk_add_f32 v[168:169], v[202:203], v[168:169] neg_lo:[0,1] neg_hi:[0,1]
	v_pk_mul_f32 v[204:205], v[204:205], v[228:229]
	v_rcp_f32_e32 v224, v16
	v_add_f32_e32 v16, 1.0, v20
	v_pk_add_f32 v[168:169], v[168:169], v[208:209]
	v_rcp_f32_e32 v225, v16
	v_cvt_pk_bf16_f32 v16, v204, v205
	v_pk_fma_f32 v[204:205], v[160:161], v[168:169], v[208:209] op_sel_hi:[0,1,1] neg_lo:[0,0,1] neg_hi:[0,0,1]
	v_pk_add_f32 v[110:111], v[168:169], v[110:111] neg_lo:[0,1] neg_hi:[0,1]
	v_lshlrev_b32_e32 v168, 16, v92
	v_and_b32_e32 v169, 0xffff0000, v92
	v_mul_f32_e32 v20, 0xbfb8aa3b, v168
	v_exp_f32_e32 v24, v20
	v_mul_f32_e32 v20, 0xbfb8aa3b, v169
	v_exp_f32_e32 v28, v20
	v_pk_mul_f32 v[202:203], v[224:225], v[206:207]
	v_pk_mul_f32 v[204:205], v[4:5], v[204:205]
	v_add_f32_e32 v24, 1.0, v24
	v_pk_mul_f32 v[202:203], v[204:205], v[202:203]
	v_lshlrev_b32_e32 v204, 16, v64
	v_cvt_pk_bf16_f32 v20, v202, v203
	v_rcp_f32_e32 v202, v24
	v_add_f32_e32 v24, 1.0, v28
	v_rcp_f32_e32 v203, v24
	v_and_b32_e32 v205, 0xffff0000, v64
	v_pk_add_f32 v[110:111], v[110:111], v[204:205]
	v_min_i32_e32 v128, 15, v144
	v_pk_mul_f32 v[168:169], v[202:203], v[168:169]
	v_pk_fma_f32 v[202:203], v[158:159], v[110:111], v[204:205] op_sel_hi:[0,1,1] neg_lo:[0,0,1] neg_hi:[0,0,1]
	v_pk_add_f32 v[110:111], v[110:111], v[198:199] neg_lo:[0,1] neg_hi:[0,1]
	v_lshlrev_b32_e32 v198, 16, v88
	v_and_b32_e32 v199, 0xffff0000, v88
	v_mul_f32_e32 v24, 0xbfb8aa3b, v198
	v_exp_f32_e32 v28, v24
	v_mul_f32_e32 v24, 0xbfb8aa3b, v199
	v_exp_f32_e32 v32, v24
	v_pk_mul_f32 v[202:203], v[4:5], v[202:203]
	v_add_f32_e32 v28, 1.0, v28
	v_pk_mul_f32 v[168:169], v[202:203], v[168:169]
	v_lshlrev_b32_e32 v202, 16, v48
	v_cvt_pk_bf16_f32 v24, v168, v169
	v_rcp_f32_e32 v168, v28
	v_add_f32_e32 v28, 1.0, v32
	v_rcp_f32_e32 v169, v28
	v_and_b32_e32 v203, 0xffff0000, v48
	v_pk_add_f32 v[110:111], v[110:111], v[202:203]
	v_add_u32_e32 v128, 1, v128
	v_pk_mul_f32 v[168:169], v[168:169], v[198:199]
	v_pk_fma_f32 v[198:199], v[156:157], v[110:111], v[202:203] op_sel_hi:[0,1,1] neg_lo:[0,0,1] neg_hi:[0,0,1]
	v_pk_mul_f32 v[198:199], v[4:5], v[198:199]
	v_cvt_f32_i32_e32 v128, v128
	v_pk_mul_f32 v[168:169], v[198:199], v[168:169]
	v_lshlrev_b32_e32 v198, 16, v84
	v_and_b32_e32 v199, 0xffff0000, v84
	v_mul_f32_e32 v28, 0xbfb8aa3b, v198
	v_exp_f32_e32 v32, v28
	v_mul_f32_e32 v28, 0xbfb8aa3b, v199
	v_exp_f32_e32 v36, v28
	v_div_scale_f32 v129, s[2:3], v128, v128, 1.0
	v_rcp_f32_e32 v133, v129
	v_add_f32_e32 v32, 1.0, v32
	v_cvt_pk_bf16_f32 v28, v168, v169
	v_rcp_f32_e32 v168, v32
	v_add_f32_e32 v32, 1.0, v36
	v_rcp_f32_e32 v169, v32
	v_fma_f32 v141, -v129, v133, 1.0
	v_pk_add_f32 v[110:111], v[110:111], v[200:201] neg_lo:[0,1] neg_hi:[0,1]
	v_lshlrev_b32_e32 v200, 16, v68
	v_and_b32_e32 v201, 0xffff0000, v68
	v_fmac_f32_e32 v133, v141, v133
	v_pk_add_f32 v[110:111], v[110:111], v[200:201]
	v_pk_mul_f32 v[168:169], v[168:169], v[198:199]
	v_pk_fma_f32 v[198:199], v[132:133], v[110:111], v[200:201] op_sel_hi:[0,1,1] neg_lo:[0,0,1] neg_hi:[0,0,1]
	v_pk_mul_f32 v[198:199], v[4:5], v[198:199]
	v_div_scale_f32 v141, vcc, 1.0, v128, 1.0
	v_pk_mul_f32 v[168:169], v[198:199], v[168:169]
	v_lshlrev_b32_e32 v198, 16, v80
	v_and_b32_e32 v199, 0xffff0000, v80
	v_mul_f32_e32 v32, 0xbfb8aa3b, v198
	v_exp_f32_e32 v36, v32
	v_mul_f32_e32 v32, 0xbfb8aa3b, v199
	v_exp_f32_e32 v40, v32
	v_mul_f32_e32 v143, v141, v133
	v_add_f32_e32 v36, 1.0, v36
	v_fma_f32 v145, -v129, v143, v141
	v_cvt_pk_bf16_f32 v32, v168, v169
	v_rcp_f32_e32 v168, v36
	v_add_f32_e32 v36, 1.0, v40
	v_fmac_f32_e32 v143, v145, v133
	v_rcp_f32_e32 v169, v36
	v_fma_f32 v129, -v129, v143, v141
	v_div_fmas_f32 v129, v129, v133, v143
	v_pk_add_f32 v[110:111], v[110:111], v[222:223] neg_lo:[0,1] neg_hi:[0,1]
	v_lshlrev_b32_e32 v200, 16, v56
	v_and_b32_e32 v201, 0xffff0000, v56
	v_div_fixup_f32 v128, v129, v128, 1.0
	v_pk_add_f32 v[110:111], v[110:111], v[200:201]
	v_pk_mul_f32 v[168:169], v[168:169], v[198:199]
	v_pk_fma_f32 v[198:199], v[128:129], v[110:111], v[200:201] op_sel_hi:[0,1,1] neg_lo:[0,0,1] neg_hi:[0,0,1]
	v_lshlrev_b32_e32 v106, 16, v107
	v_pk_mul_f32 v[198:199], v[4:5], v[198:199]
	v_lshlrev_b32_e32 v204, 16, v13
	v_and_b32_e32 v205, 0xffff0000, v13
	v_and_b32_e32 v107, 0xffff0000, v107
	v_mul_f32_e32 v13, 0xbfb8aa3b, v106
	v_pk_mul_f32 v[168:169], v[198:199], v[168:169]
	v_lshlrev_b32_e32 v198, 16, v17
	v_and_b32_e32 v199, 0xffff0000, v17
	v_exp_f32_e32 v13, v13
	v_mul_f32_e32 v17, 0xbfb8aa3b, v107
	v_exp_f32_e32 v17, v17
	v_pk_add_f32 v[208:209], v[204:205], 0 op_sel_hi:[1,0]
	v_add_f32_e32 v13, 1.0, v13
	v_rcp_f32_e32 v206, v13
	v_add_f32_e32 v13, 1.0, v17
	v_pk_add_f32 v[208:209], v[208:209], v[186:187]
	v_rcp_f32_e32 v207, v13
	v_pk_add_f32 v[208:209], v[208:209], v[184:185]
	v_lshlrev_b32_e32 v200, 16, v25
	v_and_b32_e32 v201, 0xffff0000, v25
	v_pk_add_f32 v[208:209], v[208:209], v[198:199]
	v_lshlrev_b32_e32 v202, 16, v21
	v_and_b32_e32 v203, 0xffff0000, v21
	v_pk_add_f32 v[208:209], v[208:209], v[200:201]
	v_pk_add_f32 v[110:111], v[110:111], v[196:197] neg_lo:[0,1] neg_hi:[0,1]
	v_lshlrev_b32_e32 v196, 16, v33
	v_and_b32_e32 v197, 0xffff0000, v33
	v_pk_add_f32 v[208:209], v[208:209], v[202:203]
	v_pk_mul_f32 v[106:107], v[206:207], v[106:107]
	v_lshlrev_b32_e32 v206, 16, v29
	v_and_b32_e32 v207, 0xffff0000, v29
	v_pk_add_f32 v[208:209], v[208:209], v[196:197]
	v_lshlrev_b32_e32 v40, 16, v41
	v_and_b32_e32 v41, 0xffff0000, v41
	v_pk_add_f32 v[206:207], v[208:209], v[206:207]
	v_lshlrev_b32_e32 v36, 16, v37
	v_and_b32_e32 v37, 0xffff0000, v37
	v_pk_add_f32 v[40:41], v[206:207], v[40:41]
	v_lshlrev_b32_e32 v44, 16, v45
	v_pk_add_f32 v[36:37], v[40:41], v[36:37]
	v_lshlrev_b32_e32 v40, 16, v103
	v_and_b32_e32 v41, 0xffff0000, v103
	v_mul_f32_e32 v13, 0xbfb8aa3b, v40
	v_exp_f32_e32 v13, v13
	v_mul_f32_e32 v17, 0xbfb8aa3b, v41
	v_exp_f32_e32 v17, v17
	v_and_b32_e32 v45, 0xffff0000, v45
	v_pk_add_f32 v[36:37], v[36:37], v[44:45]
	v_add_f32_e32 v13, 1.0, v13
	v_pk_add_f32 v[36:37], v[36:37], v[192:193]
	v_rcp_f32_e32 v44, v13
	v_add_f32_e32 v13, 1.0, v17
	v_pk_add_f32 v[36:37], v[36:37], v[188:189]
	v_rcp_f32_e32 v45, v13
	v_lshlrev_b32_e32 v72, 16, v73
	v_and_b32_e32 v73, 0xffff0000, v73
	v_pk_add_f32 v[36:37], v[36:37], v[190:191]
	v_lshlrev_b32_e32 v60, 16, v61
	v_and_b32_e32 v61, 0xffff0000, v61
	v_pk_add_f32 v[36:37], v[36:37], v[72:73]
	v_pk_mul_f32 v[40:41], v[44:45], v[40:41]
	v_pk_add_f32 v[36:37], v[36:37], v[60:61]
	v_lshlrev_b32_e32 v76, 16, v77
	v_pk_fma_f32 v[44:45], v[152:153], v[36:37], v[60:61] op_sel_hi:[0,1,1] neg_lo:[0,0,1] neg_hi:[0,0,1]
	v_pk_mul_f32 v[44:45], v[6:7], v[44:45]
	v_and_b32_e32 v77, 0xffff0000, v77
	v_pk_mul_f32 v[40:41], v[44:45], v[40:41]
	v_lshlrev_b32_e32 v44, 16, v99
	v_and_b32_e32 v45, 0xffff0000, v99
	v_mul_f32_e32 v17, 0xbfb8aa3b, v44
	v_exp_f32_e32 v17, v17
	v_mul_f32_e32 v21, 0xbfb8aa3b, v45
	v_exp_f32_e32 v21, v21
	v_pk_add_f32 v[36:37], v[36:37], v[204:205] neg_lo:[0,1] neg_hi:[0,1]
	v_add_f32_e32 v17, 1.0, v17
	v_rcp_f32_e32 v60, v17
	v_add_f32_e32 v17, 1.0, v21
	v_pk_add_f32 v[36:37], v[36:37], v[76:77]
	v_rcp_f32_e32 v61, v17
	v_cvt_pk_bf16_f32 v13, v40, v41
	v_pk_fma_f32 v[40:41], v[154:155], v[36:37], v[76:77] op_sel_hi:[0,1,1] neg_lo:[0,0,1] neg_hi:[0,0,1]
	v_pk_mul_f32 v[40:41], v[6:7], v[40:41]
	v_pk_add_f32 v[36:37], v[36:37], v[186:187] neg_lo:[0,1] neg_hi:[0,1]
	v_pk_mul_f32 v[40:41], v[40:41], v[106:107]
	v_pk_add_f32 v[36:37], v[36:37], v[194:195]
	v_cvt_pk_bf16_f32 v17, v40, v41
	v_pk_mul_f32 v[40:41], v[60:61], v[44:45]
	v_pk_fma_f32 v[44:45], v[160:161], v[36:37], v[194:195] op_sel_hi:[0,1,1] neg_lo:[0,0,1] neg_hi:[0,0,1]
	v_pk_mul_f32 v[44:45], v[6:7], v[44:45]
	v_pk_add_f32 v[36:37], v[36:37], v[184:185] neg_lo:[0,1] neg_hi:[0,1]
	v_pk_mul_f32 v[40:41], v[44:45], v[40:41]
	v_lshlrev_b32_e32 v44, 16, v93
	v_and_b32_e32 v45, 0xffff0000, v93
	v_mul_f32_e32 v21, 0xbfb8aa3b, v44
	v_exp_f32_e32 v25, v21
	v_mul_f32_e32 v21, 0xbfb8aa3b, v45
	v_exp_f32_e32 v29, v21
	v_cvt_pk_bf16_f32 v21, v40, v41
	v_add_f32_e32 v25, 1.0, v25
	v_rcp_f32_e32 v40, v25
	v_add_f32_e32 v25, 1.0, v29
	v_rcp_f32_e32 v41, v25
	v_lshlrev_b32_e32 v60, 16, v65
	v_and_b32_e32 v61, 0xffff0000, v65
	v_pk_add_f32 v[36:37], v[36:37], v[60:61]
	v_pk_mul_f32 v[40:41], v[40:41], v[44:45]
	v_pk_fma_f32 v[44:45], v[158:159], v[36:37], v[60:61] op_sel_hi:[0,1,1] neg_lo:[0,0,1] neg_hi:[0,0,1]
	v_pk_mul_f32 v[44:45], v[6:7], v[44:45]
	v_pk_add_f32 v[36:37], v[36:37], v[198:199] neg_lo:[0,1] neg_hi:[0,1]
	v_pk_mul_f32 v[40:41], v[44:45], v[40:41]
	v_lshlrev_b32_e32 v44, 16, v89
	v_and_b32_e32 v45, 0xffff0000, v89
	v_mul_f32_e32 v25, 0xbfb8aa3b, v44
	v_exp_f32_e32 v29, v25
	v_mul_f32_e32 v25, 0xbfb8aa3b, v45
	v_exp_f32_e32 v33, v25
	v_cvt_pk_bf16_f32 v25, v40, v41
	v_add_f32_e32 v29, 1.0, v29
	v_rcp_f32_e32 v40, v29
	v_add_f32_e32 v29, 1.0, v33
	v_rcp_f32_e32 v41, v29
	v_lshlrev_b32_e32 v48, 16, v49
	v_and_b32_e32 v49, 0xffff0000, v49
	v_pk_add_f32 v[36:37], v[36:37], v[48:49]
	v_pk_mul_f32 v[40:41], v[40:41], v[44:45]
	v_pk_fma_f32 v[44:45], v[156:157], v[36:37], v[48:49] op_sel_hi:[0,1,1] neg_lo:[0,0,1] neg_hi:[0,0,1]
	v_pk_mul_f32 v[44:45], v[6:7], v[44:45]
	v_pk_add_f32 v[36:37], v[36:37], v[200:201] neg_lo:[0,1] neg_hi:[0,1]
	v_pk_mul_f32 v[40:41], v[44:45], v[40:41]
	v_lshlrev_b32_e32 v44, 16, v85
	v_and_b32_e32 v45, 0xffff0000, v85
	v_mul_f32_e32 v29, 0xbfb8aa3b, v44
	v_exp_f32_e32 v33, v29
	v_mul_f32_e32 v29, 0xbfb8aa3b, v45
	v_exp_f32_e32 v48, v29
	v_cvt_pk_bf16_f32 v29, v40, v41
	v_add_f32_e32 v33, 1.0, v33
	v_rcp_f32_e32 v40, v33
	v_add_f32_e32 v33, 1.0, v48
	v_rcp_f32_e32 v41, v33
	v_lshlrev_b32_e32 v48, 16, v69
	v_and_b32_e32 v49, 0xffff0000, v69
	v_pk_add_f32 v[36:37], v[36:37], v[48:49]
	v_pk_mul_f32 v[40:41], v[40:41], v[44:45]
	v_pk_fma_f32 v[44:45], v[132:133], v[36:37], v[48:49] op_sel_hi:[0,1,1] neg_lo:[0,0,1] neg_hi:[0,0,1]
	v_pk_mul_f32 v[44:45], v[6:7], v[44:45]
	v_pk_add_f32 v[36:37], v[36:37], v[202:203] neg_lo:[0,1] neg_hi:[0,1]
	v_pk_mul_f32 v[40:41], v[44:45], v[40:41]
	v_lshlrev_b32_e32 v44, 16, v81
	v_and_b32_e32 v45, 0xffff0000, v81
	v_mul_f32_e32 v33, 0xbfb8aa3b, v44
	v_exp_f32_e32 v48, v33
	v_mul_f32_e32 v33, 0xbfb8aa3b, v45
	v_exp_f32_e32 v49, v33
	v_cvt_pk_bf16_f32 v33, v40, v41
	v_add_f32_e32 v40, 1.0, v48
	v_rcp_f32_e32 v40, v40
	v_add_f32_e32 v41, 1.0, v49
	v_rcp_f32_e32 v41, v41
	v_lshlrev_b32_e32 v48, 16, v57
	v_and_b32_e32 v49, 0xffff0000, v57
	v_lshlrev_b32_e32 v72, 16, v108
	v_pk_add_f32 v[36:37], v[36:37], v[48:49]
	v_lshlrev_b32_e32 v64, 16, v14
	v_and_b32_e32 v65, 0xffff0000, v14
	v_and_b32_e32 v73, 0xffff0000, v108
	v_mul_f32_e32 v14, 0xbfb8aa3b, v72
	v_pk_mul_f32 v[40:41], v[40:41], v[44:45]
	v_pk_fma_f32 v[44:45], v[128:129], v[36:37], v[48:49] op_sel_hi:[0,1,1] neg_lo:[0,0,1] neg_hi:[0,0,1]
	v_lshlrev_b32_e32 v48, 16, v18
	v_and_b32_e32 v49, 0xffff0000, v18
	v_exp_f32_e32 v14, v14
	v_mul_f32_e32 v18, 0xbfb8aa3b, v73
	v_exp_f32_e32 v18, v18
	v_pk_add_f32 v[102:103], v[64:65], 0 op_sel_hi:[1,0]
	v_add_f32_e32 v14, 1.0, v14
	v_lshlrev_b32_e32 v162, 16, v116
	v_and_b32_e32 v163, 0xffff0000, v116
	v_rcp_f32_e32 v80, v14
	v_add_f32_e32 v14, 1.0, v18
	v_pk_add_f32 v[102:103], v[102:103], v[164:165]
	v_rcp_f32_e32 v81, v14
	v_pk_add_f32 v[102:103], v[102:103], v[162:163]
	v_lshlrev_b32_e32 v56, 16, v26
	v_and_b32_e32 v57, 0xffff0000, v26
	v_pk_add_f32 v[102:103], v[102:103], v[48:49]
	v_pk_mul_f32 v[44:45], v[6:7], v[44:45]
	v_lshlrev_b32_e32 v60, 16, v22
	v_and_b32_e32 v61, 0xffff0000, v22
	v_pk_add_f32 v[102:103], v[102:103], v[56:57]
	v_pk_mul_f32 v[40:41], v[44:45], v[40:41]
	v_lshlrev_b32_e32 v44, 16, v34
	v_and_b32_e32 v45, 0xffff0000, v34
	v_pk_add_f32 v[102:103], v[102:103], v[60:61]
	v_pk_mul_f32 v[72:73], v[80:81], v[72:73]
	v_lshlrev_b32_e32 v80, 16, v30
	v_and_b32_e32 v81, 0xffff0000, v30
	v_pk_add_f32 v[102:103], v[102:103], v[44:45]
	v_lshlrev_b32_e32 v88, 16, v42
	v_and_b32_e32 v89, 0xffff0000, v42
	v_pk_add_f32 v[80:81], v[102:103], v[80:81]
	v_lshlrev_b32_e32 v92, 16, v38
	v_pk_add_f32 v[80:81], v[80:81], v[88:89]
	v_lshlrev_b32_e32 v88, 16, v104
	v_and_b32_e32 v89, 0xffff0000, v104
	v_mul_f32_e32 v14, 0xbfb8aa3b, v88
	v_exp_f32_e32 v14, v14
	v_mul_f32_e32 v18, 0xbfb8aa3b, v89
	v_and_b32_e32 v93, 0xffff0000, v38
	v_exp_f32_e32 v18, v18
	v_lshlrev_b32_e32 v98, 16, v46
	v_and_b32_e32 v99, 0xffff0000, v46
	v_pk_add_f32 v[80:81], v[80:81], v[92:93]
	v_add_f32_e32 v14, 1.0, v14
	v_pk_add_f32 v[80:81], v[80:81], v[98:99]
	v_rcp_f32_e32 v92, v14
	v_pk_add_f32 v[80:81], v[80:81], v[170:171]
	v_add_f32_e32 v14, 1.0, v18
	v_pk_add_f32 v[80:81], v[80:81], v[166:167]
	v_lshlrev_b32_e32 v68, 16, v74
	v_and_b32_e32 v69, 0xffff0000, v74
	v_rcp_f32_e32 v93, v14
	v_pk_add_f32 v[80:81], v[80:81], v[180:181]
	v_lshlrev_b32_e32 v76, 16, v62
	v_and_b32_e32 v77, 0xffff0000, v62
	v_pk_add_f32 v[68:69], v[80:81], v[68:69]
	v_pk_mul_f32 v[80:81], v[92:93], v[88:89]
	v_pk_add_f32 v[68:69], v[68:69], v[76:77]
	v_lshlrev_b32_e32 v84, 16, v78
	v_pk_fma_f32 v[76:77], v[152:153], v[68:69], v[76:77] op_sel_hi:[0,1,1] neg_lo:[0,0,1] neg_hi:[0,0,1]
	v_pk_mul_f32 v[76:77], v[0:1], v[76:77]
	v_and_b32_e32 v85, 0xffff0000, v78
	v_pk_mul_f32 v[76:77], v[76:77], v[80:81]
	v_pk_add_f32 v[64:65], v[68:69], v[64:65] neg_lo:[0,1] neg_hi:[0,1]
	v_cvt_pk_bf16_f32 v14, v76, v77
	v_lshlrev_b32_e32 v76, 16, v100
	v_and_b32_e32 v77, 0xffff0000, v100
	v_mul_f32_e32 v18, 0xbfb8aa3b, v76
	v_exp_f32_e32 v18, v18
	v_mul_f32_e32 v22, 0xbfb8aa3b, v77
	v_exp_f32_e32 v22, v22
	v_pk_add_f32 v[64:65], v[64:65], v[84:85]
	v_add_f32_e32 v18, 1.0, v18
	v_pk_fma_f32 v[68:69], v[154:155], v[64:65], v[84:85] op_sel_hi:[0,1,1] neg_lo:[0,0,1] neg_hi:[0,0,1]
	v_pk_mul_f32 v[68:69], v[0:1], v[68:69]
	v_pk_add_f32 v[64:65], v[64:65], v[164:165] neg_lo:[0,1] neg_hi:[0,1]
	v_pk_mul_f32 v[68:69], v[68:69], v[72:73]
	v_rcp_f32_e32 v72, v18
	v_add_f32_e32 v18, 1.0, v22
	v_rcp_f32_e32 v73, v18
	v_pk_add_f32 v[64:65], v[64:65], v[182:183]
	v_cvt_pk_bf16_f32 v18, v68, v69
	v_lshlrev_b32_e32 v116, 16, v117
	v_pk_mul_f32 v[68:69], v[72:73], v[76:77]
	v_pk_fma_f32 v[72:73], v[160:161], v[64:65], v[182:183] op_sel_hi:[0,1,1] neg_lo:[0,0,1] neg_hi:[0,0,1]
	v_pk_mul_f32 v[72:73], v[0:1], v[72:73]
	v_pk_add_f32 v[64:65], v[64:65], v[162:163] neg_lo:[0,1] neg_hi:[0,1]
	v_pk_mul_f32 v[68:69], v[72:73], v[68:69]
	v_lshlrev_b32_e32 v72, 16, v94
	v_and_b32_e32 v73, 0xffff0000, v94
	v_mul_f32_e32 v22, 0xbfb8aa3b, v72
	v_exp_f32_e32 v26, v22
	v_mul_f32_e32 v22, 0xbfb8aa3b, v73
	v_exp_f32_e32 v30, v22
	v_cvt_pk_bf16_f32 v22, v68, v69
	v_add_f32_e32 v26, 1.0, v26
	v_rcp_f32_e32 v68, v26
	v_add_f32_e32 v26, 1.0, v30
	v_rcp_f32_e32 v69, v26
	v_lshlrev_b32_e32 v76, 16, v66
	v_and_b32_e32 v77, 0xffff0000, v66
	v_pk_add_f32 v[64:65], v[64:65], v[76:77]
	v_pk_mul_f32 v[68:69], v[68:69], v[72:73]
	v_pk_fma_f32 v[72:73], v[158:159], v[64:65], v[76:77] op_sel_hi:[0,1,1] neg_lo:[0,0,1] neg_hi:[0,0,1]
	v_pk_add_f32 v[48:49], v[64:65], v[48:49] neg_lo:[0,1] neg_hi:[0,1]
	v_lshlrev_b32_e32 v64, 16, v90
	v_and_b32_e32 v65, 0xffff0000, v90
	v_mul_f32_e32 v26, 0xbfb8aa3b, v64
	v_exp_f32_e32 v30, v26
	v_mul_f32_e32 v26, 0xbfb8aa3b, v65
	v_exp_f32_e32 v34, v26
	v_pk_mul_f32 v[72:73], v[0:1], v[72:73]
	v_add_f32_e32 v30, 1.0, v30
	v_pk_mul_f32 v[68:69], v[72:73], v[68:69]
	v_lshlrev_b32_e32 v72, 16, v50
	v_cvt_pk_bf16_f32 v26, v68, v69
	v_rcp_f32_e32 v68, v30
	v_add_f32_e32 v30, 1.0, v34
	v_rcp_f32_e32 v69, v30
	v_and_b32_e32 v73, 0xffff0000, v50
	v_pk_add_f32 v[48:49], v[48:49], v[72:73]
	v_lshlrev_b32_e32 v76, 16, v109
	v_pk_mul_f32 v[64:65], v[68:69], v[64:65]
	v_pk_fma_f32 v[68:69], v[156:157], v[48:49], v[72:73] op_sel_hi:[0,1,1] neg_lo:[0,0,1] neg_hi:[0,0,1]
	v_pk_add_f32 v[48:49], v[48:49], v[56:57] neg_lo:[0,1] neg_hi:[0,1]
	v_lshlrev_b32_e32 v56, 16, v86
	v_and_b32_e32 v57, 0xffff0000, v86
	v_mul_f32_e32 v30, 0xbfb8aa3b, v56
	v_exp_f32_e32 v34, v30
	v_mul_f32_e32 v30, 0xbfb8aa3b, v57
	v_exp_f32_e32 v38, v30
	v_pk_mul_f32 v[68:69], v[0:1], v[68:69]
	v_add_f32_e32 v34, 1.0, v34
	v_pk_mul_f32 v[64:65], v[68:69], v[64:65]
	v_lshlrev_b32_e32 v68, 16, v70
	v_cvt_pk_bf16_f32 v30, v64, v65
	v_rcp_f32_e32 v64, v34
	v_add_f32_e32 v34, 1.0, v38
	v_rcp_f32_e32 v65, v34
	v_and_b32_e32 v69, 0xffff0000, v70
	v_pk_add_f32 v[48:49], v[48:49], v[68:69]
	v_lshlrev_b32_e32 v72, 16, v15
	v_pk_mul_f32 v[56:57], v[64:65], v[56:57]
	v_pk_fma_f32 v[64:65], v[132:133], v[48:49], v[68:69] op_sel_hi:[0,1,1] neg_lo:[0,0,1] neg_hi:[0,0,1]
	v_pk_add_f32 v[48:49], v[48:49], v[60:61] neg_lo:[0,1] neg_hi:[0,1]
	v_lshlrev_b32_e32 v60, 16, v82
	v_and_b32_e32 v61, 0xffff0000, v82
	v_mul_f32_e32 v34, 0xbfb8aa3b, v60
	v_exp_f32_e32 v38, v34
	v_mul_f32_e32 v34, 0xbfb8aa3b, v61
	v_exp_f32_e32 v42, v34
	v_pk_mul_f32 v[64:65], v[0:1], v[64:65]
	v_add_f32_e32 v38, 1.0, v38
	v_pk_mul_f32 v[56:57], v[64:65], v[56:57]
	v_lshlrev_b32_e32 v64, 16, v58
	v_cvt_pk_bf16_f32 v34, v56, v57
	v_rcp_f32_e32 v56, v38
	v_add_f32_e32 v38, 1.0, v42
	v_rcp_f32_e32 v57, v38
	v_and_b32_e32 v65, 0xffff0000, v58
	v_and_b32_e32 v73, 0xffff0000, v15
	v_and_b32_e32 v77, 0xffff0000, v109
	v_mul_f32_e32 v15, 0xbfb8aa3b, v76
	v_pk_add_f32 v[68:69], v[48:49], v[64:65]
	v_pk_mul_f32 v[48:49], v[56:57], v[60:61]
	v_lshlrev_b32_e32 v60, 16, v19
	v_and_b32_e32 v61, 0xffff0000, v19
	v_exp_f32_e32 v15, v15
	v_mul_f32_e32 v19, 0xbfb8aa3b, v77
	v_exp_f32_e32 v19, v19
	v_pk_add_f32 v[84:85], v[72:73], 0 op_sel_hi:[1,0]
	v_add_f32_e32 v15, 1.0, v15
	v_and_b32_e32 v117, 0xffff0000, v117
	v_rcp_f32_e32 v80, v15
	v_add_f32_e32 v15, 1.0, v19
	v_pk_add_f32 v[84:85], v[84:85], v[146:147]
	v_rcp_f32_e32 v81, v15
	v_pk_add_f32 v[84:85], v[84:85], v[116:117]
	v_pk_fma_f32 v[56:57], v[128:129], v[68:69], v[64:65] op_sel_hi:[0,1,1] neg_lo:[0,0,1] neg_hi:[0,0,1]
	v_lshlrev_b32_e32 v64, 16, v27
	v_and_b32_e32 v65, 0xffff0000, v27
	v_pk_add_f32 v[84:85], v[84:85], v[60:61]
	v_pk_mul_f32 v[56:57], v[0:1], v[56:57]
	v_pk_add_f32 v[44:45], v[68:69], v[44:45] neg_lo:[0,1] neg_hi:[0,1]
	v_lshlrev_b32_e32 v68, 16, v23
	v_and_b32_e32 v69, 0xffff0000, v23
	v_pk_add_f32 v[84:85], v[84:85], v[64:65]
	v_pk_mul_f32 v[48:49], v[56:57], v[48:49]
	v_lshlrev_b32_e32 v56, 16, v35
	v_and_b32_e32 v57, 0xffff0000, v35
	v_pk_add_f32 v[84:85], v[84:85], v[68:69]
	v_pk_mul_f32 v[76:77], v[80:81], v[76:77]
	v_lshlrev_b32_e32 v80, 16, v31
	v_and_b32_e32 v81, 0xffff0000, v31
	v_pk_add_f32 v[84:85], v[84:85], v[56:57]
	v_lshlrev_b32_e32 v42, 16, v43
	v_and_b32_e32 v43, 0xffff0000, v43
	v_pk_add_f32 v[80:81], v[84:85], v[80:81]
	v_lshlrev_b32_e32 v38, 16, v39
	v_and_b32_e32 v39, 0xffff0000, v39
	v_pk_add_f32 v[42:43], v[80:81], v[42:43]
	v_lshlrev_b32_e32 v46, 16, v47
	v_pk_add_f32 v[38:39], v[42:43], v[38:39]
	v_lshlrev_b32_e32 v42, 16, v105
	v_and_b32_e32 v43, 0xffff0000, v105
	v_mul_f32_e32 v15, 0xbfb8aa3b, v42
	v_exp_f32_e32 v15, v15
	v_mul_f32_e32 v19, 0xbfb8aa3b, v43
	v_exp_f32_e32 v19, v19
	v_and_b32_e32 v47, 0xffff0000, v47
	v_pk_add_f32 v[38:39], v[38:39], v[46:47]
	v_add_f32_e32 v15, 1.0, v15
	v_pk_add_f32 v[38:39], v[38:39], v[148:149]
	v_rcp_f32_e32 v46, v15
	v_add_f32_e32 v15, 1.0, v19
	v_pk_add_f32 v[38:39], v[38:39], v[126:127]
	v_rcp_f32_e32 v47, v15
	v_lshlrev_b32_e32 v74, 16, v75
	v_and_b32_e32 v75, 0xffff0000, v75
	v_pk_add_f32 v[38:39], v[38:39], v[150:151]
	v_lshlrev_b32_e32 v62, 16, v63
	v_and_b32_e32 v63, 0xffff0000, v63
	v_pk_add_f32 v[38:39], v[38:39], v[74:75]
	v_pk_mul_f32 v[42:43], v[46:47], v[42:43]
	v_pk_add_f32 v[38:39], v[38:39], v[62:63]
	v_lshlrev_b32_e32 v78, 16, v79
	v_pk_fma_f32 v[46:47], v[152:153], v[38:39], v[62:63] op_sel_hi:[0,1,1] neg_lo:[0,0,1] neg_hi:[0,0,1]
	v_pk_mul_f32 v[46:47], v[2:3], v[46:47]
	v_and_b32_e32 v79, 0xffff0000, v79
	v_pk_mul_f32 v[42:43], v[46:47], v[42:43]
	v_lshlrev_b32_e32 v46, 16, v101
	v_and_b32_e32 v47, 0xffff0000, v101
	v_mul_f32_e32 v19, 0xbfb8aa3b, v46
	v_exp_f32_e32 v19, v19
	v_mul_f32_e32 v23, 0xbfb8aa3b, v47
	v_exp_f32_e32 v23, v23
	v_pk_add_f32 v[38:39], v[38:39], v[72:73] neg_lo:[0,1] neg_hi:[0,1]
	v_add_f32_e32 v19, 1.0, v19
	v_rcp_f32_e32 v62, v19
	v_add_f32_e32 v19, 1.0, v23
	v_pk_add_f32 v[38:39], v[38:39], v[78:79]
	v_rcp_f32_e32 v63, v19
	v_cvt_pk_bf16_f32 v15, v42, v43
	v_pk_fma_f32 v[42:43], v[154:155], v[38:39], v[78:79] op_sel_hi:[0,1,1] neg_lo:[0,0,1] neg_hi:[0,0,1]
	v_pk_mul_f32 v[42:43], v[2:3], v[42:43]
	v_pk_add_f32 v[38:39], v[38:39], v[146:147] neg_lo:[0,1] neg_hi:[0,1]
	v_pk_mul_f32 v[42:43], v[42:43], v[76:77]
	v_pk_add_f32 v[38:39], v[38:39], v[130:131]
	v_cvt_pk_bf16_f32 v19, v42, v43
	v_pk_mul_f32 v[42:43], v[62:63], v[46:47]
	v_pk_fma_f32 v[46:47], v[160:161], v[38:39], v[130:131] op_sel_hi:[0,1,1] neg_lo:[0,0,1] neg_hi:[0,0,1]
	v_pk_mul_f32 v[46:47], v[2:3], v[46:47]
	v_pk_add_f32 v[38:39], v[38:39], v[116:117] neg_lo:[0,1] neg_hi:[0,1]
	v_pk_mul_f32 v[42:43], v[46:47], v[42:43]
	v_lshlrev_b32_e32 v46, 16, v95
	v_and_b32_e32 v47, 0xffff0000, v95
	v_mul_f32_e32 v23, 0xbfb8aa3b, v46
	v_exp_f32_e32 v27, v23
	v_mul_f32_e32 v23, 0xbfb8aa3b, v47
	v_exp_f32_e32 v31, v23
	v_cvt_pk_bf16_f32 v23, v42, v43
	v_add_f32_e32 v27, 1.0, v27
	v_rcp_f32_e32 v42, v27
	v_add_f32_e32 v27, 1.0, v31
	v_rcp_f32_e32 v43, v27
	v_lshlrev_b32_e32 v62, 16, v67
	v_and_b32_e32 v63, 0xffff0000, v67
	v_pk_add_f32 v[38:39], v[38:39], v[62:63]
	v_pk_mul_f32 v[42:43], v[42:43], v[46:47]
	v_pk_fma_f32 v[46:47], v[158:159], v[38:39], v[62:63] op_sel_hi:[0,1,1] neg_lo:[0,0,1] neg_hi:[0,0,1]
	v_pk_mul_f32 v[46:47], v[2:3], v[46:47]
	v_pk_add_f32 v[38:39], v[38:39], v[60:61] neg_lo:[0,1] neg_hi:[0,1]
	v_pk_mul_f32 v[42:43], v[46:47], v[42:43]
	v_lshlrev_b32_e32 v46, 16, v91
	v_and_b32_e32 v47, 0xffff0000, v91
	v_mul_f32_e32 v27, 0xbfb8aa3b, v46
	v_exp_f32_e32 v31, v27
	v_mul_f32_e32 v27, 0xbfb8aa3b, v47
	v_exp_f32_e32 v35, v27
	v_cvt_pk_bf16_f32 v27, v42, v43
	v_add_f32_e32 v31, 1.0, v31
	v_rcp_f32_e32 v42, v31
	v_add_f32_e32 v31, 1.0, v35
	v_rcp_f32_e32 v43, v31
	v_lshlrev_b32_e32 v50, 16, v51
	v_and_b32_e32 v51, 0xffff0000, v51
	v_pk_add_f32 v[38:39], v[38:39], v[50:51]
	v_pk_mul_f32 v[42:43], v[42:43], v[46:47]
	v_pk_fma_f32 v[46:47], v[156:157], v[38:39], v[50:51] op_sel_hi:[0,1,1] neg_lo:[0,0,1] neg_hi:[0,0,1]
	v_pk_mul_f32 v[46:47], v[2:3], v[46:47]
	v_lshlrev_b64 v[114:115], 11, v[114:115]
	v_pk_mul_f32 v[42:43], v[46:47], v[42:43]
	v_lshlrev_b32_e32 v46, 16, v87
	v_and_b32_e32 v47, 0xffff0000, v87
	v_mul_f32_e32 v31, 0xbfb8aa3b, v46
	v_exp_f32_e32 v35, v31
	v_mul_f32_e32 v31, 0xbfb8aa3b, v47
	v_exp_f32_e32 v50, v31
	v_lshl_add_u64 v[114:115], v[138:139], 0, v[114:115]
	v_add_f32_e32 v35, 1.0, v35
	global_store_dwordx4 v[112:113], v[12:15], off
	global_store_dwordx4 v[114:115], v[16:19], off
	global_store_dwordx4 v[120:121], v[20:23], off
	v_lshlrev_b32_e32 v12, 16, v83
	v_and_b32_e32 v13, 0xffff0000, v83
	v_cvt_pk_bf16_f32 v31, v42, v43
	v_rcp_f32_e32 v42, v35
	v_add_f32_e32 v35, 1.0, v50
	v_mul_f32_e32 v14, 0xbfb8aa3b, v12
	v_mul_f32_e32 v15, 0xbfb8aa3b, v13
	v_rcp_f32_e32 v43, v35
	v_exp_f32_e32 v14, v14
	v_exp_f32_e32 v15, v15
	v_pk_add_f32 v[38:39], v[38:39], v[64:65] neg_lo:[0,1] neg_hi:[0,1]
	v_lshlrev_b32_e32 v50, 16, v71
	v_and_b32_e32 v51, 0xffff0000, v71
	v_pk_add_f32 v[38:39], v[38:39], v[50:51]
	v_pk_mul_f32 v[42:43], v[42:43], v[46:47]
	v_pk_fma_f32 v[46:47], v[132:133], v[38:39], v[50:51] op_sel_hi:[0,1,1] neg_lo:[0,0,1] neg_hi:[0,0,1]
	v_add_f32_e32 v14, 1.0, v14
	v_add_f32_e32 v15, 1.0, v15
	v_pk_mul_f32 v[46:47], v[2:3], v[46:47]
	v_rcp_f32_e32 v14, v14
	v_rcp_f32_e32 v15, v15
	v_pk_mul_f32 v[42:43], v[46:47], v[42:43]
	v_pk_add_f32 v[38:39], v[38:39], v[68:69] neg_lo:[0,1] neg_hi:[0,1]
	v_cvt_pk_bf16_f32 v35, v42, v43
	v_lshlrev_b32_e32 v42, 16, v59
	v_and_b32_e32 v43, 0xffff0000, v59
	v_pk_add_f32 v[16:17], v[38:39], v[42:43]
	v_pk_mul_f32 v[12:13], v[14:15], v[12:13]
	v_pk_fma_f32 v[14:15], v[128:129], v[16:17], v[42:43] op_sel_hi:[0,1,1] neg_lo:[0,0,1] neg_hi:[0,0,1]
	v_ashrrev_i32_e32 v145, 31, v144
	v_pk_mul_f32 v[14:15], v[2:3], v[14:15]
	v_pk_add_f32 v[18:19], v[16:17], v[56:57] neg_lo:[0,1] neg_hi:[0,1]
	v_lshl_add_u64 v[16:17], s[28:29], 0, v[144:145]
	v_lshlrev_b64 v[118:119], 11, v[118:119]
	v_lshlrev_b64 v[122:123], 11, v[122:123]
	v_pk_mul_f32 v[20:21], v[14:15], v[12:13]
	v_lshlrev_b64 v[16:17], 11, v[16:17]
	v_lshl_add_u64 v[118:119], v[138:139], 0, v[118:119]
	v_lshl_add_u64 v[122:123], v[138:139], 0, v[122:123]
	v_lshlrev_b64 v[124:125], 11, v[124:125]
	v_cvt_pk_bf16_f32 v12, v168, v169
	v_cvt_pk_bf16_f32 v13, v40, v41
	v_cvt_pk_bf16_f32 v14, v48, v49
	v_cvt_pk_bf16_f32 v15, v20, v21
	v_lshl_add_u64 v[16:17], v[138:139], 0, v[16:17]
	v_lshl_add_u64 v[124:125], v[138:139], 0, v[124:125]
	global_store_dwordx4 v[118:119], v[24:27], off
	global_store_dwordx4 v[122:123], v[28:31], off
	global_store_dwordx4 v[124:125], v[32:35], off
	global_store_dwordx4 v[16:17], v[12:15], off
	s_waitcnt vmcnt(7)
	v_lshlrev_b32_e32 v20, 16, v52
	v_and_b32_e32 v21, 0xffff0000, v52
	v_lshlrev_b32_e32 v14, 16, v53
	v_and_b32_e32 v15, 0xffff0000, v53
	v_mul_f32_e32 v16, 0xbfb8aa3b, v14
	v_mul_f32_e32 v22, 0xbfb8aa3b, v20
	v_exp_f32_e32 v16, v16
	v_mul_f32_e32 v17, 0xbfb8aa3b, v15
	v_exp_f32_e32 v22, v22
	v_mul_f32_e32 v23, 0xbfb8aa3b, v21
	v_exp_f32_e32 v17, v17
	v_exp_f32_e32 v23, v23
	v_add_f32_e32 v16, 1.0, v16
	v_lshlrev_b32_e32 v24, 16, v54
	v_add_f32_e32 v12, 1.0, v22
	v_rcp_f32_e32 v22, v16
	v_add_f32_e32 v16, 1.0, v17
	v_and_b32_e32 v25, 0xffff0000, v54
	v_mul_f32_e32 v17, 0xbfb8aa3b, v24
	v_add_f32_e32 v13, 1.0, v23
	v_exp_f32_e32 v17, v17
	v_mul_f32_e32 v23, 0xbfb8aa3b, v25
	v_exp_f32_e32 v27, v23
	v_lshlrev_b32_e32 v28, 16, v55
	v_rcp_f32_e32 v23, v16
	v_add_f32_e32 v16, 1.0, v17
	v_and_b32_e32 v29, 0xffff0000, v55
	v_mul_f32_e32 v17, 0xbfb8aa3b, v28
	v_rcp_f32_e32 v26, v16
	v_add_f32_e32 v16, 1.0, v27
	v_exp_f32_e32 v17, v17
	v_mul_f32_e32 v27, 0xbfb8aa3b, v29
	v_exp_f32_e32 v31, v27
	v_rcp_f32_e32 v27, v16
	v_add_f32_e32 v16, 1.0, v17
	v_rcp_f32_e32 v30, v16
	v_add_f32_e32 v16, 1.0, v31
	v_rcp_f32_e32 v12, v12
	v_rcp_f32_e32 v13, v13
	v_rcp_f32_e32 v31, v16
	v_pk_add_f32 v[36:37], v[36:37], v[196:197] neg_lo:[0,1] neg_hi:[0,1]
	s_mov_b64 s[2:3], 0
	v_pk_mul_f32 v[16:17], v[12:13], v[20:21]
	v_pk_mul_f32 v[12:13], v[22:23], v[14:15]
	v_pk_mul_f32 v[20:21], v[26:27], v[24:25]
	v_pk_mul_f32 v[14:15], v[30:31], v[28:29]
	v_min_i32_e32 v22, 15, v140
.LBB0_161:
	s_and_b64 vcc, exec, s[2:3]
	s_cbranch_vccz .LBB0_193
	v_cmp_lt_i32_e32 vcc, 6, v142
	v_mov_b32_e32 v12, 0
	v_mov_b32_e32 v16, 0
	v_mov_b32_e32 v17, 0
	v_mov_b32_e32 v18, 0
	v_mov_b32_e32 v19, 0
	s_and_saveexec_b64 s[2:3], vcc
	s_cbranch_execz .LBB0_164
	v_add_u32_e32 v8, -7, v142
	v_mov_b32_e32 v9, v97
	v_lshl_add_u64 v[8:9], s[28:29], 0, v[8:9]
	v_lshlrev_b64 v[8:9], 11, v[8:9]
	v_lshl_add_u64 v[8:9], v[134:135], 0, v[8:9]
	global_load_dwordx4 v[16:19], v[8:9], off nt
.LBB0_164:
	s_or_b64 exec, exec, s[2:3]
	v_cmp_lt_i32_e32 vcc, 5, v142
	v_mov_b32_e32 v13, 0
	v_mov_b32_e32 v14, 0
	v_mov_b32_e32 v15, 0
	s_and_saveexec_b64 s[2:3], vcc
	s_cbranch_execz .LBB0_166
	v_add_u32_e32 v8, -6, v142
	v_mov_b32_e32 v9, v97
	v_lshl_add_u64 v[8:9], s[28:29], 0, v[8:9]
	v_lshlrev_b64 v[8:9], 11, v[8:9]
	v_lshl_add_u64 v[8:9], v[134:135], 0, v[8:9]
	global_load_dwordx4 v[12:15], v[8:9], off nt
.LBB0_166:
	s_or_b64 exec, exec, s[2:3]
	v_cmp_lt_i32_e32 vcc, 4, v142
	v_mov_b32_e32 v20, 0
	v_mov_b32_e32 v92, 0
	v_mov_b32_e32 v93, 0
	v_mov_b32_e32 v94, 0
	v_mov_b32_e32 v95, 0
	s_and_saveexec_b64 s[2:3], vcc
	s_cbranch_execz .LBB0_168
	v_add_u32_e32 v8, -5, v142
	v_mov_b32_e32 v9, v97
	v_lshl_add_u64 v[8:9], s[28:29], 0, v[8:9]
	v_lshlrev_b64 v[8:9], 11, v[8:9]
	v_lshl_add_u64 v[8:9], v[134:135], 0, v[8:9]
	global_load_dwordx4 v[92:95], v[8:9], off nt
.LBB0_168:
	s_or_b64 exec, exec, s[2:3]
	v_cmp_lt_i32_e32 vcc, 3, v142
	v_mov_b32_e32 v21, 0
	v_mov_b32_e32 v22, 0
	v_mov_b32_e32 v23, 0
	s_and_saveexec_b64 s[2:3], vcc
	s_cbranch_execz .LBB0_170
	v_add_u32_e32 v8, -4, v142
	v_mov_b32_e32 v9, v97
	v_lshl_add_u64 v[8:9], s[28:29], 0, v[8:9]
	v_lshlrev_b64 v[8:9], 11, v[8:9]
	v_lshl_add_u64 v[8:9], v[134:135], 0, v[8:9]
	global_load_dwordx4 v[20:23], v[8:9], off nt
.LBB0_170:
	s_or_b64 exec, exec, s[2:3]
	v_cmp_lt_i32_e32 vcc, 2, v142
	v_mov_b32_e32 v24, 0
	v_mov_b32_e32 v28, 0
	v_mov_b32_e32 v29, 0
	v_mov_b32_e32 v30, 0
	v_mov_b32_e32 v31, 0
	s_and_saveexec_b64 s[2:3], vcc
	s_cbranch_execz .LBB0_172
	v_add_u32_e32 v8, -3, v142
	v_mov_b32_e32 v9, v97
	v_lshl_add_u64 v[8:9], s[28:29], 0, v[8:9]
	v_lshlrev_b64 v[8:9], 11, v[8:9]
	v_lshl_add_u64 v[8:9], v[134:135], 0, v[8:9]
	global_load_dwordx4 v[28:31], v[8:9], off nt
.LBB0_172:
	s_or_b64 exec, exec, s[2:3]
	v_cmp_lt_i32_e32 vcc, 1, v142
	v_mov_b32_e32 v25, 0
	v_mov_b32_e32 v26, 0
	v_mov_b32_e32 v27, 0
	s_and_saveexec_b64 s[2:3], vcc
	s_cbranch_execz .LBB0_174
	v_add_u32_e32 v8, -2, v142
	v_mov_b32_e32 v9, v97
	v_lshl_add_u64 v[8:9], s[28:29], 0, v[8:9]
	v_lshlrev_b64 v[8:9], 11, v[8:9]
	v_lshl_add_u64 v[8:9], v[134:135], 0, v[8:9]
	global_load_dwordx4 v[24:27], v[8:9], off nt
.LBB0_174:
	s_or_b64 exec, exec, s[2:3]
	v_mov_b32_e32 v36, 0
	v_cmp_lt_i32_e32 vcc, 0, v142
	v_mov_b32_e32 v52, 0
	v_mov_b32_e32 v53, 0
	v_mov_b32_e32 v54, 0
	v_mov_b32_e32 v55, 0
	s_and_saveexec_b64 s[2:3], vcc
	s_cbranch_execz .LBB0_176
	v_add_u32_e32 v8, -1, v142
	v_mov_b32_e32 v9, v97
	v_lshl_add_u64 v[8:9], s[28:29], 0, v[8:9]
	v_lshlrev_b64 v[8:9], 11, v[8:9]
	v_lshl_add_u64 v[8:9], v[134:135], 0, v[8:9]
	global_load_dwordx4 v[52:55], v[8:9], off nt
.LBB0_176:
	s_or_b64 exec, exec, s[2:3]
	v_cmp_lt_i32_e32 vcc, -1, v142
	v_mov_b32_e32 v37, 0
	v_mov_b32_e32 v38, 0
	v_mov_b32_e32 v39, 0
	s_and_saveexec_b64 s[2:3], vcc
	s_cbranch_execz .LBB0_178
	v_mov_b32_e32 v143, v97
	v_lshl_add_u64 v[8:9], s[28:29], 0, v[142:143]
	v_lshlrev_b64 v[8:9], 11, v[8:9]
	v_lshl_add_u64 v[8:9], v[134:135], 0, v[8:9]
	global_load_dwordx4 v[36:39], v[8:9], off nt
.LBB0_178:
	s_or_b64 exec, exec, s[2:3]
	v_or_b32_e32 v116, 1, v142
	v_cmp_lt_i32_e32 vcc, -2, v142
	v_mov_b32_e32 v98, 0
	v_mov_b32_e32 v60, 0
	v_mov_b32_e32 v61, 0
	v_mov_b32_e32 v62, 0
	v_mov_b32_e32 v63, 0
	s_and_saveexec_b64 s[2:3], vcc
	s_cbranch_execz .LBB0_180
	v_mov_b32_e32 v117, v97
	v_lshl_add_u64 v[8:9], s[28:29], 0, v[116:117]
	v_lshlrev_b64 v[8:9], 11, v[8:9]
	v_lshl_add_u64 v[8:9], v[134:135], 0, v[8:9]
	global_load_dwordx4 v[60:63], v[8:9], off nt
.LBB0_180:
	s_or_b64 exec, exec, s[2:3]
	v_or_b32_e32 v104, 2, v142
	v_cmp_lt_i32_e32 vcc, -3, v142
	v_mov_b32_e32 v99, 0
	v_mov_b32_e32 v100, 0
	v_mov_b32_e32 v101, 0
	s_and_saveexec_b64 s[2:3], vcc
	s_cbranch_execz .LBB0_182
	v_mov_b32_e32 v105, v97
	v_lshl_add_u64 v[8:9], s[28:29], 0, v[104:105]
	v_lshlrev_b64 v[8:9], 11, v[8:9]
	v_lshl_add_u64 v[8:9], v[134:135], 0, v[8:9]
	global_load_dwordx4 v[98:101], v[8:9], off nt
.LBB0_182:
	s_or_b64 exec, exec, s[2:3]
	v_or_b32_e32 v108, 3, v142
	v_cmp_lt_i32_e32 vcc, -4, v142
	v_mov_b32_e32 v32, 0
	v_mov_b32_e32 v48, 0
	v_mov_b32_e32 v49, 0
	v_mov_b32_e32 v50, 0
	v_mov_b32_e32 v51, 0
	s_and_saveexec_b64 s[2:3], vcc
	s_cbranch_execz .LBB0_184
	v_mov_b32_e32 v109, v97
	v_lshl_add_u64 v[8:9], s[28:29], 0, v[108:109]
	v_lshlrev_b64 v[8:9], 11, v[8:9]
	v_lshl_add_u64 v[8:9], v[134:135], 0, v[8:9]
	global_load_dwordx4 v[48:51], v[8:9], off nt
.LBB0_184:
	s_or_b64 exec, exec, s[2:3]
	v_or_b32_e32 v112, 4, v142
	v_cmp_lt_i32_e32 vcc, -5, v142
	v_mov_b32_e32 v33, 0
	v_mov_b32_e32 v34, 0
	v_mov_b32_e32 v35, 0
	s_and_saveexec_b64 s[2:3], vcc
	s_cbranch_execz .LBB0_186
	v_mov_b32_e32 v113, v97
	v_lshl_add_u64 v[8:9], s[28:29], 0, v[112:113]
	v_lshlrev_b64 v[8:9], 11, v[8:9]
	v_lshl_add_u64 v[8:9], v[134:135], 0, v[8:9]
	global_load_dwordx4 v[32:35], v[8:9], off nt
.LBB0_186:
	s_or_b64 exec, exec, s[2:3]
	v_or_b32_e32 v130, 5, v142
	v_cmp_lt_i32_e32 vcc, -6, v142
	v_mov_b32_e32 v44, 0
	v_mov_b32_e32 v56, 0
	v_mov_b32_e32 v57, 0
	v_mov_b32_e32 v58, 0
	v_mov_b32_e32 v59, 0
	s_and_saveexec_b64 s[2:3], vcc
	s_cbranch_execz .LBB0_188
	v_mov_b32_e32 v131, v97
	v_lshl_add_u64 v[8:9], s[28:29], 0, v[130:131]
	v_lshlrev_b64 v[8:9], 11, v[8:9]
	v_lshl_add_u64 v[8:9], v[134:135], 0, v[8:9]
	global_load_dwordx4 v[56:59], v[8:9], off nt
.LBB0_188:
	s_or_b64 exec, exec, s[2:3]
	v_or_b32_e32 v102, 6, v142
	v_cmp_lt_i32_e32 vcc, -7, v142
	v_mov_b32_e32 v45, 0
	v_mov_b32_e32 v46, 0
	v_mov_b32_e32 v47, 0
	s_and_saveexec_b64 s[2:3], vcc
	s_cbranch_execz .LBB0_190
	v_mov_b32_e32 v103, v97
	v_lshl_add_u64 v[8:9], s[28:29], 0, v[102:103]
	v_lshlrev_b64 v[8:9], 11, v[8:9]
	v_lshl_add_u64 v[8:9], v[134:135], 0, v[8:9]
	global_load_dwordx4 v[44:47], v[8:9], off nt

.LBB0_192:
	s_or_b64 exec, exec, s[2:3]
	s_waitcnt vmcnt(0)
	v_lshlrev_b32_e32 v110, 16, v92
	v_and_b32_e32 v111, 0xffff0000, v92
	v_min_i32_e32 v92, 7, v142
	v_add_u32_e32 v92, 1, v92
	v_ashrrev_i32_e32 v143, 31, v142
	v_cvt_f32_i32_e32 v92, v92
	v_lshl_add_u64 v[40:41], s[28:29], 0, v[142:143]
	v_lshlrev_b64 v[118:119], 11, v[40:41]
	v_lshl_add_u64 v[40:41], v[136:137], 0, v[118:119]
	v_add_co_u32_e32 v42, vcc, s53, v40
	v_lshlrev_b32_e32 v144, 16, v93
	v_and_b32_e32 v145, 0xffff0000, v93
	v_div_scale_f32 v93, s[2:3], v92, v92, 1.0
	global_load_dwordx4 v[84:87], v[40:41], off nt
	global_load_dwordx4 v[88:91], v[40:41], off offset:2048 nt
	v_addc_co_u32_e32 v43, vcc, 0, v41, vcc
	v_rcp_f32_e32 v103, v93
	v_add_co_u32_e32 v80, vcc, s58, v40
	v_min_i32_e32 v109, 7, v116
	s_nop 0
	v_addc_co_u32_e32 v81, vcc, 0, v41, vcc
	v_add_co_u32_e32 v40, vcc, s64, v40
	v_lshlrev_b32_e32 v128, 16, v94
	s_nop 0
	v_addc_co_u32_e32 v41, vcc, 0, v41, vcc
	v_and_b32_e32 v129, 0xffff0000, v94
	v_fma_f32 v94, -v93, v103, 1.0
	v_add_u32_e32 v109, 1, v109
	v_fmac_f32_e32 v103, v94, v103
	v_div_scale_f32 v94, vcc, 1.0, v92, 1.0
	v_cvt_f32_i32_e32 v109, v109
	v_lshlrev_b32_e32 v106, 16, v95
	v_and_b32_e32 v107, 0xffff0000, v95
	v_mul_f32_e32 v95, v94, v103
	v_fma_f32 v105, -v93, v95, v94
	v_fmac_f32_e32 v95, v105, v103
	v_fma_f32 v93, -v93, v95, v94
	v_div_scale_f32 v94, s[2:3], v109, v109, 1.0
	v_rcp_f32_e32 v105, v94
	v_lshlrev_b32_e32 v148, 16, v98
	v_and_b32_e32 v149, 0xffff0000, v98
	v_min_i32_e32 v98, 7, v104
	v_div_fmas_f32 v93, v93, v103, v95
	v_fma_f32 v95, -v94, v105, 1.0
	v_add_u32_e32 v98, 1, v98
	v_fmac_f32_e32 v105, v95, v105
	v_div_scale_f32 v95, vcc, 1.0, v109, 1.0
	v_cvt_f32_i32_e32 v98, v98
	v_mul_f32_e32 v103, v95, v105
	v_fma_f32 v113, -v94, v103, v95
	v_fmac_f32_e32 v103, v113, v105
	v_fma_f32 v94, -v94, v103, v95
	v_lshlrev_b32_e32 v146, 16, v99
	v_and_b32_e32 v147, 0xffff0000, v99
	v_div_scale_f32 v99, s[2:3], v98, v98, 1.0
	v_div_fmas_f32 v94, v94, v105, v103
	v_rcp_f32_e32 v103, v99
	v_lshlrev_b32_e32 v132, 16, v100
	v_and_b32_e32 v133, 0xffff0000, v100
	v_ashrrev_i32_e32 v117, 31, v116
	v_fma_f32 v100, -v99, v103, 1.0
	v_fmac_f32_e32 v103, v100, v103
	v_div_scale_f32 v100, vcc, 1.0, v98, 1.0
	global_load_dwordx4 v[72:75], v[80:81], off nt
	global_load_dwordx4 v[68:71], v[80:81], off offset:2048 nt
	global_load_dwordx4 v[76:79], v[42:43], off offset:2048 nt
	global_load_dwordx4 v[64:67], v[40:41], off nt
	s_nop 0
	global_load_dwordx4 v[80:83], v[80:81], off offset:-4096 nt
	s_nop 0
	global_load_dwordx4 v[40:43], v[40:41], off offset:2048 nt
	v_div_fixup_f32 v114, v93, v92, 1.0
	v_lshl_add_u64 v[92:93], v[138:139], 0, v[118:119]
	v_div_fixup_f32 v118, v94, v109, 1.0
	v_lshl_add_u64 v[94:95], s[28:29], 0, v[116:117]
	v_lshlrev_b32_e32 v116, 16, v101
	v_and_b32_e32 v117, 0xffff0000, v101
	v_mul_f32_e32 v101, v100, v103
	v_fma_f32 v105, -v99, v101, v100
	v_fmac_f32_e32 v101, v105, v103
	v_fma_f32 v99, -v99, v101, v100
	v_min_i32_e32 v100, 7, v108
	v_add_u32_e32 v100, 1, v100
	v_div_fmas_f32 v99, v99, v103, v101
	v_cvt_f32_i32_e32 v103, v100
	v_ashrrev_i32_e32 v105, 31, v104
	v_div_fixup_f32 v126, v99, v98, 1.0
	v_lshl_add_u64 v[98:99], s[28:29], 0, v[104:105]
	v_div_scale_f32 v109, s[2:3], v103, v103, 1.0
	v_rcp_f32_e32 v113, v109
	v_lshlrev_b64 v[98:99], 11, v[98:99]
	v_lshl_add_u64 v[100:101], v[138:139], 0, v[98:99]
	s_waitcnt vmcnt(6)
	v_lshlrev_b32_e32 v164, 16, v88
	v_fma_f32 v98, -v109, v113, 1.0
	v_fmac_f32_e32 v113, v98, v113
	v_div_scale_f32 v98, vcc, 1.0, v103, 1.0
	v_mul_f32_e32 v99, v98, v113
	v_fma_f32 v104, -v109, v99, v98
	v_fmac_f32_e32 v99, v104, v113
	v_fma_f32 v98, -v109, v99, v98
	v_div_fmas_f32 v98, v98, v113, v99
	v_min_i32_e32 v99, 7, v112
	v_add_u32_e32 v99, 1, v99
	v_cvt_f32_i32_e32 v104, v99
	v_div_fixup_f32 v124, v98, v103, 1.0
	v_ashrrev_i32_e32 v109, 31, v108
	v_lshl_add_u64 v[98:99], s[28:29], 0, v[108:109]
	v_div_scale_f32 v103, s[2:3], v104, v104, 1.0
	v_rcp_f32_e32 v105, v103
	v_ashrrev_i32_e32 v131, 31, v130
	v_lshlrev_b32_e32 v162, 16, v16
	v_and_b32_e32 v163, 0xffff0000, v16
	v_fma_f32 v108, -v103, v105, 1.0
	v_fmac_f32_e32 v105, v108, v105
	v_div_scale_f32 v108, vcc, 1.0, v104, 1.0
	v_mul_f32_e32 v109, v108, v105
	v_fma_f32 v113, -v103, v109, v108
	v_fmac_f32_e32 v109, v113, v105
	v_fma_f32 v103, -v103, v109, v108
	v_div_fmas_f32 v103, v103, v105, v109
	v_min_i32_e32 v105, 7, v130
	v_add_u32_e32 v105, 1, v105
	v_cvt_f32_i32_e32 v108, v105
	v_div_fixup_f32 v122, v103, v104, 1.0
	v_ashrrev_i32_e32 v113, 31, v112
	v_lshl_add_u64 v[104:105], s[28:29], 0, v[112:113]
	v_div_scale_f32 v103, s[2:3], v108, v108, 1.0
	v_rcp_f32_e32 v109, v103
	v_and_b32_e32 v165, 0xffff0000, v88
	v_mul_f32_e32 v16, 0xbfb8aa3b, v164
	v_exp_f32_e32 v16, v16
	v_fma_f32 v112, -v103, v109, 1.0
	v_fmac_f32_e32 v109, v112, v109
	v_div_scale_f32 v112, vcc, 1.0, v108, 1.0
	v_mul_f32_e32 v113, v112, v109
	v_fma_f32 v115, -v103, v113, v112
	v_fmac_f32_e32 v113, v115, v109
	v_fma_f32 v103, -v103, v113, v112
	v_div_fmas_f32 v103, v103, v109, v113
	v_min_i32_e32 v109, 7, v102
	v_add_u32_e32 v109, 1, v109
	v_cvt_f32_i32_e32 v112, v109
	v_div_fixup_f32 v120, v103, v108, 1.0
	v_lshl_add_u64 v[108:109], s[28:29], 0, v[130:131]
	v_lshlrev_b32_e32 v130, 16, v20
	v_and_b32_e32 v131, 0xffff0000, v20
	v_mul_f32_e32 v20, 0xbfb8aa3b, v165
	v_exp_f32_e32 v20, v20
	v_add_f32_e32 v16, 1.0, v16
	v_rcp_f32_e32 v168, v16
	v_lshlrev_b32_e32 v182, 16, v84
	v_add_f32_e32 v16, 1.0, v20
	v_rcp_f32_e32 v169, v16
	v_and_b32_e32 v183, 0xffff0000, v84
	v_mul_f32_e32 v16, 0xbfb8aa3b, v183
	v_pk_add_f32 v[180:181], v[162:163], 0 op_sel_hi:[1,0]
	v_pk_mul_f32 v[164:165], v[168:169], v[164:165]
	v_lshlrev_b32_e32 v168, 16, v12
	v_and_b32_e32 v169, 0xffff0000, v12
	v_mul_f32_e32 v12, 0xbfb8aa3b, v182
	v_exp_f32_e32 v12, v12
	v_exp_f32_e32 v16, v16
	v_div_scale_f32 v103, s[2:3], v112, v112, 1.0
	v_pk_add_f32 v[180:181], v[180:181], v[168:169]
	v_rcp_f32_e32 v113, v103
	v_pk_add_f32 v[180:181], v[180:181], v[110:111]
	v_lshlrev_b32_e32 v150, 16, v28
	v_and_b32_e32 v151, 0xffff0000, v28
	v_pk_add_f32 v[180:181], v[180:181], v[130:131]
	v_add_f32_e32 v12, 1.0, v12
	v_lshlrev_b32_e32 v156, 16, v24
	v_and_b32_e32 v157, 0xffff0000, v24
	v_pk_add_f32 v[180:181], v[180:181], v[150:151]
	v_rcp_f32_e32 v184, v12
	v_add_f32_e32 v12, 1.0, v16
	v_lshlrev_b32_e32 v158, 16, v52
	v_and_b32_e32 v159, 0xffff0000, v52
	v_rcp_f32_e32 v185, v12
	v_pk_add_f32 v[180:181], v[180:181], v[156:157]
	v_fma_f32 v115, -v103, v113, 1.0
	v_lshlrev_b32_e32 v166, 16, v36
	v_and_b32_e32 v167, 0xffff0000, v36
	v_pk_add_f32 v[180:181], v[180:181], v[158:159]
	v_fmac_f32_e32 v113, v115, v113
	v_div_scale_f32 v115, vcc, 1.0, v112, 1.0
	v_pk_add_f32 v[180:181], v[180:181], v[166:167]
	v_mul_f32_e32 v119, v115, v113
	v_pk_fma_f32 v[166:167], v[114:115], v[180:181], v[166:167] op_sel_hi:[0,1,1] neg_lo:[0,0,1] neg_hi:[0,0,1]
	v_fma_f32 v121, -v103, v119, v115
	v_lshlrev_b32_e32 v170, 16, v60
	v_and_b32_e32 v171, 0xffff0000, v60
	v_pk_mul_f32 v[182:183], v[184:185], v[182:183]
	v_pk_mul_f32 v[166:167], v[4:5], v[166:167]
	v_pk_add_f32 v[162:163], v[180:181], v[162:163] neg_lo:[0,1] neg_hi:[0,1]
	v_fmac_f32_e32 v119, v121, v113
	v_pk_mul_f32 v[166:167], v[166:167], v[182:183]
	v_pk_add_f32 v[162:163], v[162:163], v[170:171]
	v_cvt_pk_bf16_f32 v12, v166, v167
	v_pk_fma_f32 v[166:167], v[118:119], v[162:163], v[170:171] op_sel_hi:[0,1,1] neg_lo:[0,0,1] neg_hi:[0,0,1]
	s_waitcnt vmcnt(1)
	v_lshlrev_b32_e32 v170, 16, v80
	v_and_b32_e32 v171, 0xffff0000, v80
	v_mul_f32_e32 v16, 0xbfb8aa3b, v170
	v_exp_f32_e32 v16, v16
	v_mul_f32_e32 v20, 0xbfb8aa3b, v171
	v_exp_f32_e32 v20, v20
	v_pk_add_f32 v[162:163], v[162:163], v[168:169] neg_lo:[0,1] neg_hi:[0,1]
	v_pk_mul_f32 v[166:167], v[4:5], v[166:167]
	v_add_f32_e32 v16, 1.0, v16
	v_pk_add_f32 v[162:163], v[162:163], v[148:149]
	v_pk_mul_f32 v[164:165], v[166:167], v[164:165]
	v_rcp_f32_e32 v166, v16
	v_add_f32_e32 v16, 1.0, v20
	v_pk_fma_f32 v[148:149], v[126:127], v[162:163], v[148:149] op_sel_hi:[0,1,1] neg_lo:[0,0,1] neg_hi:[0,0,1]
	v_pk_add_f32 v[110:111], v[162:163], v[110:111] neg_lo:[0,1] neg_hi:[0,1]
	v_lshlrev_b32_e32 v162, 16, v76
	v_rcp_f32_e32 v167, v16
	v_and_b32_e32 v163, 0xffff0000, v76
	v_mul_f32_e32 v20, 0xbfb8aa3b, v162
	v_exp_f32_e32 v24, v20
	v_mul_f32_e32 v20, 0xbfb8aa3b, v163
	v_exp_f32_e32 v28, v20
	v_cvt_pk_bf16_f32 v16, v164, v165
	v_pk_mul_f32 v[164:165], v[166:167], v[170:171]
	v_pk_mul_f32 v[148:149], v[4:5], v[148:149]
	v_add_f32_e32 v24, 1.0, v24
	v_pk_mul_f32 v[148:149], v[148:149], v[164:165]
	v_lshlrev_b32_e32 v164, 16, v48
	v_cvt_pk_bf16_f32 v20, v148, v149
	v_rcp_f32_e32 v148, v24
	v_add_f32_e32 v24, 1.0, v28
	v_rcp_f32_e32 v149, v24
	v_and_b32_e32 v165, 0xffff0000, v48
	v_pk_add_f32 v[110:111], v[110:111], v[164:165]
	v_fma_f32 v103, -v103, v119, v115
	v_pk_mul_f32 v[148:149], v[148:149], v[162:163]
	v_pk_fma_f32 v[162:163], v[124:125], v[110:111], v[164:165] op_sel_hi:[0,1,1] neg_lo:[0,0,1] neg_hi:[0,0,1]
	v_pk_add_f32 v[110:111], v[110:111], v[130:131] neg_lo:[0,1] neg_hi:[0,1]
	v_lshlrev_b32_e32 v130, 16, v72
	v_and_b32_e32 v131, 0xffff0000, v72
	v_mul_f32_e32 v24, 0xbfb8aa3b, v130
	v_exp_f32_e32 v28, v24
	v_mul_f32_e32 v24, 0xbfb8aa3b, v131
	v_exp_f32_e32 v36, v24
	v_pk_mul_f32 v[162:163], v[4:5], v[162:163]
	v_add_f32_e32 v28, 1.0, v28
	v_pk_mul_f32 v[148:149], v[162:163], v[148:149]
	v_lshlrev_b32_e32 v162, 16, v32
	v_cvt_pk_bf16_f32 v24, v148, v149
	v_rcp_f32_e32 v148, v28
	v_add_f32_e32 v28, 1.0, v36
	v_rcp_f32_e32 v149, v28
	v_and_b32_e32 v163, 0xffff0000, v32
	v_pk_add_f32 v[110:111], v[110:111], v[162:163]
	v_div_fmas_f32 v103, v103, v113, v119
	v_pk_mul_f32 v[130:131], v[148:149], v[130:131]
	v_pk_fma_f32 v[148:149], v[122:123], v[110:111], v[162:163] op_sel_hi:[0,1,1] neg_lo:[0,0,1] neg_hi:[0,0,1]
	v_pk_mul_f32 v[148:149], v[4:5], v[148:149]
	v_pk_add_f32 v[110:111], v[110:111], v[150:151] neg_lo:[0,1] neg_hi:[0,1]
	v_pk_mul_f32 v[130:131], v[148:149], v[130:131]
	v_lshlrev_b32_e32 v148, 16, v68
	v_and_b32_e32 v149, 0xffff0000, v68
	v_mul_f32_e32 v28, 0xbfb8aa3b, v148
	v_exp_f32_e32 v32, v28
	v_mul_f32_e32 v28, 0xbfb8aa3b, v149
	v_exp_f32_e32 v36, v28
	v_cvt_pk_bf16_f32 v28, v130, v131
	v_add_f32_e32 v32, 1.0, v32
	v_rcp_f32_e32 v130, v32
	v_add_f32_e32 v32, 1.0, v36
	v_rcp_f32_e32 v131, v32
	v_lshlrev_b32_e32 v150, 16, v56
	v_and_b32_e32 v151, 0xffff0000, v56
	v_pk_add_f32 v[110:111], v[110:111], v[150:151]
	v_pk_mul_f32 v[130:131], v[130:131], v[148:149]
	v_pk_fma_f32 v[148:149], v[120:121], v[110:111], v[150:151] op_sel_hi:[0,1,1] neg_lo:[0,0,1] neg_hi:[0,0,1]
	v_pk_mul_f32 v[148:149], v[4:5], v[148:149]
	v_pk_add_f32 v[110:111], v[110:111], v[156:157] neg_lo:[0,1] neg_hi:[0,1]
	v_pk_mul_f32 v[130:131], v[148:149], v[130:131]
	v_lshlrev_b32_e32 v148, 16, v64
	v_and_b32_e32 v149, 0xffff0000, v64
	v_mul_f32_e32 v32, 0xbfb8aa3b, v148
	v_exp_f32_e32 v36, v32
	v_mul_f32_e32 v32, 0xbfb8aa3b, v149
	v_exp_f32_e32 v48, v32
	v_cvt_pk_bf16_f32 v32, v130, v131
	v_add_f32_e32 v36, 1.0, v36
	v_rcp_f32_e32 v130, v36
	v_add_f32_e32 v36, 1.0, v48
	v_rcp_f32_e32 v131, v36
	v_lshlrev_b32_e32 v150, 16, v44
	v_and_b32_e32 v151, 0xffff0000, v44
	v_div_fixup_f32 v112, v103, v112, 1.0
	v_pk_add_f32 v[110:111], v[110:111], v[150:151]
	v_pk_mul_f32 v[130:131], v[130:131], v[148:149]
	v_pk_fma_f32 v[148:149], v[112:113], v[110:111], v[150:151] op_sel_hi:[0,1,1] neg_lo:[0,0,1] neg_hi:[0,0,1]
	v_lshlrev_b32_e32 v88, 16, v89
	v_pk_mul_f32 v[148:149], v[4:5], v[148:149]
	v_pk_add_f32 v[110:111], v[110:111], v[158:159] neg_lo:[0,1] neg_hi:[0,1]
	v_lshlrev_b32_e32 v158, 16, v17
	v_and_b32_e32 v159, 0xffff0000, v17
	v_and_b32_e32 v89, 0xffff0000, v89
	v_mul_f32_e32 v17, 0xbfb8aa3b, v88
	v_pk_mul_f32 v[130:131], v[148:149], v[130:131]
	v_lshlrev_b32_e32 v148, 16, v21
	v_and_b32_e32 v149, 0xffff0000, v21
	v_exp_f32_e32 v17, v17
	v_mul_f32_e32 v21, 0xbfb8aa3b, v89
	v_exp_f32_e32 v21, v21
	v_lshlrev_b32_e32 v84, 16, v85
	v_add_f32_e32 v17, 1.0, v17
	v_rcp_f32_e32 v162, v17
	v_add_f32_e32 v17, 1.0, v21
	v_rcp_f32_e32 v163, v17
	v_and_b32_e32 v85, 0xffff0000, v85
	v_mul_f32_e32 v17, 0xbfb8aa3b, v85
	v_pk_add_f32 v[164:165], v[158:159], 0 op_sel_hi:[1,0]
	v_pk_mul_f32 v[88:89], v[162:163], v[88:89]
	v_lshlrev_b32_e32 v162, 16, v13
	v_and_b32_e32 v163, 0xffff0000, v13
	v_mul_f32_e32 v13, 0xbfb8aa3b, v84
	v_exp_f32_e32 v13, v13
	v_exp_f32_e32 v17, v17
	v_pk_add_f32 v[164:165], v[164:165], v[162:163]
	v_lshlrev_b32_e32 v150, 16, v29
	v_pk_add_f32 v[164:165], v[164:165], v[144:145]
	v_and_b32_e32 v151, 0xffff0000, v29
	v_pk_add_f32 v[164:165], v[164:165], v[148:149]
	v_add_f32_e32 v13, 1.0, v13
	v_lshlrev_b32_e32 v156, 16, v25
	v_and_b32_e32 v157, 0xffff0000, v25
	v_pk_add_f32 v[164:165], v[164:165], v[150:151]
	v_rcp_f32_e32 v166, v13
	v_add_f32_e32 v13, 1.0, v17
	v_lshlrev_b32_e32 v80, 16, v81
	v_lshlrev_b32_e32 v52, 16, v53
	v_and_b32_e32 v53, 0xffff0000, v53
	v_rcp_f32_e32 v167, v13
	v_pk_add_f32 v[164:165], v[164:165], v[156:157]
	v_and_b32_e32 v81, 0xffff0000, v81
	v_mul_f32_e32 v17, 0xbfb8aa3b, v80
	v_lshlrev_b32_e32 v36, 16, v37
	v_and_b32_e32 v37, 0xffff0000, v37
	v_pk_add_f32 v[164:165], v[164:165], v[52:53]
	v_exp_f32_e32 v17, v17
	v_mul_f32_e32 v21, 0xbfb8aa3b, v81
	v_pk_add_f32 v[164:165], v[164:165], v[36:37]
	v_exp_f32_e32 v21, v21
	v_pk_fma_f32 v[36:37], v[114:115], v[164:165], v[36:37] op_sel_hi:[0,1,1] neg_lo:[0,0,1] neg_hi:[0,0,1]
	v_pk_mul_f32 v[84:85], v[166:167], v[84:85]
	v_pk_mul_f32 v[36:37], v[6:7], v[36:37]
	v_lshlrev_b32_e32 v60, 16, v61
	v_and_b32_e32 v61, 0xffff0000, v61
	v_pk_mul_f32 v[36:37], v[36:37], v[84:85]
	v_pk_add_f32 v[84:85], v[164:165], v[158:159] neg_lo:[0,1] neg_hi:[0,1]
	v_add_f32_e32 v17, 1.0, v17
	v_cvt_pk_bf16_f32 v13, v36, v37
	v_pk_add_f32 v[36:37], v[84:85], v[60:61]
	v_rcp_f32_e32 v84, v17
	v_add_f32_e32 v17, 1.0, v21
	v_rcp_f32_e32 v85, v17
	v_lshlrev_b32_e32 v76, 16, v77
	v_pk_fma_f32 v[60:61], v[118:119], v[36:37], v[60:61] op_sel_hi:[0,1,1] neg_lo:[0,0,1] neg_hi:[0,0,1]
	v_and_b32_e32 v77, 0xffff0000, v77
	v_mul_f32_e32 v21, 0xbfb8aa3b, v76
	v_pk_mul_f32 v[60:61], v[6:7], v[60:61]
	v_pk_add_f32 v[36:37], v[36:37], v[162:163] neg_lo:[0,1] neg_hi:[0,1]
	v_exp_f32_e32 v25, v21
	v_mul_f32_e32 v21, 0xbfb8aa3b, v77
	v_pk_mul_f32 v[60:61], v[60:61], v[88:89]
	v_pk_add_f32 v[36:37], v[36:37], v[146:147]
	v_exp_f32_e32 v29, v21
	v_cvt_pk_bf16_f32 v17, v60, v61
	v_pk_mul_f32 v[60:61], v[84:85], v[80:81]
	v_pk_fma_f32 v[80:81], v[126:127], v[36:37], v[146:147] op_sel_hi:[0,1,1] neg_lo:[0,0,1] neg_hi:[0,0,1]
	v_pk_mul_f32 v[80:81], v[6:7], v[80:81]
	v_add_f32_e32 v25, 1.0, v25
	v_pk_mul_f32 v[60:61], v[80:81], v[60:61]
	v_pk_add_f32 v[36:37], v[36:37], v[144:145] neg_lo:[0,1] neg_hi:[0,1]
	v_cvt_pk_bf16_f32 v21, v60, v61
	v_rcp_f32_e32 v60, v25
	v_add_f32_e32 v25, 1.0, v29
	v_rcp_f32_e32 v61, v25
	v_lshlrev_b32_e32 v48, 16, v49
	v_and_b32_e32 v49, 0xffff0000, v49
	v_pk_add_f32 v[36:37], v[36:37], v[48:49]
	v_pk_mul_f32 v[60:61], v[60:61], v[76:77]
	v_pk_fma_f32 v[48:49], v[124:125], v[36:37], v[48:49] op_sel_hi:[0,1,1] neg_lo:[0,0,1] neg_hi:[0,0,1]
	v_pk_mul_f32 v[48:49], v[6:7], v[48:49]
	v_pk_add_f32 v[36:37], v[36:37], v[148:149] neg_lo:[0,1] neg_hi:[0,1]
	v_pk_mul_f32 v[48:49], v[48:49], v[60:61]
	v_lshlrev_b32_e32 v60, 16, v73
	v_and_b32_e32 v61, 0xffff0000, v73
	v_mul_f32_e32 v25, 0xbfb8aa3b, v60
	v_exp_f32_e32 v29, v25
	v_mul_f32_e32 v25, 0xbfb8aa3b, v61
	v_exp_f32_e32 v44, v25
	v_cvt_pk_bf16_f32 v25, v48, v49
	v_add_f32_e32 v29, 1.0, v29
	v_rcp_f32_e32 v48, v29
	v_add_f32_e32 v29, 1.0, v44
	v_rcp_f32_e32 v49, v29
	v_lshlrev_b32_e32 v72, 16, v33
	v_and_b32_e32 v73, 0xffff0000, v33
	v_pk_add_f32 v[36:37], v[36:37], v[72:73]
	v_pk_mul_f32 v[48:49], v[48:49], v[60:61]
	v_pk_fma_f32 v[60:61], v[122:123], v[36:37], v[72:73] op_sel_hi:[0,1,1] neg_lo:[0,0,1] neg_hi:[0,0,1]
	v_pk_mul_f32 v[60:61], v[6:7], v[60:61]
	v_pk_add_f32 v[36:37], v[36:37], v[150:151] neg_lo:[0,1] neg_hi:[0,1]
	v_pk_mul_f32 v[48:49], v[60:61], v[48:49]
	v_lshlrev_b32_e32 v60, 16, v69
	v_and_b32_e32 v61, 0xffff0000, v69
	v_mul_f32_e32 v29, 0xbfb8aa3b, v60
	v_exp_f32_e32 v33, v29
	v_mul_f32_e32 v29, 0xbfb8aa3b, v61
	v_exp_f32_e32 v44, v29
	v_cvt_pk_bf16_f32 v29, v48, v49
	v_add_f32_e32 v33, 1.0, v33
	v_rcp_f32_e32 v48, v33
	v_add_f32_e32 v33, 1.0, v44
	v_rcp_f32_e32 v49, v33
	v_lshlrev_b32_e32 v56, 16, v57
	v_and_b32_e32 v57, 0xffff0000, v57
	v_pk_add_f32 v[36:37], v[36:37], v[56:57]
	v_pk_mul_f32 v[48:49], v[48:49], v[60:61]
	v_pk_fma_f32 v[56:57], v[120:121], v[36:37], v[56:57] op_sel_hi:[0,1,1] neg_lo:[0,0,1] neg_hi:[0,0,1]
	v_pk_mul_f32 v[56:57], v[6:7], v[56:57]
	v_pk_add_f32 v[36:37], v[36:37], v[156:157] neg_lo:[0,1] neg_hi:[0,1]
	v_pk_mul_f32 v[48:49], v[56:57], v[48:49]
	v_lshlrev_b32_e32 v56, 16, v65
	v_and_b32_e32 v57, 0xffff0000, v65
	v_mul_f32_e32 v33, 0xbfb8aa3b, v56
	v_exp_f32_e32 v44, v33
	v_mul_f32_e32 v33, 0xbfb8aa3b, v57
	v_exp_f32_e32 v60, v33
	v_cvt_pk_bf16_f32 v33, v48, v49
	v_add_f32_e32 v44, 1.0, v44
	v_rcp_f32_e32 v48, v44
	v_add_f32_e32 v44, 1.0, v60
	v_rcp_f32_e32 v49, v44
	v_lshlrev_b32_e32 v44, 16, v45
	v_and_b32_e32 v45, 0xffff0000, v45
	v_pk_add_f32 v[36:37], v[36:37], v[44:45]
	v_lshlrev_b32_e32 v68, 16, v90
	v_pk_fma_f32 v[44:45], v[112:113], v[36:37], v[44:45] op_sel_hi:[0,1,1] neg_lo:[0,0,1] neg_hi:[0,0,1]
	v_pk_mul_f32 v[48:49], v[48:49], v[56:57]
	v_pk_mul_f32 v[44:45], v[6:7], v[44:45]
	v_lshlrev_b32_e32 v64, 16, v18
	v_and_b32_e32 v65, 0xffff0000, v18
	v_and_b32_e32 v69, 0xffff0000, v90
	v_mul_f32_e32 v18, 0xbfb8aa3b, v68
	v_pk_mul_f32 v[48:49], v[44:45], v[48:49]
	v_lshlrev_b32_e32 v44, 16, v22
	v_and_b32_e32 v45, 0xffff0000, v22
	v_exp_f32_e32 v18, v18
	v_mul_f32_e32 v22, 0xbfb8aa3b, v69
	v_exp_f32_e32 v22, v22
	v_lshlrev_b32_e32 v88, 16, v86
	v_add_f32_e32 v18, 1.0, v18
	v_rcp_f32_e32 v76, v18
	v_add_f32_e32 v18, 1.0, v22
	v_rcp_f32_e32 v77, v18
	v_and_b32_e32 v89, 0xffff0000, v86
	v_mul_f32_e32 v18, 0xbfb8aa3b, v89
	v_pk_add_f32 v[84:85], v[64:65], 0 op_sel_hi:[1,0]
	v_pk_mul_f32 v[68:69], v[76:77], v[68:69]
	v_lshlrev_b32_e32 v76, 16, v14
	v_and_b32_e32 v77, 0xffff0000, v14
	v_mul_f32_e32 v14, 0xbfb8aa3b, v88
	v_exp_f32_e32 v14, v14
	v_exp_f32_e32 v18, v18
	v_pk_add_f32 v[84:85], v[84:85], v[76:77]
	v_pk_add_f32 v[36:37], v[36:37], v[52:53] neg_lo:[0,1] neg_hi:[0,1]
	v_pk_add_f32 v[84:85], v[84:85], v[128:129]
	v_lshlrev_b32_e32 v52, 16, v30
	v_and_b32_e32 v53, 0xffff0000, v30
	v_pk_add_f32 v[84:85], v[84:85], v[44:45]
	v_add_f32_e32 v14, 1.0, v14
	v_lshlrev_b32_e32 v56, 16, v26
	v_and_b32_e32 v57, 0xffff0000, v26
	v_pk_add_f32 v[84:85], v[84:85], v[52:53]
	v_rcp_f32_e32 v144, v14
	v_add_f32_e32 v14, 1.0, v18
	v_lshlrev_b32_e32 v60, 16, v54
	v_and_b32_e32 v61, 0xffff0000, v54
	v_rcp_f32_e32 v145, v14
	v_pk_add_f32 v[84:85], v[84:85], v[56:57]
	v_lshlrev_b32_e32 v72, 16, v38
	v_and_b32_e32 v73, 0xffff0000, v38
	v_pk_add_f32 v[84:85], v[84:85], v[60:61]
	v_lshlrev_b32_e32 v80, 16, v62
	v_pk_add_f32 v[84:85], v[84:85], v[72:73]
	v_and_b32_e32 v81, 0xffff0000, v62
	v_pk_fma_f32 v[72:73], v[114:115], v[84:85], v[72:73] op_sel_hi:[0,1,1] neg_lo:[0,0,1] neg_hi:[0,0,1]
	v_pk_mul_f32 v[88:89], v[144:145], v[88:89]
	v_pk_mul_f32 v[72:73], v[0:1], v[72:73]
	v_pk_add_f32 v[64:65], v[84:85], v[64:65] neg_lo:[0,1] neg_hi:[0,1]
	v_pk_mul_f32 v[72:73], v[72:73], v[88:89]
	v_pk_add_f32 v[64:65], v[64:65], v[80:81]
	v_cvt_pk_bf16_f32 v14, v72, v73
	v_pk_fma_f32 v[72:73], v[118:119], v[64:65], v[80:81] op_sel_hi:[0,1,1] neg_lo:[0,0,1] neg_hi:[0,0,1]
	v_lshlrev_b32_e32 v80, 16, v82
	v_and_b32_e32 v81, 0xffff0000, v82
	v_mul_f32_e32 v18, 0xbfb8aa3b, v80
	v_exp_f32_e32 v18, v18
	v_mul_f32_e32 v22, 0xbfb8aa3b, v81
	v_exp_f32_e32 v22, v22
	v_pk_mul_f32 v[72:73], v[0:1], v[72:73]
	v_add_f32_e32 v18, 1.0, v18
	v_pk_mul_f32 v[68:69], v[72:73], v[68:69]
	v_rcp_f32_e32 v72, v18
	v_add_f32_e32 v18, 1.0, v22
	v_rcp_f32_e32 v73, v18
	v_pk_add_f32 v[64:65], v[64:65], v[76:77] neg_lo:[0,1] neg_hi:[0,1]
	v_cvt_pk_bf16_f32 v18, v68, v69
	v_pk_add_f32 v[64:65], v[64:65], v[132:133]
	v_pk_mul_f32 v[68:69], v[72:73], v[80:81]
	v_pk_fma_f32 v[72:73], v[126:127], v[64:65], v[132:133] op_sel_hi:[0,1,1] neg_lo:[0,0,1] neg_hi:[0,0,1]
	v_pk_mul_f32 v[72:73], v[0:1], v[72:73]
	v_pk_add_f32 v[64:65], v[64:65], v[128:129] neg_lo:[0,1] neg_hi:[0,1]
	v_pk_mul_f32 v[68:69], v[72:73], v[68:69]
	v_lshlrev_b32_e32 v72, 16, v78
	v_and_b32_e32 v73, 0xffff0000, v78
	v_mul_f32_e32 v22, 0xbfb8aa3b, v72
	v_exp_f32_e32 v26, v22
	v_mul_f32_e32 v22, 0xbfb8aa3b, v73
	v_exp_f32_e32 v30, v22
	v_cvt_pk_bf16_f32 v22, v68, v69
	v_add_f32_e32 v26, 1.0, v26
	v_rcp_f32_e32 v68, v26
	v_add_f32_e32 v26, 1.0, v30
	v_rcp_f32_e32 v69, v26
	v_lshlrev_b32_e32 v76, 16, v50
	v_and_b32_e32 v77, 0xffff0000, v50
	v_pk_add_f32 v[64:65], v[64:65], v[76:77]
	v_pk_mul_f32 v[68:69], v[68:69], v[72:73]
	v_pk_fma_f32 v[72:73], v[124:125], v[64:65], v[76:77] op_sel_hi:[0,1,1] neg_lo:[0,0,1] neg_hi:[0,0,1]
	v_pk_add_f32 v[44:45], v[64:65], v[44:45] neg_lo:[0,1] neg_hi:[0,1]
	v_lshlrev_b32_e32 v64, 16, v74
	v_and_b32_e32 v65, 0xffff0000, v74
	v_mul_f32_e32 v26, 0xbfb8aa3b, v64
	v_exp_f32_e32 v30, v26
	v_mul_f32_e32 v26, 0xbfb8aa3b, v65
	v_exp_f32_e32 v38, v26
	v_pk_mul_f32 v[72:73], v[0:1], v[72:73]
	v_add_f32_e32 v30, 1.0, v30
	v_pk_mul_f32 v[68:69], v[72:73], v[68:69]
	v_lshlrev_b32_e32 v72, 16, v34
	v_cvt_pk_bf16_f32 v26, v68, v69
	v_rcp_f32_e32 v68, v30
	v_add_f32_e32 v30, 1.0, v38
	v_rcp_f32_e32 v69, v30
	v_and_b32_e32 v73, 0xffff0000, v34
	v_pk_add_f32 v[44:45], v[44:45], v[72:73]
	v_lshlrev_b32_e32 v84, 16, v87
	v_pk_mul_f32 v[64:65], v[68:69], v[64:65]
	v_pk_fma_f32 v[68:69], v[122:123], v[44:45], v[72:73] op_sel_hi:[0,1,1] neg_lo:[0,0,1] neg_hi:[0,0,1]
	v_pk_add_f32 v[44:45], v[44:45], v[52:53] neg_lo:[0,1] neg_hi:[0,1]
	v_lshlrev_b32_e32 v52, 16, v70
	v_and_b32_e32 v53, 0xffff0000, v70
	v_mul_f32_e32 v30, 0xbfb8aa3b, v52
	v_exp_f32_e32 v34, v30
	v_mul_f32_e32 v30, 0xbfb8aa3b, v53
	v_exp_f32_e32 v38, v30
	v_pk_mul_f32 v[68:69], v[0:1], v[68:69]
	v_add_f32_e32 v34, 1.0, v34
	v_pk_mul_f32 v[64:65], v[68:69], v[64:65]
	v_lshlrev_b32_e32 v68, 16, v58
	v_cvt_pk_bf16_f32 v30, v64, v65
	v_rcp_f32_e32 v64, v34
	v_add_f32_e32 v34, 1.0, v38
	v_rcp_f32_e32 v65, v34
	v_and_b32_e32 v69, 0xffff0000, v58
	v_pk_add_f32 v[44:45], v[44:45], v[68:69]
	v_lshlrev_b32_e32 v72, 16, v91
	v_pk_mul_f32 v[52:53], v[64:65], v[52:53]
	v_pk_fma_f32 v[64:65], v[120:121], v[44:45], v[68:69] op_sel_hi:[0,1,1] neg_lo:[0,0,1] neg_hi:[0,0,1]
	v_pk_add_f32 v[44:45], v[44:45], v[56:57] neg_lo:[0,1] neg_hi:[0,1]
	v_lshlrev_b32_e32 v56, 16, v66
	v_and_b32_e32 v57, 0xffff0000, v66
	v_mul_f32_e32 v34, 0xbfb8aa3b, v56
	v_exp_f32_e32 v38, v34
	v_mul_f32_e32 v34, 0xbfb8aa3b, v57
	v_exp_f32_e32 v50, v34
	v_pk_mul_f32 v[64:65], v[0:1], v[64:65]
	v_add_f32_e32 v38, 1.0, v38
	v_pk_mul_f32 v[52:53], v[64:65], v[52:53]
	v_lshlrev_b32_e32 v64, 16, v46
	v_cvt_pk_bf16_f32 v34, v52, v53
	v_rcp_f32_e32 v52, v38
	v_add_f32_e32 v38, 1.0, v50
	v_rcp_f32_e32 v53, v38
	v_and_b32_e32 v65, 0xffff0000, v46
	v_pk_add_f32 v[44:45], v[44:45], v[64:65]
	v_lshlrev_b32_e32 v68, 16, v19
	v_pk_mul_f32 v[52:53], v[52:53], v[56:57]
	v_pk_fma_f32 v[56:57], v[112:113], v[44:45], v[64:65] op_sel_hi:[0,1,1] neg_lo:[0,0,1] neg_hi:[0,0,1]
	v_pk_mul_f32 v[56:57], v[0:1], v[56:57]
	v_and_b32_e32 v69, 0xffff0000, v19
	v_and_b32_e32 v73, 0xffff0000, v91
	v_mul_f32_e32 v19, 0xbfb8aa3b, v72
	v_pk_mul_f32 v[52:53], v[56:57], v[52:53]
	v_lshlrev_b32_e32 v56, 16, v23
	v_and_b32_e32 v57, 0xffff0000, v23
	v_exp_f32_e32 v19, v19
	v_mul_f32_e32 v23, 0xbfb8aa3b, v73
	v_exp_f32_e32 v23, v23
	v_and_b32_e32 v85, 0xffff0000, v87
	v_add_f32_e32 v19, 1.0, v19
	v_rcp_f32_e32 v76, v19
	v_add_f32_e32 v19, 1.0, v23
	v_rcp_f32_e32 v77, v19
	v_mul_f32_e32 v19, 0xbfb8aa3b, v85
	v_pk_add_f32 v[80:81], v[68:69], 0 op_sel_hi:[1,0]
	v_exp_f32_e32 v19, v19
	v_pk_mul_f32 v[72:73], v[76:77], v[72:73]
	v_lshlrev_b32_e32 v76, 16, v15
	v_and_b32_e32 v77, 0xffff0000, v15
	v_mul_f32_e32 v15, 0xbfb8aa3b, v84
	v_exp_f32_e32 v15, v15
	v_pk_add_f32 v[80:81], v[80:81], v[76:77]
	v_pk_add_f32 v[44:45], v[44:45], v[60:61] neg_lo:[0,1] neg_hi:[0,1]
	v_pk_add_f32 v[80:81], v[80:81], v[106:107]
	v_lshlrev_b32_e32 v60, 16, v31
	v_and_b32_e32 v61, 0xffff0000, v31
	v_pk_add_f32 v[80:81], v[80:81], v[56:57]
	v_add_f32_e32 v15, 1.0, v15
	v_lshlrev_b32_e32 v64, 16, v27
	v_and_b32_e32 v65, 0xffff0000, v27
	v_pk_add_f32 v[80:81], v[80:81], v[60:61]
	v_rcp_f32_e32 v86, v15
	v_add_f32_e32 v15, 1.0, v19
	v_lshlrev_b32_e32 v54, 16, v55
	v_and_b32_e32 v55, 0xffff0000, v55
	v_rcp_f32_e32 v87, v15
	v_pk_add_f32 v[80:81], v[80:81], v[64:65]
	v_lshlrev_b32_e32 v38, 16, v39
	v_and_b32_e32 v39, 0xffff0000, v39
	v_pk_add_f32 v[80:81], v[80:81], v[54:55]
	v_pk_mul_f32 v[84:85], v[86:87], v[84:85]
	v_pk_add_f32 v[80:81], v[80:81], v[38:39]
	v_lshlrev_b32_e32 v62, 16, v63
	v_pk_fma_f32 v[38:39], v[114:115], v[80:81], v[38:39] op_sel_hi:[0,1,1] neg_lo:[0,0,1] neg_hi:[0,0,1]
	v_pk_mul_f32 v[38:39], v[2:3], v[38:39]
	v_and_b32_e32 v63, 0xffff0000, v63
	v_pk_mul_f32 v[38:39], v[38:39], v[84:85]
	v_pk_add_f32 v[68:69], v[80:81], v[68:69] neg_lo:[0,1] neg_hi:[0,1]
	v_cvt_pk_bf16_f32 v15, v38, v39
	v_pk_add_f32 v[38:39], v[68:69], v[62:63]
	v_lshlrev_b32_e32 v68, 16, v83
	v_and_b32_e32 v69, 0xffff0000, v83
	v_mul_f32_e32 v19, 0xbfb8aa3b, v68
	v_exp_f32_e32 v19, v19
	v_mul_f32_e32 v23, 0xbfb8aa3b, v69
	v_exp_f32_e32 v23, v23
	v_pk_fma_f32 v[62:63], v[118:119], v[38:39], v[62:63] op_sel_hi:[0,1,1] neg_lo:[0,0,1] neg_hi:[0,0,1]
	v_pk_mul_f32 v[62:63], v[2:3], v[62:63]
	v_add_f32_e32 v19, 1.0, v19
	v_pk_mul_f32 v[62:63], v[62:63], v[72:73]
	v_rcp_f32_e32 v72, v19
	v_add_f32_e32 v19, 1.0, v23
	v_rcp_f32_e32 v73, v19
	v_pk_add_f32 v[38:39], v[38:39], v[76:77] neg_lo:[0,1] neg_hi:[0,1]
	v_cvt_pk_bf16_f32 v19, v62, v63
	v_pk_add_f32 v[38:39], v[38:39], v[116:117]
	v_pk_mul_f32 v[62:63], v[72:73], v[68:69]
	v_pk_fma_f32 v[68:69], v[126:127], v[38:39], v[116:117] op_sel_hi:[0,1,1] neg_lo:[0,0,1] neg_hi:[0,0,1]
	v_pk_mul_f32 v[68:69], v[2:3], v[68:69]
	v_pk_add_f32 v[38:39], v[38:39], v[106:107] neg_lo:[0,1] neg_hi:[0,1]
	v_pk_mul_f32 v[62:63], v[68:69], v[62:63]
	v_lshlrev_b32_e32 v68, 16, v79
	v_and_b32_e32 v69, 0xffff0000, v79
	v_mul_f32_e32 v23, 0xbfb8aa3b, v68
	v_exp_f32_e32 v27, v23
	v_mul_f32_e32 v23, 0xbfb8aa3b, v69
	v_exp_f32_e32 v31, v23
	v_lshlrev_b32_e32 v50, 16, v51
	v_and_b32_e32 v51, 0xffff0000, v51
	v_add_f32_e32 v27, 1.0, v27
	v_pk_add_f32 v[38:39], v[38:39], v[50:51]
	v_cvt_pk_bf16_f32 v23, v62, v63
	v_rcp_f32_e32 v62, v27
	v_add_f32_e32 v27, 1.0, v31
	v_pk_fma_f32 v[50:51], v[124:125], v[38:39], v[50:51] op_sel_hi:[0,1,1] neg_lo:[0,0,1] neg_hi:[0,0,1]
	v_pk_add_f32 v[38:39], v[38:39], v[56:57] neg_lo:[0,1] neg_hi:[0,1]
	v_lshlrev_b32_e32 v56, 16, v75
	v_rcp_f32_e32 v63, v27
	v_and_b32_e32 v57, 0xffff0000, v75
	v_mul_f32_e32 v27, 0xbfb8aa3b, v56
	v_exp_f32_e32 v31, v27
	v_mul_f32_e32 v27, 0xbfb8aa3b, v57
	v_exp_f32_e32 v46, v27
	v_pk_mul_f32 v[62:63], v[62:63], v[68:69]
	v_pk_mul_f32 v[50:51], v[2:3], v[50:51]
	v_add_f32_e32 v31, 1.0, v31
	v_pk_mul_f32 v[50:51], v[50:51], v[62:63]
	v_lshlrev_b32_e32 v62, 16, v35
	v_cvt_pk_bf16_f32 v27, v50, v51
	v_rcp_f32_e32 v50, v31
	v_add_f32_e32 v31, 1.0, v46
	v_rcp_f32_e32 v51, v31
	v_and_b32_e32 v63, 0xffff0000, v35
	v_pk_add_f32 v[38:39], v[38:39], v[62:63]
	v_lshlrev_b64 v[94:95], 11, v[94:95]
	v_pk_mul_f32 v[50:51], v[50:51], v[56:57]
	v_pk_fma_f32 v[56:57], v[122:123], v[38:39], v[62:63] op_sel_hi:[0,1,1] neg_lo:[0,0,1] neg_hi:[0,0,1]
	v_pk_mul_f32 v[56:57], v[2:3], v[56:57]
	v_lshl_add_u64 v[94:95], v[138:139], 0, v[94:95]
	v_pk_mul_f32 v[50:51], v[56:57], v[50:51]
	v_lshlrev_b32_e32 v56, 16, v71
	v_and_b32_e32 v57, 0xffff0000, v71
	v_mul_f32_e32 v31, 0xbfb8aa3b, v56
	v_exp_f32_e32 v35, v31
	v_mul_f32_e32 v31, 0xbfb8aa3b, v57
	v_exp_f32_e32 v46, v31
	global_store_dwordx4 v[92:93], v[12:15], off
	global_store_dwordx4 v[94:95], v[16:19], off
	global_store_dwordx4 v[100:101], v[20:23], off
	v_lshlrev_b32_e32 v12, 16, v67
	v_and_b32_e32 v13, 0xffff0000, v67
	v_mul_f32_e32 v14, 0xbfb8aa3b, v12
	v_mul_f32_e32 v15, 0xbfb8aa3b, v13
	v_exp_f32_e32 v14, v14
	v_exp_f32_e32 v15, v15
	v_add_f32_e32 v35, 1.0, v35
	v_cvt_pk_bf16_f32 v31, v50, v51
	v_rcp_f32_e32 v50, v35
	v_add_f32_e32 v35, 1.0, v46
	v_rcp_f32_e32 v51, v35
	v_add_f32_e32 v14, 1.0, v14
	v_add_f32_e32 v15, 1.0, v15
	v_pk_add_f32 v[38:39], v[38:39], v[60:61] neg_lo:[0,1] neg_hi:[0,1]
	v_lshlrev_b32_e32 v58, 16, v59
	v_and_b32_e32 v59, 0xffff0000, v59
	v_rcp_f32_e32 v14, v14
	v_rcp_f32_e32 v15, v15
	v_pk_add_f32 v[38:39], v[38:39], v[58:59]
	v_pk_mul_f32 v[50:51], v[50:51], v[56:57]
	v_pk_fma_f32 v[56:57], v[120:121], v[38:39], v[58:59] op_sel_hi:[0,1,1] neg_lo:[0,0,1] neg_hi:[0,0,1]
	v_pk_add_f32 v[38:39], v[38:39], v[64:65] neg_lo:[0,1] neg_hi:[0,1]
	v_lshlrev_b32_e32 v46, 16, v47
	v_and_b32_e32 v47, 0xffff0000, v47
	v_pk_add_f32 v[16:17], v[38:39], v[46:47]
	v_pk_mul_f32 v[12:13], v[14:15], v[12:13]
	v_pk_fma_f32 v[14:15], v[112:113], v[16:17], v[46:47] op_sel_hi:[0,1,1] neg_lo:[0,0,1] neg_hi:[0,0,1]
	v_ashrrev_i32_e32 v103, 31, v102
	v_pk_mul_f32 v[14:15], v[2:3], v[14:15]
	v_pk_add_f32 v[18:19], v[16:17], v[54:55] neg_lo:[0,1] neg_hi:[0,1]
	v_lshl_add_u64 v[16:17], s[28:29], 0, v[102:103]
	v_lshlrev_b64 v[98:99], 11, v[98:99]
	v_lshlrev_b64 v[104:105], 11, v[104:105]
	v_pk_mul_f32 v[56:57], v[2:3], v[56:57]
	v_pk_mul_f32 v[20:21], v[14:15], v[12:13]
	v_lshlrev_b64 v[16:17], 11, v[16:17]
	v_lshl_add_u64 v[98:99], v[138:139], 0, v[98:99]
	v_lshl_add_u64 v[104:105], v[138:139], 0, v[104:105]
	v_lshlrev_b64 v[108:109], 11, v[108:109]
	v_pk_mul_f32 v[50:51], v[56:57], v[50:51]
	v_cvt_pk_bf16_f32 v12, v130, v131
	v_cvt_pk_bf16_f32 v13, v48, v49
	v_cvt_pk_bf16_f32 v14, v52, v53
	v_cvt_pk_bf16_f32 v15, v20, v21
	v_lshl_add_u64 v[16:17], v[138:139], 0, v[16:17]
	v_lshl_add_u64 v[108:109], v[138:139], 0, v[108:109]
	v_cvt_pk_bf16_f32 v35, v50, v51
	global_store_dwordx4 v[98:99], v[24:27], off
	global_store_dwordx4 v[104:105], v[28:31], off
	global_store_dwordx4 v[108:109], v[32:35], off
	global_store_dwordx4 v[16:17], v[12:15], off
	s_waitcnt vmcnt(7)
	v_lshlrev_b32_e32 v20, 16, v40
	v_and_b32_e32 v21, 0xffff0000, v40
	v_lshlrev_b32_e32 v14, 16, v41
	v_and_b32_e32 v15, 0xffff0000, v41
	v_mul_f32_e32 v16, 0xbfb8aa3b, v14
	v_mul_f32_e32 v22, 0xbfb8aa3b, v20
	v_exp_f32_e32 v16, v16
	v_mul_f32_e32 v17, 0xbfb8aa3b, v15
	v_exp_f32_e32 v22, v22
	v_mul_f32_e32 v23, 0xbfb8aa3b, v21
	v_exp_f32_e32 v17, v17
	v_exp_f32_e32 v23, v23
	v_add_f32_e32 v16, 1.0, v16
	v_lshlrev_b32_e32 v24, 16, v42
	v_add_f32_e32 v12, 1.0, v22
	v_rcp_f32_e32 v22, v16
	v_add_f32_e32 v16, 1.0, v17
	v_and_b32_e32 v25, 0xffff0000, v42
	v_mul_f32_e32 v17, 0xbfb8aa3b, v24
	v_add_f32_e32 v13, 1.0, v23
	v_exp_f32_e32 v17, v17
	v_mul_f32_e32 v23, 0xbfb8aa3b, v25
	v_exp_f32_e32 v27, v23
	v_lshlrev_b32_e32 v28, 16, v43
	v_rcp_f32_e32 v23, v16
	v_add_f32_e32 v16, 1.0, v17
	v_and_b32_e32 v29, 0xffff0000, v43
	v_mul_f32_e32 v17, 0xbfb8aa3b, v28
	v_rcp_f32_e32 v26, v16
	v_add_f32_e32 v16, 1.0, v27
	v_exp_f32_e32 v17, v17
	v_mul_f32_e32 v27, 0xbfb8aa3b, v29
	v_exp_f32_e32 v31, v27
	v_rcp_f32_e32 v27, v16
	v_add_f32_e32 v16, 1.0, v17
	v_rcp_f32_e32 v30, v16
	v_add_f32_e32 v16, 1.0, v31
	v_rcp_f32_e32 v12, v12
	v_rcp_f32_e32 v13, v13
	v_rcp_f32_e32 v31, v16
	v_pk_mul_f32 v[16:17], v[12:13], v[20:21]
	v_pk_mul_f32 v[12:13], v[22:23], v[14:15]
	v_pk_mul_f32 v[20:21], v[26:27], v[24:25]
	v_pk_mul_f32 v[14:15], v[30:31], v[28:29]
	v_min_i32_e32 v22, 7, v140

.LBB0_194:
	s_andn2_b64 vcc, exec, s[2:3]
	s_cbranch_vccnz .LBB0_111
	s_mov_b64 s[2:3], -1
	s_cmp_eq_u32 s26, 1
	v_cmp_lt_i32_e32 vcc, 0, v142
	s_cbranch_scc1 .LBB0_215
	v_mov_b32_e32 v64, 0
	v_mov_b32_e32 v68, 0
	v_mov_b32_e32 v69, 0
	v_mov_b32_e32 v70, 0
	v_mov_b32_e32 v71, 0
	s_and_saveexec_b64 s[2:3], vcc
	s_cbranch_execz .LBB0_198
	v_add_u32_e32 v8, -1, v142
	v_mov_b32_e32 v9, v97
	v_lshl_add_u64 v[8:9], s[28:29], 0, v[8:9]
	v_lshlrev_b64 v[8:9], 11, v[8:9]
	v_lshl_add_u64 v[8:9], v[134:135], 0, v[8:9]
	global_load_dwordx4 v[68:71], v[8:9], off nt
.LBB0_198:
	s_or_b64 exec, exec, s[2:3]
	v_cmp_lt_i32_e32 vcc, -1, v142
	v_mov_b32_e32 v65, 0
	v_mov_b32_e32 v66, 0
	v_mov_b32_e32 v67, 0
	s_and_saveexec_b64 s[2:3], vcc
	s_cbranch_execz .LBB0_200
	v_mov_b32_e32 v143, v97
	v_lshl_add_u64 v[8:9], s[28:29], 0, v[142:143]
	v_lshlrev_b64 v[8:9], 11, v[8:9]
	v_lshl_add_u64 v[8:9], v[134:135], 0, v[8:9]
	global_load_dwordx4 v[64:67], v[8:9], off nt
.LBB0_200:
	s_or_b64 exec, exec, s[2:3]
	v_or_b32_e32 v90, 1, v142
	v_cmp_lt_i32_e32 vcc, -2, v142
	v_mov_b32_e32 v56, 0
	v_mov_b32_e32 v60, 0
	v_mov_b32_e32 v61, 0
	v_mov_b32_e32 v62, 0
	v_mov_b32_e32 v63, 0
	s_and_saveexec_b64 s[2:3], vcc
	s_cbranch_execz .LBB0_202
	v_mov_b32_e32 v91, v97
	v_lshl_add_u64 v[8:9], s[28:29], 0, v[90:91]
	v_lshlrev_b64 v[8:9], 11, v[8:9]
	v_lshl_add_u64 v[8:9], v[134:135], 0, v[8:9]
	global_load_dwordx4 v[60:63], v[8:9], off nt
.LBB0_202:
	s_or_b64 exec, exec, s[2:3]
	v_or_b32_e32 v86, 2, v142
	v_cmp_lt_i32_e32 vcc, -3, v142
	v_mov_b32_e32 v57, 0
	v_mov_b32_e32 v58, 0
	v_mov_b32_e32 v59, 0
	s_and_saveexec_b64 s[2:3], vcc
	s_cbranch_execz .LBB0_204
	v_mov_b32_e32 v87, v97
	v_lshl_add_u64 v[8:9], s[28:29], 0, v[86:87]
	v_lshlrev_b64 v[8:9], 11, v[8:9]
	v_lshl_add_u64 v[8:9], v[134:135], 0, v[8:9]
	global_load_dwordx4 v[56:59], v[8:9], off nt
.LBB0_204:
	s_or_b64 exec, exec, s[2:3]
	v_or_b32_e32 v82, 3, v142
	v_cmp_lt_i32_e32 vcc, -4, v142
	v_mov_b32_e32 v28, 0
	v_mov_b32_e32 v32, 0
	v_mov_b32_e32 v33, 0
	v_mov_b32_e32 v34, 0
	v_mov_b32_e32 v35, 0
	s_and_saveexec_b64 s[2:3], vcc
	s_cbranch_execz .LBB0_206
	v_mov_b32_e32 v83, v97
	v_lshl_add_u64 v[8:9], s[28:29], 0, v[82:83]
	v_lshlrev_b64 v[8:9], 11, v[8:9]
	v_lshl_add_u64 v[8:9], v[134:135], 0, v[8:9]
	global_load_dwordx4 v[32:35], v[8:9], off nt
.LBB0_206:
	s_or_b64 exec, exec, s[2:3]
	v_or_b32_e32 v78, 4, v142
	v_cmp_lt_i32_e32 vcc, -5, v142
	v_mov_b32_e32 v29, 0
	v_mov_b32_e32 v30, 0
	v_mov_b32_e32 v31, 0
	s_and_saveexec_b64 s[2:3], vcc
	s_cbranch_execz .LBB0_208
	v_mov_b32_e32 v79, v97
	v_lshl_add_u64 v[8:9], s[28:29], 0, v[78:79]
	v_lshlrev_b64 v[8:9], 11, v[8:9]
	v_lshl_add_u64 v[8:9], v[134:135], 0, v[8:9]
	global_load_dwordx4 v[28:31], v[8:9], off nt
.LBB0_208:
	s_or_b64 exec, exec, s[2:3]
	v_or_b32_e32 v106, 5, v142
	v_cmp_lt_i32_e32 vcc, -6, v142
	v_mov_b32_e32 v16, 0
	v_mov_b32_e32 v24, 0
	v_mov_b32_e32 v25, 0
	v_mov_b32_e32 v26, 0
	v_mov_b32_e32 v27, 0
	s_and_saveexec_b64 s[2:3], vcc
	s_cbranch_execz .LBB0_210
	v_mov_b32_e32 v107, v97
	v_lshl_add_u64 v[8:9], s[28:29], 0, v[106:107]
	v_lshlrev_b64 v[8:9], 11, v[8:9]
	v_lshl_add_u64 v[8:9], v[134:135], 0, v[8:9]
	global_load_dwordx4 v[24:27], v[8:9], off nt
.LBB0_210:
	s_or_b64 exec, exec, s[2:3]
	v_or_b32_e32 v76, 6, v142
	v_cmp_lt_i32_e32 vcc, -7, v142
	v_mov_b32_e32 v17, 0
	v_mov_b32_e32 v18, 0
	v_mov_b32_e32 v19, 0
	s_and_saveexec_b64 s[2:3], vcc
	s_cbranch_execz .LBB0_212
	v_mov_b32_e32 v77, v97
	v_lshl_add_u64 v[8:9], s[28:29], 0, v[76:77]
	v_lshlrev_b64 v[8:9], 11, v[8:9]
	v_lshl_add_u64 v[8:9], v[134:135], 0, v[8:9]
	global_load_dwordx4 v[16:19], v[8:9], off nt

.LBB0_214:
	s_or_b64 exec, exec, s[2:3]
	v_ashrrev_i32_e32 v143, 31, v142
	v_lshl_add_u64 v[12:13], s[28:29], 0, v[142:143]
	v_lshlrev_b64 v[88:89], 11, v[12:13]
	v_lshl_add_u64 v[12:13], v[136:137], 0, v[88:89]
	global_load_dwordx4 v[72:75], v[12:13], off nt
	global_load_dwordx4 v[52:55], v[12:13], off offset:2048 nt
	v_min_i32_e32 v77, 1, v142
	v_add_u32_e32 v77, 1, v77
	v_cvt_f32_i32_e32 v77, v77
	v_add_co_u32_e32 v14, vcc, s53, v12
	s_waitcnt vmcnt(2)
	v_lshlrev_b32_e32 v110, 16, v64
	v_div_scale_f32 v79, s[2:3], v77, v77, 1.0
	v_addc_co_u32_e32 v15, vcc, 0, v13, vcc
	v_rcp_f32_e32 v80, v79
	v_add_co_u32_e32 v20, vcc, s58, v12
	v_and_b32_e32 v111, 0xffff0000, v64
	s_nop 0
	v_addc_co_u32_e32 v21, vcc, 0, v13, vcc
	v_add_co_u32_e32 v12, vcc, s64, v12
	v_fma_f32 v81, -v79, v80, 1.0
	s_nop 0
	v_addc_co_u32_e32 v13, vcc, 0, v13, vcc
	v_fmac_f32_e32 v80, v81, v80
	v_div_scale_f32 v81, vcc, 1.0, v77, 1.0
	v_mul_f32_e32 v83, v81, v80
	v_fma_f32 v84, -v79, v83, v81
	v_fmac_f32_e32 v83, v84, v80
	v_lshlrev_b32_e32 v100, 16, v65
	v_and_b32_e32 v101, 0xffff0000, v65
	v_fma_f32 v79, -v79, v83, v81
	v_lshlrev_b32_e32 v112, 16, v68
	v_and_b32_e32 v113, 0xffff0000, v68
	v_div_fmas_f32 v79, v79, v80, v83
	v_pk_add_f32 v[80:81], v[112:113], 0 op_sel_hi:[1,0]
	v_div_fixup_f32 v94, v79, v77, 1.0
	v_pk_add_f32 v[118:119], v[80:81], v[110:111]
	v_lshlrev_b32_e32 v104, 16, v69
	v_pk_fma_f32 v[80:81], v[94:95], v[118:119], v[110:111] op_sel_hi:[0,1,1] neg_lo:[0,0,1] neg_hi:[0,0,1]
	v_pk_mul_f32 v[80:81], v[4:5], v[80:81]
	v_and_b32_e32 v105, 0xffff0000, v69
	v_pk_add_f32 v[68:69], v[104:105], 0 op_sel_hi:[1,0]
	v_lshlrev_b32_e32 v122, 16, v60
	v_pk_add_f32 v[108:109], v[68:69], v[100:101]
	v_and_b32_e32 v123, 0xffff0000, v60
	v_pk_fma_f32 v[68:69], v[94:95], v[108:109], v[100:101] op_sel_hi:[0,1,1] neg_lo:[0,0,1] neg_hi:[0,0,1]
	v_pk_mul_f32 v[68:69], v[6:7], v[68:69]
	v_min_i32_e32 v60, 1, v90
	v_add_u32_e32 v60, 1, v60
	v_cvt_f32_i32_e32 v60, v60
	v_lshlrev_b32_e32 v116, 16, v61
	v_and_b32_e32 v117, 0xffff0000, v61
	v_lshlrev_b32_e32 v120, 16, v56
	v_div_scale_f32 v61, s[2:3], v60, v60, 1.0
	v_and_b32_e32 v121, 0xffff0000, v56
	v_min_i32_e32 v56, 1, v86
	v_add_u32_e32 v56, 1, v56
	v_cvt_f32_i32_e32 v56, v56
	global_load_dwordx4 v[48:51], v[20:21], off offset:-4096 nt
	global_load_dwordx4 v[44:47], v[14:15], off offset:2048 nt
	global_load_dwordx4 v[40:43], v[20:21], off nt
	global_load_dwordx4 v[36:39], v[20:21], off offset:2048 nt
	s_nop 0
	global_load_dwordx4 v[20:23], v[12:13], off nt
	s_nop 0
	global_load_dwordx4 v[12:15], v[12:13], off offset:2048 nt
	v_lshlrev_b32_e32 v114, 16, v57
	v_and_b32_e32 v115, 0xffff0000, v57
	v_div_scale_f32 v57, s[2:3], v56, v56, 1.0
	v_ashrrev_i32_e32 v91, 31, v90
	v_ashrrev_i32_e32 v87, 31, v86
	v_ashrrev_i32_e32 v83, 31, v82
	v_ashrrev_i32_e32 v79, 31, v78
	v_ashrrev_i32_e32 v107, 31, v106
	v_pk_add_f32 v[104:105], v[108:109], v[104:105] neg_lo:[0,1] neg_hi:[0,1]
	s_waitcnt vmcnt(7)
	v_lshlrev_b32_e32 v84, 16, v72
	v_mul_f32_e32 v64, 0xbfb8aa3b, v84
	v_exp_f32_e32 v64, v64
	v_and_b32_e32 v85, 0xffff0000, v72
	v_and_b32_e32 v65, 0xffff0000, v73
	s_waitcnt vmcnt(6)
	v_lshlrev_b32_e32 v108, 16, v53
	v_add_f32_e32 v64, 1.0, v64
	v_rcp_f32_e32 v92, v64
	v_mul_f32_e32 v64, 0xbfb8aa3b, v85
	v_exp_f32_e32 v64, v64
	v_and_b32_e32 v109, 0xffff0000, v53
	v_pk_add_f32 v[104:105], v[104:105], v[116:117]
	v_add_f32_e32 v64, 1.0, v64
	v_rcp_f32_e32 v93, v64
	v_lshlrev_b32_e32 v64, 16, v73
	v_mul_f32_e32 v72, 0xbfb8aa3b, v64
	v_mul_f32_e32 v73, 0xbfb8aa3b, v65
	v_exp_f32_e32 v72, v72
	v_exp_f32_e32 v73, v73
	v_pk_mul_f32 v[84:85], v[92:93], v[84:85]
	v_lshlrev_b32_e32 v92, 16, v70
	v_add_f32_e32 v72, 1.0, v72
	v_add_f32_e32 v73, 1.0, v73
	v_rcp_f32_e32 v72, v72
	v_rcp_f32_e32 v73, v73
	v_pk_mul_f32 v[98:99], v[80:81], v[84:85]
	v_lshlrev_b32_e32 v80, 16, v66
	v_and_b32_e32 v81, 0xffff0000, v66
	v_pk_mul_f32 v[64:65], v[72:73], v[64:65]
	v_lshlrev_b32_e32 v72, 16, v74
	v_mul_f32_e32 v66, 0xbfb8aa3b, v72
	v_exp_f32_e32 v66, v66
	v_and_b32_e32 v73, 0xffff0000, v74
	v_and_b32_e32 v93, 0xffff0000, v70
	v_pk_mul_f32 v[68:69], v[68:69], v[64:65]
	v_add_f32_e32 v66, 1.0, v66
	v_rcp_f32_e32 v84, v66
	v_mul_f32_e32 v66, 0xbfb8aa3b, v73
	v_exp_f32_e32 v66, v66
	v_pk_add_f32 v[64:65], v[92:93], 0 op_sel_hi:[1,0]
	v_lshlrev_b32_e32 v70, 16, v71
	v_pk_add_f32 v[102:103], v[64:65], v[80:81]
	v_add_f32_e32 v66, 1.0, v66
	v_rcp_f32_e32 v85, v66
	v_pk_fma_f32 v[64:65], v[94:95], v[102:103], v[80:81] op_sel_hi:[0,1,1] neg_lo:[0,0,1] neg_hi:[0,0,1]
	v_pk_mul_f32 v[64:65], v[0:1], v[64:65]
	v_lshlrev_b32_e32 v66, 16, v75
	v_pk_mul_f32 v[72:73], v[84:85], v[72:73]
	v_mul_f32_e32 v74, 0xbfb8aa3b, v66
	v_pk_mul_f32 v[72:73], v[64:65], v[72:73]
	v_lshlrev_b32_e32 v64, 16, v67
	v_and_b32_e32 v65, 0xffff0000, v67
	v_and_b32_e32 v67, 0xffff0000, v75
	v_mul_f32_e32 v75, 0xbfb8aa3b, v67
	v_exp_f32_e32 v74, v74
	v_exp_f32_e32 v75, v75
	v_and_b32_e32 v71, 0xffff0000, v71
	v_pk_add_f32 v[84:85], v[70:71], 0 op_sel_hi:[1,0]
	v_add_f32_e32 v74, 1.0, v74
	v_add_f32_e32 v75, 1.0, v75
	v_rcp_f32_e32 v74, v74
	v_rcp_f32_e32 v75, v75
	v_pk_add_f32 v[84:85], v[84:85], v[64:65]
	v_pk_add_f32 v[100:101], v[104:105], v[100:101] neg_lo:[0,1] neg_hi:[0,1]
	v_pk_mul_f32 v[66:67], v[74:75], v[66:67]
	v_pk_fma_f32 v[74:75], v[94:95], v[84:85], v[64:65] op_sel_hi:[0,1,1] neg_lo:[0,0,1] neg_hi:[0,0,1]
	v_pk_mul_f32 v[74:75], v[2:3], v[74:75]
	v_lshlrev_b32_e32 v94, 16, v58
	v_pk_mul_f32 v[74:75], v[74:75], v[66:67]
	v_cvt_pk_bf16_f32 v66, v98, v99
	v_lshlrev_b32_e32 v98, 16, v62
	v_and_b32_e32 v99, 0xffff0000, v62
	v_rcp_f32_e32 v62, v61
	v_cvt_pk_bf16_f32 v67, v68, v69
	v_cvt_pk_bf16_f32 v68, v72, v73
	v_cvt_pk_bf16_f32 v69, v74, v75
	v_lshl_add_u64 v[72:73], v[138:139], 0, v[88:89]
	global_store_dwordx4 v[72:73], v[66:69], off
	v_and_b32_e32 v95, 0xffff0000, v58
	v_rcp_f32_e32 v58, v57
	v_lshlrev_b32_e32 v66, 16, v63
	v_and_b32_e32 v67, 0xffff0000, v63
	v_fma_f32 v63, -v61, v62, 1.0
	v_fmac_f32_e32 v62, v63, v62
	v_div_scale_f32 v63, vcc, 1.0, v60, 1.0
	v_mul_f32_e32 v68, v63, v62
	v_fma_f32 v69, -v61, v68, v63
	v_fmac_f32_e32 v68, v69, v62
	v_fma_f32 v61, -v61, v68, v63
	v_div_fmas_f32 v61, v61, v62, v68
	v_lshlrev_b32_e32 v62, 16, v59
	v_and_b32_e32 v63, 0xffff0000, v59
	v_fma_f32 v59, -v57, v58, 1.0
	v_fmac_f32_e32 v58, v59, v58
	v_div_scale_f32 v59, vcc, 1.0, v56, 1.0
	v_mul_f32_e32 v68, v59, v58
	v_fma_f32 v69, -v57, v68, v59
	v_fmac_f32_e32 v68, v69, v58
	v_fma_f32 v57, -v57, v68, v59
	v_div_fmas_f32 v57, v57, v58, v68
	v_min_i32_e32 v58, 1, v82
	v_add_u32_e32 v58, 1, v58
	v_cvt_f32_i32_e32 v58, v58
	v_div_fixup_f32 v88, v61, v60, 1.0
	v_lshl_add_u64 v[60:61], s[28:29], 0, v[90:91]
	v_div_fixup_f32 v90, v57, v56, 1.0
	v_div_scale_f32 v59, s[2:3], v58, v58, 1.0
	v_rcp_f32_e32 v68, v59
	v_lshl_add_u64 v[56:57], s[28:29], 0, v[86:87]
	v_pk_add_f32 v[100:101], v[100:101], v[114:115]
	v_lshlrev_b64 v[60:61], 11, v[60:61]
	v_fma_f32 v69, -v59, v68, 1.0
	v_fmac_f32_e32 v68, v69, v68
	v_div_scale_f32 v69, vcc, 1.0, v58, 1.0
	v_mul_f32_e32 v72, v69, v68
	v_fma_f32 v73, -v59, v72, v69
	v_fmac_f32_e32 v72, v73, v68
	v_fma_f32 v59, -v59, v72, v69
	v_div_fmas_f32 v59, v59, v68, v72
	v_min_i32_e32 v68, 1, v78
	v_add_u32_e32 v68, 1, v68
	v_cvt_f32_i32_e32 v68, v68
	v_div_fixup_f32 v86, v59, v58, 1.0
	v_lshl_add_u64 v[58:59], s[28:29], 0, v[82:83]
	v_lshl_add_u64 v[60:61], v[138:139], 0, v[60:61]
	v_div_scale_f32 v69, s[2:3], v68, v68, 1.0
	v_rcp_f32_e32 v72, v69
	v_lshlrev_b64 v[56:57], 11, v[56:57]
	v_lshlrev_b64 v[58:59], 11, v[58:59]
	v_lshl_add_u64 v[56:57], v[138:139], 0, v[56:57]
	v_fma_f32 v73, -v69, v72, 1.0
	v_fmac_f32_e32 v72, v73, v72
	v_div_scale_f32 v73, vcc, 1.0, v68, 1.0
	v_mul_f32_e32 v74, v73, v72
	v_fma_f32 v75, -v69, v74, v73
	v_fmac_f32_e32 v74, v75, v72
	v_fma_f32 v69, -v69, v74, v73
	v_div_fmas_f32 v69, v69, v72, v74
	v_min_i32_e32 v72, 1, v106
	v_add_u32_e32 v72, 1, v72
	v_cvt_f32_i32_e32 v72, v72
	v_div_fixup_f32 v82, v69, v68, 1.0
	v_lshl_add_u64 v[68:69], s[28:29], 0, v[78:79]
	v_lshlrev_b64 v[68:69], 11, v[68:69]
	v_div_scale_f32 v73, s[2:3], v72, v72, 1.0
	v_rcp_f32_e32 v74, v73
	v_lshl_add_u64 v[58:59], v[138:139], 0, v[58:59]
	v_lshl_add_u64 v[68:69], v[138:139], 0, v[68:69]
	v_fma_f32 v75, -v73, v74, 1.0
	v_fmac_f32_e32 v74, v75, v74
	v_div_scale_f32 v75, vcc, 1.0, v72, 1.0
	v_mul_f32_e32 v77, v75, v74
	v_fma_f32 v78, -v73, v77, v75
	v_fmac_f32_e32 v77, v78, v74
	v_fma_f32 v73, -v73, v77, v75
	v_div_fmas_f32 v73, v73, v74, v77
	v_div_fixup_f32 v78, v73, v72, 1.0
	v_lshl_add_u64 v[72:73], s[28:29], 0, v[106:107]
	v_pk_add_f32 v[106:107], v[118:119], v[112:113] neg_lo:[0,1] neg_hi:[0,1]
	v_lshlrev_b32_e32 v112, 16, v52
	v_and_b32_e32 v113, 0xffff0000, v52
	v_mul_f32_e32 v52, 0xbfb8aa3b, v112
	v_exp_f32_e32 v52, v52
	v_pk_add_f32 v[106:107], v[106:107], v[122:123]
	v_lshlrev_b64 v[72:73], 11, v[72:73]
	v_lshl_add_u64 v[74:75], v[138:139], 0, v[72:73]
	v_add_f32_e32 v52, 1.0, v52
	v_rcp_f32_e32 v118, v52
	v_mul_f32_e32 v52, 0xbfb8aa3b, v113
	v_exp_f32_e32 v52, v52
	v_min_i32_e32 v72, 1, v76
	v_add_u32_e32 v72, 1, v72
	v_cvt_f32_i32_e32 v72, v72
	v_add_f32_e32 v52, 1.0, v52
	v_rcp_f32_e32 v119, v52
	v_div_scale_f32 v73, s[2:3], v72, v72, 1.0
	v_pk_mul_f32 v[112:113], v[118:119], v[112:113]
	v_pk_fma_f32 v[118:119], v[88:89], v[106:107], v[122:123] op_sel_hi:[0,1,1] neg_lo:[0,0,1] neg_hi:[0,0,1]
	v_pk_add_f32 v[106:107], v[106:107], v[110:111] neg_lo:[0,1] neg_hi:[0,1]
	s_waitcnt vmcnt(6)
	v_lshlrev_b32_e32 v110, 16, v48
	v_and_b32_e32 v111, 0xffff0000, v48
	v_mul_f32_e32 v48, 0xbfb8aa3b, v110
	v_exp_f32_e32 v48, v48
	v_pk_mul_f32 v[118:119], v[4:5], v[118:119]
	v_pk_add_f32 v[106:107], v[106:107], v[120:121]
	v_pk_mul_f32 v[112:113], v[118:119], v[112:113]
	v_add_f32_e32 v48, 1.0, v48
	v_cvt_pk_bf16_f32 v52, v112, v113
	v_rcp_f32_e32 v112, v48
	v_mul_f32_e32 v48, 0xbfb8aa3b, v111
	v_exp_f32_e32 v48, v48
	v_rcp_f32_e32 v77, v73
	s_mov_b64 s[2:3], 0
	v_add_f32_e32 v48, 1.0, v48
	v_rcp_f32_e32 v113, v48
	v_fma_f32 v79, -v73, v77, 1.0
	v_fmac_f32_e32 v77, v79, v77
	v_div_scale_f32 v79, vcc, 1.0, v72, 1.0
	v_pk_mul_f32 v[110:111], v[112:113], v[110:111]
	v_pk_fma_f32 v[112:113], v[90:91], v[106:107], v[120:121] op_sel_hi:[0,1,1] neg_lo:[0,0,1] neg_hi:[0,0,1]
	v_pk_mul_f32 v[112:113], v[4:5], v[112:113]
	v_mul_f32_e32 v83, v79, v77
	v_pk_mul_f32 v[110:111], v[112:113], v[110:111]
	s_waitcnt vmcnt(5)
	v_lshlrev_b32_e32 v112, 16, v44
	v_cvt_pk_bf16_f32 v48, v110, v111
	v_lshlrev_b32_e32 v110, 16, v32
	v_and_b32_e32 v111, 0xffff0000, v32
	v_mul_f32_e32 v32, 0xbfb8aa3b, v112
	v_exp_f32_e32 v32, v32
	v_and_b32_e32 v113, 0xffff0000, v44
	v_pk_add_f32 v[106:107], v[106:107], v[122:123] neg_lo:[0,1] neg_hi:[0,1]
	v_fma_f32 v87, -v73, v83, v79
	v_add_f32_e32 v32, 1.0, v32
	v_rcp_f32_e32 v118, v32
	v_mul_f32_e32 v32, 0xbfb8aa3b, v113
	v_exp_f32_e32 v32, v32
	v_pk_add_f32 v[106:107], v[106:107], v[110:111]
	v_fmac_f32_e32 v83, v87, v77
	v_fma_f32 v73, -v73, v83, v79
	v_add_f32_e32 v32, 1.0, v32
	v_rcp_f32_e32 v119, v32
	v_div_fmas_f32 v73, v73, v77, v83
	v_div_fixup_f32 v72, v73, v72, 1.0
	v_lshlrev_b32_e32 v44, 16, v45
	v_pk_mul_f32 v[112:113], v[118:119], v[112:113]
	v_pk_fma_f32 v[118:119], v[86:87], v[106:107], v[110:111] op_sel_hi:[0,1,1] neg_lo:[0,0,1] neg_hi:[0,0,1]
	v_pk_mul_f32 v[118:119], v[4:5], v[118:119]
	v_pk_add_f32 v[106:107], v[106:107], v[120:121] neg_lo:[0,1] neg_hi:[0,1]
	v_pk_mul_f32 v[112:113], v[118:119], v[112:113]
	s_waitcnt vmcnt(4)
	v_lshlrev_b32_e32 v118, 16, v40
	v_cvt_pk_bf16_f32 v32, v112, v113
	v_lshlrev_b32_e32 v112, 16, v28
	v_and_b32_e32 v113, 0xffff0000, v28
	v_mul_f32_e32 v28, 0xbfb8aa3b, v118
	v_exp_f32_e32 v28, v28
	v_and_b32_e32 v119, 0xffff0000, v40
	v_pk_add_f32 v[106:107], v[106:107], v[112:113]
	v_and_b32_e32 v45, 0xffff0000, v45
	v_add_f32_e32 v28, 1.0, v28
	v_rcp_f32_e32 v120, v28
	v_mul_f32_e32 v28, 0xbfb8aa3b, v119
	v_exp_f32_e32 v28, v28
	v_lshlrev_b32_e32 v40, 16, v41
	v_and_b32_e32 v41, 0xffff0000, v41
	v_ashrrev_i32_e32 v77, 31, v76
	v_add_f32_e32 v28, 1.0, v28
	v_rcp_f32_e32 v121, v28
	s_nop 0
	v_pk_mul_f32 v[118:119], v[120:121], v[118:119]
	v_pk_fma_f32 v[120:121], v[82:83], v[106:107], v[112:113] op_sel_hi:[0,1,1] neg_lo:[0,0,1] neg_hi:[0,0,1]
	v_pk_mul_f32 v[120:121], v[4:5], v[120:121]
	v_pk_add_f32 v[106:107], v[106:107], v[110:111] neg_lo:[0,1] neg_hi:[0,1]
	v_pk_mul_f32 v[118:119], v[120:121], v[118:119]
	v_lshlrev_b32_e32 v110, 16, v24
	v_cvt_pk_bf16_f32 v28, v118, v119
	s_waitcnt vmcnt(3)
	v_lshlrev_b32_e32 v118, 16, v36
	v_and_b32_e32 v111, 0xffff0000, v24
	v_mul_f32_e32 v24, 0xbfb8aa3b, v118
	v_exp_f32_e32 v24, v24
	v_and_b32_e32 v119, 0xffff0000, v36
	v_pk_add_f32 v[106:107], v[106:107], v[110:111]
	v_lshlrev_b32_e32 v36, 16, v37
	v_add_f32_e32 v24, 1.0, v24
	v_rcp_f32_e32 v120, v24
	v_mul_f32_e32 v24, 0xbfb8aa3b, v119
	v_exp_f32_e32 v24, v24
	v_and_b32_e32 v37, 0xffff0000, v37
	v_add_f32_e32 v24, 1.0, v24
	v_rcp_f32_e32 v121, v24
	s_nop 0
	v_pk_mul_f32 v[118:119], v[120:121], v[118:119]
	v_pk_fma_f32 v[120:121], v[78:79], v[106:107], v[110:111] op_sel_hi:[0,1,1] neg_lo:[0,0,1] neg_hi:[0,0,1]
	v_pk_mul_f32 v[120:121], v[4:5], v[120:121]
	v_pk_add_f32 v[106:107], v[106:107], v[112:113] neg_lo:[0,1] neg_hi:[0,1]
	v_pk_mul_f32 v[118:119], v[120:121], v[118:119]
	v_lshlrev_b32_e32 v112, 16, v16
	v_and_b32_e32 v113, 0xffff0000, v16
	v_cvt_pk_bf16_f32 v24, v118, v119
	v_pk_add_f32 v[118:119], v[106:107], v[112:113]
	s_waitcnt vmcnt(2)
	v_lshlrev_b32_e32 v106, 16, v20
	v_mul_f32_e32 v16, 0xbfb8aa3b, v106
	v_exp_f32_e32 v16, v16
	v_and_b32_e32 v107, 0xffff0000, v20
	v_pk_fma_f32 v[112:113], v[72:73], v[118:119], v[112:113] op_sel_hi:[0,1,1] neg_lo:[0,0,1] neg_hi:[0,0,1]
	v_pk_mul_f32 v[112:113], v[4:5], v[112:113]
	v_add_f32_e32 v16, 1.0, v16
	v_rcp_f32_e32 v120, v16
	v_mul_f32_e32 v16, 0xbfb8aa3b, v107
	v_exp_f32_e32 v16, v16
	v_lshlrev_b32_e32 v20, 16, v21
	v_and_b32_e32 v21, 0xffff0000, v21
	v_pk_add_f32 v[110:111], v[118:119], v[110:111] neg_lo:[0,1] neg_hi:[0,1]
	v_add_f32_e32 v16, 1.0, v16
	v_rcp_f32_e32 v121, v16
	v_mul_f32_e32 v16, 0xbfb8aa3b, v108
	v_exp_f32_e32 v16, v16
	v_pk_mul_f32 v[106:107], v[120:121], v[106:107]
	s_nop 0
	v_pk_mul_f32 v[106:107], v[112:113], v[106:107]
	v_add_f32_e32 v16, 1.0, v16
	v_rcp_f32_e32 v112, v16
	v_mul_f32_e32 v16, 0xbfb8aa3b, v109
	v_exp_f32_e32 v16, v16
	s_nop 0
	v_add_f32_e32 v16, 1.0, v16
	v_rcp_f32_e32 v113, v16
	s_nop 0
	v_pk_mul_f32 v[108:109], v[112:113], v[108:109]
	v_pk_fma_f32 v[112:113], v[88:89], v[104:105], v[116:117] op_sel_hi:[0,1,1] neg_lo:[0,0,1] neg_hi:[0,0,1]
	v_lshlrev_b32_e32 v104, 16, v49
	v_mul_f32_e32 v16, 0xbfb8aa3b, v104
	v_exp_f32_e32 v16, v16
	v_pk_mul_f32 v[112:113], v[6:7], v[112:113]
	v_and_b32_e32 v105, 0xffff0000, v49
	v_pk_mul_f32 v[108:109], v[112:113], v[108:109]
	v_add_f32_e32 v16, 1.0, v16
	v_cvt_pk_bf16_f32 v53, v108, v109
	v_rcp_f32_e32 v108, v16
	v_mul_f32_e32 v16, 0xbfb8aa3b, v105
	v_exp_f32_e32 v16, v16
	s_nop 0
	v_add_f32_e32 v16, 1.0, v16
	v_rcp_f32_e32 v109, v16
	v_mul_f32_e32 v16, 0xbfb8aa3b, v44
	v_exp_f32_e32 v16, v16
	v_pk_mul_f32 v[104:105], v[108:109], v[104:105]
	v_pk_fma_f32 v[108:109], v[90:91], v[100:101], v[114:115] op_sel_hi:[0,1,1] neg_lo:[0,0,1] neg_hi:[0,0,1]
	v_pk_mul_f32 v[108:109], v[6:7], v[108:109]
	v_add_f32_e32 v16, 1.0, v16
	v_pk_mul_f32 v[104:105], v[108:109], v[104:105]
	v_rcp_f32_e32 v108, v16
	v_mul_f32_e32 v16, 0xbfb8aa3b, v45
	v_exp_f32_e32 v16, v16
	v_pk_add_f32 v[100:101], v[100:101], v[116:117] neg_lo:[0,1] neg_hi:[0,1]
	v_cvt_pk_bf16_f32 v49, v104, v105
	v_lshlrev_b32_e32 v104, 16, v33
	v_add_f32_e32 v16, 1.0, v16
	v_rcp_f32_e32 v109, v16
	v_mul_f32_e32 v16, 0xbfb8aa3b, v40
	v_exp_f32_e32 v16, v16
	v_and_b32_e32 v105, 0xffff0000, v33
	v_pk_add_f32 v[100:101], v[100:101], v[104:105]
	v_pk_mul_f32 v[44:45], v[108:109], v[44:45]
	v_pk_fma_f32 v[108:109], v[86:87], v[100:101], v[104:105] op_sel_hi:[0,1,1] neg_lo:[0,0,1] neg_hi:[0,0,1]
	v_pk_mul_f32 v[108:109], v[6:7], v[108:109]
	v_add_f32_e32 v16, 1.0, v16
	v_pk_mul_f32 v[44:45], v[108:109], v[44:45]
	v_rcp_f32_e32 v108, v16
	v_mul_f32_e32 v16, 0xbfb8aa3b, v41
	v_exp_f32_e32 v16, v16
	v_pk_add_f32 v[100:101], v[100:101], v[114:115] neg_lo:[0,1] neg_hi:[0,1]
	v_cvt_pk_bf16_f32 v33, v44, v45
	v_lshlrev_b32_e32 v44, 16, v29
	v_add_f32_e32 v16, 1.0, v16
	v_rcp_f32_e32 v109, v16
	v_mul_f32_e32 v16, 0xbfb8aa3b, v36
	v_exp_f32_e32 v16, v16
	v_and_b32_e32 v45, 0xffff0000, v29
	v_pk_add_f32 v[100:101], v[100:101], v[44:45]
	v_pk_mul_f32 v[40:41], v[108:109], v[40:41]
	v_add_f32_e32 v16, 1.0, v16
	v_pk_fma_f32 v[108:109], v[82:83], v[100:101], v[44:45] op_sel_hi:[0,1,1] neg_lo:[0,0,1] neg_hi:[0,0,1]
	v_pk_add_f32 v[100:101], v[100:101], v[104:105] neg_lo:[0,1] neg_hi:[0,1]
	v_rcp_f32_e32 v104, v16
	v_mul_f32_e32 v16, 0xbfb8aa3b, v37
	v_exp_f32_e32 v16, v16
	v_pk_mul_f32 v[108:109], v[6:7], v[108:109]
	v_add_f32_e32 v16, 1.0, v16
	v_rcp_f32_e32 v105, v16
	v_pk_mul_f32 v[40:41], v[108:109], v[40:41]
	v_lshlrev_b32_e32 v16, 16, v17
	v_cvt_pk_bf16_f32 v29, v40, v41
	v_lshlrev_b32_e32 v40, 16, v25
	v_and_b32_e32 v41, 0xffff0000, v25
	v_pk_add_f32 v[100:101], v[100:101], v[40:41]
	v_pk_mul_f32 v[36:37], v[104:105], v[36:37]
	v_pk_fma_f32 v[104:105], v[78:79], v[100:101], v[40:41] op_sel_hi:[0,1,1] neg_lo:[0,0,1] neg_hi:[0,0,1]
	v_pk_mul_f32 v[104:105], v[6:7], v[104:105]
	v_pk_add_f32 v[44:45], v[100:101], v[44:45] neg_lo:[0,1] neg_hi:[0,1]
	v_pk_mul_f32 v[36:37], v[104:105], v[36:37]
	v_and_b32_e32 v17, 0xffff0000, v17
	v_cvt_pk_bf16_f32 v25, v36, v37
	v_pk_add_f32 v[36:37], v[44:45], v[16:17]
	v_mul_f32_e32 v44, 0xbfb8aa3b, v20
	v_mul_f32_e32 v45, 0xbfb8aa3b, v21
	v_exp_f32_e32 v44, v44
	v_exp_f32_e32 v45, v45
	v_pk_fma_f32 v[16:17], v[72:73], v[36:37], v[16:17] op_sel_hi:[0,1,1] neg_lo:[0,0,1] neg_hi:[0,0,1]
	v_pk_add_f32 v[36:37], v[36:37], v[40:41] neg_lo:[0,1] neg_hi:[0,1]
	v_add_f32_e32 v44, 1.0, v44
	v_add_f32_e32 v45, 1.0, v45
	v_rcp_f32_e32 v44, v44
	v_rcp_f32_e32 v45, v45
	v_lshlrev_b32_e32 v40, 16, v54
	v_and_b32_e32 v41, 0xffff0000, v54
	v_pk_mul_f32 v[16:17], v[6:7], v[16:17]
	v_pk_mul_f32 v[20:21], v[44:45], v[20:21]
	v_mul_f32_e32 v44, 0xbfb8aa3b, v40
	v_mul_f32_e32 v45, 0xbfb8aa3b, v41
	v_exp_f32_e32 v44, v44
	v_exp_f32_e32 v45, v45
	v_pk_mul_f32 v[16:17], v[16:17], v[20:21]
	v_pk_add_f32 v[20:21], v[102:103], v[92:93] neg_lo:[0,1] neg_hi:[0,1]
	v_add_f32_e32 v44, 1.0, v44
	v_add_f32_e32 v45, 1.0, v45
	v_rcp_f32_e32 v44, v44
	v_rcp_f32_e32 v45, v45
	v_pk_add_f32 v[20:21], v[20:21], v[98:99]
	v_pk_mul_f32 v[40:41], v[44:45], v[40:41]
	v_pk_fma_f32 v[44:45], v[88:89], v[20:21], v[98:99] op_sel_hi:[0,1,1] neg_lo:[0,0,1] neg_hi:[0,0,1]
	v_pk_mul_f32 v[44:45], v[0:1], v[44:45]
	v_pk_add_f32 v[20:21], v[20:21], v[80:81] neg_lo:[0,1] neg_hi:[0,1]
	v_pk_mul_f32 v[40:41], v[44:45], v[40:41]
	v_pk_add_f32 v[20:21], v[20:21], v[94:95]
	v_cvt_pk_bf16_f32 v54, v40, v41
	v_lshlrev_b32_e32 v40, 16, v50
	v_and_b32_e32 v41, 0xffff0000, v50
	v_mul_f32_e32 v44, 0xbfb8aa3b, v40
	v_mul_f32_e32 v45, 0xbfb8aa3b, v41
	v_exp_f32_e32 v44, v44
	v_exp_f32_e32 v45, v45
	v_add_f32_e32 v44, 1.0, v44
	v_add_f32_e32 v45, 1.0, v45
	v_rcp_f32_e32 v44, v44
	v_rcp_f32_e32 v45, v45
	s_nop 0
	v_pk_mul_f32 v[40:41], v[44:45], v[40:41]
	v_pk_fma_f32 v[44:45], v[90:91], v[20:21], v[94:95] op_sel_hi:[0,1,1] neg_lo:[0,0,1] neg_hi:[0,0,1]
	v_pk_mul_f32 v[44:45], v[0:1], v[44:45]
	v_pk_add_f32 v[20:21], v[20:21], v[98:99] neg_lo:[0,1] neg_hi:[0,1]
	v_pk_mul_f32 v[40:41], v[44:45], v[40:41]
	v_lshlrev_b32_e32 v44, 16, v46
	v_cvt_pk_bf16_f32 v50, v40, v41
	v_lshlrev_b32_e32 v40, 16, v34
	v_and_b32_e32 v41, 0xffff0000, v34
	v_mul_f32_e32 v34, 0xbfb8aa3b, v44
	v_exp_f32_e32 v34, v34
	v_and_b32_e32 v45, 0xffff0000, v46
	v_pk_add_f32 v[20:21], v[20:21], v[40:41]
	v_lshlrev_b32_e32 v46, 16, v47
	v_add_f32_e32 v34, 1.0, v34
	v_rcp_f32_e32 v80, v34
	v_mul_f32_e32 v34, 0xbfb8aa3b, v45
	v_exp_f32_e32 v34, v34
	v_and_b32_e32 v47, 0xffff0000, v47
	v_add_f32_e32 v34, 1.0, v34
	v_rcp_f32_e32 v81, v34
	s_nop 0
	v_pk_mul_f32 v[44:45], v[80:81], v[44:45]
	v_pk_fma_f32 v[80:81], v[86:87], v[20:21], v[40:41] op_sel_hi:[0,1,1] neg_lo:[0,0,1] neg_hi:[0,0,1]
	v_pk_mul_f32 v[80:81], v[0:1], v[80:81]
	v_pk_add_f32 v[20:21], v[20:21], v[94:95] neg_lo:[0,1] neg_hi:[0,1]
	v_pk_mul_f32 v[44:45], v[80:81], v[44:45]
	v_lshlrev_b32_e32 v80, 16, v42
	v_cvt_pk_bf16_f32 v34, v44, v45
	v_lshlrev_b32_e32 v44, 16, v30
	v_and_b32_e32 v45, 0xffff0000, v30
	v_mul_f32_e32 v30, 0xbfb8aa3b, v80
	v_exp_f32_e32 v30, v30
	v_and_b32_e32 v81, 0xffff0000, v42
	v_pk_add_f32 v[20:21], v[20:21], v[44:45]
	v_lshlrev_b32_e32 v42, 16, v43
	v_add_f32_e32 v30, 1.0, v30
	v_rcp_f32_e32 v92, v30
	v_mul_f32_e32 v30, 0xbfb8aa3b, v81
	v_exp_f32_e32 v30, v30
	v_and_b32_e32 v43, 0xffff0000, v43
	v_add_f32_e32 v30, 1.0, v30
	v_rcp_f32_e32 v93, v30
	s_nop 0
	v_pk_mul_f32 v[80:81], v[92:93], v[80:81]
	v_pk_fma_f32 v[92:93], v[82:83], v[20:21], v[44:45] op_sel_hi:[0,1,1] neg_lo:[0,0,1] neg_hi:[0,0,1]
	v_pk_mul_f32 v[92:93], v[0:1], v[92:93]
	v_pk_add_f32 v[20:21], v[20:21], v[40:41] neg_lo:[0,1] neg_hi:[0,1]
	v_pk_mul_f32 v[80:81], v[92:93], v[80:81]
	v_lshlrev_b32_e32 v40, 16, v26
	v_cvt_pk_bf16_f32 v30, v80, v81
	v_lshlrev_b32_e32 v80, 16, v38
	v_and_b32_e32 v41, 0xffff0000, v26
	v_mul_f32_e32 v26, 0xbfb8aa3b, v80
	v_exp_f32_e32 v26, v26
	v_and_b32_e32 v81, 0xffff0000, v38
	v_pk_add_f32 v[20:21], v[20:21], v[40:41]
	v_lshlrev_b32_e32 v38, 16, v39
	v_add_f32_e32 v26, 1.0, v26
	v_rcp_f32_e32 v92, v26
	v_mul_f32_e32 v26, 0xbfb8aa3b, v81
	v_exp_f32_e32 v26, v26
	v_and_b32_e32 v39, 0xffff0000, v39
	v_add_f32_e32 v26, 1.0, v26
	v_rcp_f32_e32 v93, v26
	s_nop 0
	v_pk_mul_f32 v[80:81], v[92:93], v[80:81]
	v_pk_fma_f32 v[92:93], v[78:79], v[20:21], v[40:41] op_sel_hi:[0,1,1] neg_lo:[0,0,1] neg_hi:[0,0,1]
	v_pk_mul_f32 v[92:93], v[0:1], v[92:93]
	v_pk_add_f32 v[20:21], v[20:21], v[44:45] neg_lo:[0,1] neg_hi:[0,1]
	v_pk_mul_f32 v[80:81], v[92:93], v[80:81]
	v_lshlrev_b32_e32 v44, 16, v18
	v_and_b32_e32 v45, 0xffff0000, v18
	v_cvt_pk_bf16_f32 v26, v80, v81
	v_pk_add_f32 v[80:81], v[20:21], v[44:45]
	v_lshlrev_b32_e32 v20, 16, v22
	v_mul_f32_e32 v18, 0xbfb8aa3b, v20
	v_exp_f32_e32 v18, v18
	v_and_b32_e32 v21, 0xffff0000, v22
	v_pk_fma_f32 v[44:45], v[72:73], v[80:81], v[44:45] op_sel_hi:[0,1,1] neg_lo:[0,0,1] neg_hi:[0,0,1]
	v_pk_mul_f32 v[44:45], v[0:1], v[44:45]
	v_add_f32_e32 v18, 1.0, v18
	v_rcp_f32_e32 v92, v18
	v_mul_f32_e32 v18, 0xbfb8aa3b, v21
	v_exp_f32_e32 v18, v18
	v_lshlrev_b32_e32 v22, 16, v23
	v_and_b32_e32 v23, 0xffff0000, v23
	v_add_f32_e32 v18, 1.0, v18
	v_rcp_f32_e32 v93, v18
	s_nop 0
	v_pk_mul_f32 v[20:21], v[92:93], v[20:21]
	s_nop 0
	v_pk_mul_f32 v[20:21], v[44:45], v[20:21]
	v_pk_add_f32 v[44:45], v[80:81], v[40:41] neg_lo:[0,1] neg_hi:[0,1]
	v_pk_add_f32 v[40:41], v[84:85], v[70:71] neg_lo:[0,1] neg_hi:[0,1]
	v_lshlrev_b32_e32 v70, 16, v55
	v_mul_f32_e32 v18, 0xbfb8aa3b, v70
	v_exp_f32_e32 v18, v18
	v_and_b32_e32 v71, 0xffff0000, v55
	v_pk_add_f32 v[40:41], v[40:41], v[66:67]
	v_add_f32_e32 v18, 1.0, v18
	v_rcp_f32_e32 v80, v18
	v_mul_f32_e32 v18, 0xbfb8aa3b, v71
	v_exp_f32_e32 v18, v18
	s_nop 0
	v_add_f32_e32 v18, 1.0, v18
	v_rcp_f32_e32 v81, v18
	s_nop 0
	v_pk_mul_f32 v[70:71], v[80:81], v[70:71]
	v_pk_fma_f32 v[80:81], v[88:89], v[40:41], v[66:67] op_sel_hi:[0,1,1] neg_lo:[0,0,1] neg_hi:[0,0,1]
	v_pk_add_f32 v[40:41], v[40:41], v[64:65] neg_lo:[0,1] neg_hi:[0,1]
	v_lshlrev_b32_e32 v64, 16, v51
	v_mul_f32_e32 v18, 0xbfb8aa3b, v64
	v_exp_f32_e32 v18, v18
	v_pk_mul_f32 v[80:81], v[2:3], v[80:81]
	v_and_b32_e32 v65, 0xffff0000, v51
	v_pk_mul_f32 v[70:71], v[80:81], v[70:71]
	v_add_f32_e32 v18, 1.0, v18
	v_cvt_pk_bf16_f32 v55, v70, v71
	v_rcp_f32_e32 v70, v18
	v_mul_f32_e32 v18, 0xbfb8aa3b, v65
	v_exp_f32_e32 v18, v18
	v_pk_add_f32 v[40:41], v[40:41], v[62:63]
	v_add_f32_e32 v18, 1.0, v18
	v_rcp_f32_e32 v71, v18
	v_mul_f32_e32 v18, 0xbfb8aa3b, v46
	v_exp_f32_e32 v18, v18
	v_pk_mul_f32 v[64:65], v[70:71], v[64:65]
	v_pk_fma_f32 v[70:71], v[90:91], v[40:41], v[62:63] op_sel_hi:[0,1,1] neg_lo:[0,0,1] neg_hi:[0,0,1]
	v_add_f32_e32 v18, 1.0, v18
	v_pk_add_f32 v[40:41], v[40:41], v[66:67] neg_lo:[0,1] neg_hi:[0,1]
	v_rcp_f32_e32 v66, v18
	v_mul_f32_e32 v18, 0xbfb8aa3b, v47
	v_exp_f32_e32 v18, v18
	v_pk_mul_f32 v[70:71], v[2:3], v[70:71]
	v_add_f32_e32 v18, 1.0, v18
	v_rcp_f32_e32 v67, v18
	v_mul_f32_e32 v18, 0xbfb8aa3b, v42
	v_exp_f32_e32 v18, v18
	v_pk_mul_f32 v[64:65], v[70:71], v[64:65]
	v_pk_mul_f32 v[46:47], v[66:67], v[46:47]
	v_cvt_pk_bf16_f32 v51, v64, v65
	v_lshlrev_b32_e32 v64, 16, v35
	v_and_b32_e32 v65, 0xffff0000, v35
	v_pk_add_f32 v[40:41], v[40:41], v[64:65]
	v_add_f32_e32 v18, 1.0, v18
	v_pk_fma_f32 v[66:67], v[86:87], v[40:41], v[64:65] op_sel_hi:[0,1,1] neg_lo:[0,0,1] neg_hi:[0,0,1]
	v_pk_add_f32 v[40:41], v[40:41], v[62:63] neg_lo:[0,1] neg_hi:[0,1]
	v_rcp_f32_e32 v62, v18
	v_mul_f32_e32 v18, 0xbfb8aa3b, v43
	v_exp_f32_e32 v18, v18
	v_pk_mul_f32 v[66:67], v[2:3], v[66:67]
	v_add_f32_e32 v18, 1.0, v18
	v_rcp_f32_e32 v63, v18
	v_mul_f32_e32 v18, 0xbfb8aa3b, v38
	v_pk_mul_f32 v[46:47], v[66:67], v[46:47]
	v_exp_f32_e32 v18, v18
	v_cvt_pk_bf16_f32 v35, v46, v47
	v_lshlrev_b32_e32 v46, 16, v31
	v_and_b32_e32 v47, 0xffff0000, v31
	v_pk_add_f32 v[40:41], v[40:41], v[46:47]
	v_pk_mul_f32 v[42:43], v[62:63], v[42:43]
	v_pk_fma_f32 v[62:63], v[82:83], v[40:41], v[46:47] op_sel_hi:[0,1,1] neg_lo:[0,0,1] neg_hi:[0,0,1]
	v_pk_mul_f32 v[62:63], v[2:3], v[62:63]
	v_add_f32_e32 v18, 1.0, v18
	v_pk_mul_f32 v[42:43], v[62:63], v[42:43]
	v_rcp_f32_e32 v62, v18
	v_mul_f32_e32 v18, 0xbfb8aa3b, v39
	v_exp_f32_e32 v18, v18
	v_pk_add_f32 v[40:41], v[40:41], v[64:65] neg_lo:[0,1] neg_hi:[0,1]
	v_cvt_pk_bf16_f32 v31, v42, v43
	v_lshlrev_b32_e32 v42, 16, v27
	v_add_f32_e32 v18, 1.0, v18
	v_rcp_f32_e32 v63, v18
	v_and_b32_e32 v43, 0xffff0000, v27
	v_pk_add_f32 v[40:41], v[40:41], v[42:43]
	v_lshlrev_b32_e32 v18, 16, v19
	v_pk_mul_f32 v[38:39], v[62:63], v[38:39]
	v_pk_fma_f32 v[62:63], v[78:79], v[40:41], v[42:43] op_sel_hi:[0,1,1] neg_lo:[0,0,1] neg_hi:[0,0,1]
	v_pk_mul_f32 v[62:63], v[2:3], v[62:63]
	v_pk_add_f32 v[40:41], v[40:41], v[46:47] neg_lo:[0,1] neg_hi:[0,1]
	v_pk_mul_f32 v[38:39], v[62:63], v[38:39]
	v_and_b32_e32 v19, 0xffff0000, v19
	v_cvt_pk_bf16_f32 v27, v38, v39
	global_store_dwordx4 v[60:61], v[52:55], off
	global_store_dwordx4 v[56:57], v[48:51], off
	global_store_dwordx4 v[58:59], v[32:35], off
	global_store_dwordx4 v[68:69], v[28:31], off
	global_store_dwordx4 v[74:75], v[24:27], off
	s_nop 1
	v_mul_f32_e32 v26, 0xbfb8aa3b, v22
	v_mul_f32_e32 v27, 0xbfb8aa3b, v23
	v_exp_f32_e32 v26, v26
	v_exp_f32_e32 v27, v27
	v_pk_add_f32 v[24:25], v[40:41], v[18:19]
	v_add_f32_e32 v26, 1.0, v26
	v_add_f32_e32 v27, 1.0, v27
	v_rcp_f32_e32 v26, v26
	v_rcp_f32_e32 v27, v27
	v_pk_fma_f32 v[18:19], v[72:73], v[24:25], v[18:19] op_sel_hi:[0,1,1] neg_lo:[0,0,1] neg_hi:[0,0,1]
	v_pk_mul_f32 v[18:19], v[2:3], v[18:19]
	v_pk_mul_f32 v[22:23], v[26:27], v[22:23]
	s_nop 0
	v_pk_mul_f32 v[26:27], v[18:19], v[22:23]
	v_cvt_pk_bf16_f32 v23, v16, v17
	v_lshl_add_u64 v[16:17], s[28:29], 0, v[76:77]
	v_lshlrev_b64 v[16:17], 11, v[16:17]
	v_pk_add_f32 v[18:19], v[24:25], v[42:43] neg_lo:[0,1] neg_hi:[0,1]
	v_cvt_pk_bf16_f32 v22, v106, v107
	v_cvt_pk_bf16_f32 v24, v20, v21
	v_cvt_pk_bf16_f32 v25, v26, v27
	v_lshl_add_u64 v[16:17], v[138:139], 0, v[16:17]
	global_store_dwordx4 v[16:17], v[22:25], off
	s_waitcnt vmcnt(7)
	v_lshlrev_b32_e32 v16, 16, v12
	v_and_b32_e32 v17, 0xffff0000, v12
	v_mul_f32_e32 v12, 0xbfb8aa3b, v16
	v_exp_f32_e32 v12, v12
	s_nop 0
	v_add_f32_e32 v12, 1.0, v12
	v_rcp_f32_e32 v20, v12
	v_mul_f32_e32 v12, 0xbfb8aa3b, v17
	v_exp_f32_e32 v12, v12
	s_nop 0
	v_add_f32_e32 v12, 1.0, v12
	v_rcp_f32_e32 v21, v12
	v_lshlrev_b32_e32 v12, 16, v13
	v_and_b32_e32 v13, 0xffff0000, v13
	v_pk_mul_f32 v[16:17], v[20:21], v[16:17]
	v_mul_f32_e32 v20, 0xbfb8aa3b, v12
	v_mul_f32_e32 v21, 0xbfb8aa3b, v13
	v_exp_f32_e32 v20, v20
	v_exp_f32_e32 v21, v21
	v_add_f32_e32 v20, 1.0, v20
	v_add_f32_e32 v21, 1.0, v21
	v_rcp_f32_e32 v20, v20
	v_rcp_f32_e32 v21, v21
	s_nop 0
	v_pk_mul_f32 v[12:13], v[20:21], v[12:13]
	v_lshlrev_b32_e32 v20, 16, v14
	v_and_b32_e32 v21, 0xffff0000, v14
	v_mul_f32_e32 v14, 0xbfb8aa3b, v20
	v_exp_f32_e32 v14, v14
	s_nop 0
	v_add_f32_e32 v14, 1.0, v14
	v_rcp_f32_e32 v22, v14
	v_mul_f32_e32 v14, 0xbfb8aa3b, v21
	v_exp_f32_e32 v14, v14
	s_nop 0
	v_add_f32_e32 v14, 1.0, v14
	v_rcp_f32_e32 v23, v14
	v_lshlrev_b32_e32 v14, 16, v15
	v_and_b32_e32 v15, 0xffff0000, v15
	v_pk_mul_f32 v[20:21], v[22:23], v[20:21]
	v_mul_f32_e32 v22, 0xbfb8aa3b, v14
	v_mul_f32_e32 v23, 0xbfb8aa3b, v15
	v_exp_f32_e32 v22, v22
	v_exp_f32_e32 v23, v23
	v_add_f32_e32 v22, 1.0, v22
	v_add_f32_e32 v23, 1.0, v23
	v_rcp_f32_e32 v22, v22
	v_rcp_f32_e32 v23, v23
	s_nop 0
	v_pk_mul_f32 v[14:15], v[22:23], v[14:15]
	v_min_i32_e32 v22, 1, v140
.LBB0_215:
	s_and_b64 vcc, exec, s[2:3]
	s_cbranch_vccz .LBB0_111
	v_cmp_lt_i32_e32 vcc, 2, v142
	v_mov_b32_e32 v72, 0
	v_mov_b32_e32 v76, 0
	v_mov_b32_e32 v77, 0
	v_mov_b32_e32 v78, 0
	v_mov_b32_e32 v79, 0
	s_and_saveexec_b64 s[2:3], vcc
	s_cbranch_execz .LBB0_218
	v_add_u32_e32 v8, -3, v142
	v_mov_b32_e32 v9, v97
	v_lshl_add_u64 v[8:9], s[28:29], 0, v[8:9]
	v_lshlrev_b64 v[8:9], 11, v[8:9]
	v_lshl_add_u64 v[8:9], v[134:135], 0, v[8:9]
	global_load_dwordx4 v[76:79], v[8:9], off nt
.LBB0_218:
	s_or_b64 exec, exec, s[2:3]
	v_cmp_lt_i32_e32 vcc, 1, v142
	v_mov_b32_e32 v73, 0
	v_mov_b32_e32 v74, 0
	v_mov_b32_e32 v75, 0
	s_and_saveexec_b64 s[2:3], vcc
	s_cbranch_execz .LBB0_220
	v_add_u32_e32 v8, -2, v142
	v_mov_b32_e32 v9, v97
	v_lshl_add_u64 v[8:9], s[28:29], 0, v[8:9]
	v_lshlrev_b64 v[8:9], 11, v[8:9]
	v_lshl_add_u64 v[8:9], v[134:135], 0, v[8:9]
	global_load_dwordx4 v[72:75], v[8:9], off nt
.LBB0_220:
	s_or_b64 exec, exec, s[2:3]
	v_mov_b32_e32 v40, 0
	v_cmp_lt_i32_e32 vcc, 0, v142
	v_mov_b32_e32 v80, 0
	v_mov_b32_e32 v81, 0
	v_mov_b32_e32 v82, 0
	v_mov_b32_e32 v83, 0
	s_and_saveexec_b64 s[2:3], vcc
	s_cbranch_execz .LBB0_222
	v_add_u32_e32 v8, -1, v142
	v_mov_b32_e32 v9, v97
	v_lshl_add_u64 v[8:9], s[28:29], 0, v[8:9]
	v_lshlrev_b64 v[8:9], 11, v[8:9]
	v_lshl_add_u64 v[8:9], v[134:135], 0, v[8:9]
	global_load_dwordx4 v[80:83], v[8:9], off nt
.LBB0_222:
	s_or_b64 exec, exec, s[2:3]
	v_cmp_lt_i32_e32 vcc, -1, v142
	v_mov_b32_e32 v41, 0
	v_mov_b32_e32 v42, 0
	v_mov_b32_e32 v43, 0
	s_and_saveexec_b64 s[2:3], vcc
	s_cbranch_execz .LBB0_224
	v_mov_b32_e32 v143, v97
	v_lshl_add_u64 v[8:9], s[28:29], 0, v[142:143]
	v_lshlrev_b64 v[8:9], 11, v[8:9]
	v_lshl_add_u64 v[8:9], v[134:135], 0, v[8:9]
	global_load_dwordx4 v[40:43], v[8:9], off nt
.LBB0_224:
	s_or_b64 exec, exec, s[2:3]
	v_or_b32_e32 v104, 1, v142
	v_cmp_lt_i32_e32 vcc, -2, v142
	v_mov_b32_e32 v68, 0
	v_mov_b32_e32 v48, 0
	v_mov_b32_e32 v49, 0
	v_mov_b32_e32 v50, 0
	v_mov_b32_e32 v51, 0
	s_and_saveexec_b64 s[2:3], vcc
	s_cbranch_execz .LBB0_226
	v_mov_b32_e32 v105, v97
	v_lshl_add_u64 v[8:9], s[28:29], 0, v[104:105]
	v_lshlrev_b64 v[8:9], 11, v[8:9]
	v_lshl_add_u64 v[8:9], v[134:135], 0, v[8:9]
	global_load_dwordx4 v[48:51], v[8:9], off nt
.LBB0_226:
	s_or_b64 exec, exec, s[2:3]
	v_or_b32_e32 v100, 2, v142
	v_cmp_lt_i32_e32 vcc, -3, v142
	v_mov_b32_e32 v69, 0
	v_mov_b32_e32 v70, 0
	v_mov_b32_e32 v71, 0
	s_and_saveexec_b64 s[2:3], vcc
	s_cbranch_execz .LBB0_228
	v_mov_b32_e32 v101, v97
	v_lshl_add_u64 v[8:9], s[28:29], 0, v[100:101]
	v_lshlrev_b64 v[8:9], 11, v[8:9]
	v_lshl_add_u64 v[8:9], v[134:135], 0, v[8:9]
	global_load_dwordx4 v[68:71], v[8:9], off nt
.LBB0_228:
	s_or_b64 exec, exec, s[2:3]
	v_or_b32_e32 v98, 3, v142
	v_cmp_lt_i32_e32 vcc, -4, v142
	v_mov_b32_e32 v28, 0
	v_mov_b32_e32 v32, 0
	v_mov_b32_e32 v33, 0
	v_mov_b32_e32 v34, 0
	v_mov_b32_e32 v35, 0
	s_and_saveexec_b64 s[2:3], vcc
	s_cbranch_execz .LBB0_230
	v_mov_b32_e32 v99, v97
	v_lshl_add_u64 v[8:9], s[28:29], 0, v[98:99]
	v_lshlrev_b64 v[8:9], 11, v[8:9]
	v_lshl_add_u64 v[8:9], v[134:135], 0, v[8:9]
	global_load_dwordx4 v[32:35], v[8:9], off nt
.LBB0_230:
	s_or_b64 exec, exec, s[2:3]
	v_or_b32_e32 v94, 4, v142
	v_cmp_lt_i32_e32 vcc, -5, v142
	v_mov_b32_e32 v29, 0
	v_mov_b32_e32 v30, 0
	v_mov_b32_e32 v31, 0
	s_and_saveexec_b64 s[2:3], vcc
	s_cbranch_execz .LBB0_232
	v_mov_b32_e32 v95, v97
	v_lshl_add_u64 v[8:9], s[28:29], 0, v[94:95]
	v_lshlrev_b64 v[8:9], 11, v[8:9]
	v_lshl_add_u64 v[8:9], v[134:135], 0, v[8:9]
	global_load_dwordx4 v[28:31], v[8:9], off nt
.LBB0_232:
	s_or_b64 exec, exec, s[2:3]
	v_or_b32_e32 v92, 5, v142
	v_cmp_lt_i32_e32 vcc, -6, v142
	v_mov_b32_e32 v16, 0
	v_mov_b32_e32 v20, 0
	v_mov_b32_e32 v21, 0
	v_mov_b32_e32 v22, 0
	v_mov_b32_e32 v23, 0
	s_and_saveexec_b64 s[2:3], vcc
	s_cbranch_execz .LBB0_234
	v_mov_b32_e32 v93, v97
	v_lshl_add_u64 v[8:9], s[28:29], 0, v[92:93]
	v_lshlrev_b64 v[8:9], 11, v[8:9]
	v_lshl_add_u64 v[8:9], v[134:135], 0, v[8:9]
	global_load_dwordx4 v[20:23], v[8:9], off nt
.LBB0_234:
	s_or_b64 exec, exec, s[2:3]
	v_or_b32_e32 v84, 6, v142
	v_cmp_lt_i32_e32 vcc, -7, v142
	v_mov_b32_e32 v17, 0
	v_mov_b32_e32 v18, 0
	v_mov_b32_e32 v19, 0
	s_and_saveexec_b64 s[2:3], vcc
	s_cbranch_execz .LBB0_236
	v_mov_b32_e32 v85, v97
	v_lshl_add_u64 v[8:9], s[28:29], 0, v[84:85]
	v_lshlrev_b64 v[8:9], 11, v[8:9]
	v_lshl_add_u64 v[8:9], v[134:135], 0, v[8:9]
	global_load_dwordx4 v[16:19], v[8:9], off nt
.LBB0_236:
	s_or_b64 exec, exec, s[2:3]
	v_or_b32_e32 v140, 7, v142
	v_cmp_lt_i32_e32 vcc, -8, v142
	v_mov_b32_e32 v8, 0
	v_mov_b32_e32 v9, 0
	v_mov_b32_e32 v10, 0
	v_mov_b32_e32 v11, 0
	s_and_saveexec_b64 s[2:3], vcc
	s_cbranch_execz .LBB0_110
	v_mov_b32_e32 v141, v97
	v_lshl_add_u64 v[8:9], s[28:29], 0, v[140:141]
	v_lshlrev_b64 v[8:9], 11, v[8:9]
	v_lshl_add_u64 v[8:9], v[134:135], 0, v[8:9]
	global_load_dwordx4 v[8:11], v[8:9], off nt
	s_branch .LBB0_110
